# v89 + FFN-up conv epilogue: 100 pad nops between independent DPP multiply-adds removed (each checked against the 2-wait-state DPP rule)
# speedup vs baseline: 1.0003x; 1.0003x over previous
; #define PG8_LAS __attribute__((address_space(3)))
; #define PG8_FMAC_DPP(c_, x_, w_, ctrl_) asm("v_fmac_f32_dpp %0, %1, %2 " ctrl_ : "+v"(c_) : "v"(x_), "v"(w_))
;     PG8_NOPRE
;     __device__ __forceinline__ void operator()(const f32x4 (&acc_)[2][2][4][2], const Unit& u, int wr, int wc, int fr_, int fq_, int ui) const {
;     ...
;         { float r[2][4]; load_rs(r, rsl, wr, fr);
; #pragma unroll
;           for (int ai = 0; ai < 2; ++ai)
; #pragma unroll
;             for (int bj = 0; bj < 2; ++bj)
; #pragma unroll
;                 for (int m = 0; m < 4; ++m)
; #pragma unroll
;                     for (int n = 0; n < 2; ++n) acc[ai][bj][m][n] = acc[ai][bj][m][n] * r[ai][m]; }
;     ...
;                         if (m == 0 && !(ai == 0 && wr == 0)) { const int slot = ai == 0 ? 0 : (wr == 0 ? 1 : 2); const PG8_LAS float* b = xh + (((slot * 4 + wc) * 2) * 4 + fq) * 16 + n * 4 + bj * 8;
;                             h2 = *(const PG8_LAS f32x4*)b; h1 = *(const PG8_LAS f32x4*)(b + 64); }
; #pragma unroll
;                         for (int k = 0; k < 4; ++k) { const float cur = acc[ai][bj][m][n][k];
;                             float cc = fmaf(Wq[bj][2][k], cur, Wq[bj][3][k]);
;                             PG8_FMAC_DPP(cc, cur, Wq[bj][1][k], "row_shr:1 row_mask:0xf bank_mask:0xf bound_ctrl:1");
;                             PG8_FMAC_DPP(cc, cur, Wq[bj][0][k], "row_shr:2 row_mask:0xf bank_mask:0xf bound_ctrl:1");
;                             if (m == 0) { const float z = fr == 0 ? h2[k] : h1[k]; cc = fmaf(W1m[bj][k], h1[k], cc); cc = fmaf(W0m[bj][k], z, cc); }
;                             else { const float p = acc[ai][bj][m > 0 ? m - 1 : 0][n][k]; PG8_FMAC_DPP(cc, p, W1m[bj][k], "row_ror:1 row_mask:0xf bank_mask:0xf"); PG8_FMAC_DPP(cc, p, W0m[bj][k], "row_ror:2 row_mask:0xf bank_mask:0xf"); }
;                             c[bj][k] = cc; }
.LBB0_556:
	s_and_b32 s10, s96, 15
	v_pk_mul_f32 v[96:97], v[6:7], v[216:217] op_sel_hi:[1,0]
	v_pk_mul_f32 v[218:219], v[4:5], v[216:217] op_sel_hi:[1,0]
	s_cmp_lg_u32 s10, 0
	s_waitcnt lgkmcnt(0)
	v_fma_f32 v4, v134, v218, v98
	v_fma_f32 v5, v135, v219, v99
	v_fma_f32 v6, v136, v96, v100
	v_fma_f32 v7, v137, v97, v101
	s_cselect_b64 s[68:69], -1, 0
	v_fmac_f32_dpp v4, v218, v130 row_shr:1 row_mask:0xf bank_mask:0xf bound_ctrl:1
	v_fmac_f32_dpp v5, v219, v131 row_shr:1 row_mask:0xf bank_mask:0xf bound_ctrl:1
	v_fmac_f32_dpp v6, v96, v132 row_shr:1 row_mask:0xf bank_mask:0xf bound_ctrl:1
	v_fmac_f32_dpp v7, v97, v133 row_shr:1 row_mask:0xf bank_mask:0xf bound_ctrl:1
	v_fmac_f32_dpp v4, v218, v126 row_shr:2 row_mask:0xf bank_mask:0xf bound_ctrl:1
	v_fmac_f32_dpp v5, v219, v127 row_shr:2 row_mask:0xf bank_mask:0xf bound_ctrl:1
	v_fmac_f32_dpp v6, v96, v128 row_shr:2 row_mask:0xf bank_mask:0xf bound_ctrl:1
	v_fmac_f32_dpp v7, v97, v129 row_shr:2 row_mask:0xf bank_mask:0xf bound_ctrl:1
	v_cndmask_b32_e64 v119, 0, 1, s[62:63]
	v_cmp_ne_u32_e64 s[14:15], 1, v119
	s_andn2_b64 vcc, exec, s[62:63]
	s_cbranch_vccnz .LBB0_558
	ds_read_b128 v[178:181], v197 offset:32
	ds_read_b128 v[118:121], v197 offset:288
	s_mov_b64 s[68:69], 0
	s_branch .LBB0_559

; #define PG8_LAS __attribute__((address_space(3)))
; #define PG8_G __attribute__((address_space(1)))
;     PG8_NOPRE
;     __device__ __forceinline__ void operator()(const f32x4 (&acc_)[2][2][4][2], const Unit& u, int wr, int wc, int fr_, int fq_, int ui) const {
;     ...
;             for (int ai = 0; ai < 2; ++ai)
; #pragma unroll
;                 for (int m = 0; m < 4; ++m) {
;                     f32x4 c[2];
; #pragma unroll
;                     for (int bj = 0; bj < 2; ++bj) {
;                         f32x4 h1 = {0.f, 0.f, 0.f, 0.f}, h2 = {0.f, 0.f, 0.f, 0.f};
;                         if (m == 0 && !(ai == 0 && wr == 0)) { const int slot = ai == 0 ? 0 : (wr == 0 ? 1 : 2); const PG8_LAS float* b = xh + (((slot * 4 + wc) * 2) * 4 + fq) * 16 + n * 4 + bj * 8;
;                             h2 = *(const PG8_LAS f32x4*)b; h1 = *(const PG8_LAS f32x4*)(b + 64); }
; #pragma unroll
;                         for (int k = 0; k < 4; ++k) { const float cur = acc[ai][bj][m][n][k];
;                             float cc = fmaf(Wq[bj][2][k], cur, Wq[bj][3][k]);
;                             PG8_FMAC_DPP(cc, cur, Wq[bj][1][k], "row_shr:1 row_mask:0xf bank_mask:0xf bound_ctrl:1");
;                             PG8_FMAC_DPP(cc, cur, Wq[bj][0][k], "row_shr:2 row_mask:0xf bank_mask:0xf bound_ctrl:1");
;                             if (m == 0) { const float z = fr == 0 ? h2[k] : h1[k]; cc = fmaf(W1m[bj][k], h1[k], cc); cc = fmaf(W0m[bj][k], z, cc); }
;                             else { const float p = acc[ai][bj][m > 0 ? m - 1 : 0][n][k]; PG8_FMAC_DPP(cc, p, W1m[bj][k], "row_ror:1 row_mask:0xf bank_mask:0xf"); PG8_FMAC_DPP(cc, p, W0m[bj][k], "row_ror:2 row_mask:0xf bank_mask:0xf"); }
;                             c[bj][k] = cc; }
;     ...
;                         for (int k = 0; k < 4; ++k) ex[k] = __builtin_amdgcn_exp2f(-c[0][k]);
;                         const f32x4 den = ex + 1.0f, gv = c[0] * c[1]; f32x4 rc;
; #pragma unroll
;                         for (int k = 0; k < 4; ++k) rc[k] = __builtin_amdgcn_rcpf(den[k]);
;                         const f32x4 a = gv * rc;
;                         u32x2 w; w.x = cvt_pk_bf16(a[0], a[1]); w.y = cvt_pk_bf16(a[2], a[3]);
;                         if (n == 0) wkeep[ai][m] = w;
;                         else { const u32x4 w4 = {wkeep[ai][m].x, wkeep[ai][m].y, w.x, w.y}; *(PG8_G u32x4*)(ACT + (size_t)row * 5632 + ch0) = w4; }
.LBB0_563:
	s_or_b64 exec, exec, s[82:83]
	s_nop 0
	v_mov_b32_e32 v4, v199
	v_pk_mul_f32 v[118:119], v[144:145], v[4:5] op_sel_hi:[1,0]
	v_pk_mul_f32 v[8:9], v[140:141], v[196:197] op_sel_hi:[1,0]
	v_pk_mul_f32 v[12:13], v[138:139], v[196:197] op_sel_hi:[1,0]
	v_pk_mul_f32 v[138:139], v[104:105], v[198:199] op_sel_hi:[1,0]
	v_pk_mul_f32 v[140:141], v[102:103], v[198:199] op_sel_hi:[1,0]
	v_pk_mul_f32 v[102:103], v[88:89], v[4:5] op_sel_hi:[1,0]
	v_pk_mul_f32 v[6:7], v[84:85], v[196:197] op_sel_hi:[1,0]
	v_pk_mul_f32 v[164:165], v[164:165], v[212:213] op_sel_hi:[1,0]
	v_pk_mul_f32 v[162:163], v[162:163], v[212:213] op_sel_hi:[1,0]
	v_pk_mul_f32 v[160:161], v[160:161], v[210:211] op_sel_hi:[1,0]
	v_pk_mul_f32 v[158:159], v[158:159], v[210:211] op_sel_hi:[1,0]
	v_pk_mul_f32 v[156:157], v[156:157], v[212:213] op_sel_hi:[1,0]
	v_pk_mul_f32 v[154:155], v[154:155], v[212:213] op_sel_hi:[1,0]
	v_pk_mul_f32 v[152:153], v[152:153], v[210:211] op_sel_hi:[1,0]
	v_pk_mul_f32 v[150:151], v[150:151], v[210:211] op_sel_hi:[1,0]
	v_pk_mul_f32 v[148:149], v[148:149], v[198:199] op_sel_hi:[1,0]
	v_pk_mul_f32 v[146:147], v[146:147], v[198:199] op_sel_hi:[1,0]
	v_pk_mul_f32 v[142:143], v[142:143], v[4:5] op_sel_hi:[1,0]
	v_pk_mul_f32 v[14:15], v[90:91], v[4:5] op_sel_hi:[1,0]
	v_pk_mul_f32 v[4:5], v[86:87], v[196:197] op_sel_hi:[1,0]
	v_fma_f32 v84, v134, v162, v98
	v_fma_f32 v85, v135, v163, v99
	v_fma_f32 v86, v136, v164, v100
	v_fma_f32 v87, v137, v165, v101
	v_fmac_f32_dpp v84, v162, v130 row_shr:1 row_mask:0xf bank_mask:0xf bound_ctrl:1
	v_fmac_f32_dpp v85, v163, v131 row_shr:1 row_mask:0xf bank_mask:0xf bound_ctrl:1
	v_fmac_f32_dpp v86, v164, v132 row_shr:1 row_mask:0xf bank_mask:0xf bound_ctrl:1
	v_fmac_f32_dpp v87, v165, v133 row_shr:1 row_mask:0xf bank_mask:0xf bound_ctrl:1
	v_fmac_f32_dpp v84, v162, v126 row_shr:2 row_mask:0xf bank_mask:0xf bound_ctrl:1
	v_fmac_f32_dpp v85, v163, v127 row_shr:2 row_mask:0xf bank_mask:0xf bound_ctrl:1
	v_fmac_f32_dpp v86, v164, v128 row_shr:2 row_mask:0xf bank_mask:0xf bound_ctrl:1
	v_fmac_f32_dpp v87, v165, v129 row_shr:2 row_mask:0xf bank_mask:0xf bound_ctrl:1
	v_fmac_f32_dpp v84, v218, v242 row_ror:1 row_mask:0xf bank_mask:0xf
	v_fmac_f32_dpp v85, v219, v240 row_ror:1 row_mask:0xf bank_mask:0xf
	v_fmac_f32_dpp v86, v96, v238 row_ror:1 row_mask:0xf bank_mask:0xf
	v_fmac_f32_dpp v87, v97, v234 row_ror:1 row_mask:0xf bank_mask:0xf
	v_fmac_f32_dpp v84, v218, v241 row_ror:2 row_mask:0xf bank_mask:0xf
	v_fmac_f32_dpp v85, v219, v239 row_ror:2 row_mask:0xf bank_mask:0xf
	v_fmac_f32_dpp v86, v96, v237 row_ror:2 row_mask:0xf bank_mask:0xf
	v_fmac_f32_dpp v87, v97, v233 row_ror:2 row_mask:0xf bank_mask:0xf
	v_fma_f32 v88, v122, v154, v106
	v_fma_f32 v89, v123, v155, v107
	v_fma_f32 v90, v124, v156, v108
	v_fma_f32 v91, v125, v157, v109
	v_fmac_f32_dpp v88, v154, v114 row_shr:1 row_mask:0xf bank_mask:0xf bound_ctrl:1
	v_fmac_f32_dpp v89, v155, v115 row_shr:1 row_mask:0xf bank_mask:0xf bound_ctrl:1
	v_fmac_f32_dpp v90, v156, v116 row_shr:1 row_mask:0xf bank_mask:0xf bound_ctrl:1
	v_fmac_f32_dpp v91, v157, v117 row_shr:1 row_mask:0xf bank_mask:0xf bound_ctrl:1
	v_fmac_f32_dpp v88, v154, v110 row_shr:2 row_mask:0xf bank_mask:0xf bound_ctrl:1
	v_fmac_f32_dpp v89, v155, v111 row_shr:2 row_mask:0xf bank_mask:0xf bound_ctrl:1
	v_fmac_f32_dpp v90, v156, v112 row_shr:2 row_mask:0xf bank_mask:0xf bound_ctrl:1
	v_fmac_f32_dpp v91, v157, v113 row_shr:2 row_mask:0xf bank_mask:0xf bound_ctrl:1
	v_fmac_f32_dpp v88, v176, v236 row_ror:1 row_mask:0xf bank_mask:0xf
	v_fmac_f32_dpp v89, v177, v232 row_ror:1 row_mask:0xf bank_mask:0xf
	v_fmac_f32_dpp v90, v174, v224 row_ror:1 row_mask:0xf bank_mask:0xf
	v_fmac_f32_dpp v91, v175, v213 row_ror:1 row_mask:0xf bank_mask:0xf
	v_fmac_f32_dpp v88, v176, v235 row_ror:2 row_mask:0xf bank_mask:0xf
	v_fmac_f32_dpp v89, v177, v225 row_ror:2 row_mask:0xf bank_mask:0xf
	v_fmac_f32_dpp v90, v174, v223 row_ror:2 row_mask:0xf bank_mask:0xf
	v_fmac_f32_dpp v91, v175, v211 row_ror:2 row_mask:0xf bank_mask:0xf
	v_exp_f32_e64 v96, -v84
	v_exp_f32_e64 v97, -v85
	v_exp_f32_e64 v104, -v86
	v_exp_f32_e64 v105, -v87
	v_add_f32_e32 v96, 1.0, v96
	v_add_f32_e32 v97, 1.0, v97
	v_add_f32_e32 v104, 1.0, v104
	v_add_f32_e32 v105, 1.0, v105
	v_rcp_f32_e32 v96, v96
	v_rcp_f32_e32 v104, v104
	v_rcp_f32_e32 v105, v105
	v_rcp_f32_e32 v97, v97
	v_pk_mul_f32 v[86:87], v[86:87], v[90:91]
	v_pk_mul_f32 v[84:85], v[84:85], v[88:89]
	v_pk_mul_f32 v[86:87], v[104:105], v[86:87]
	v_pk_mul_f32 v[84:85], v[96:97], v[84:85]
	s_nop 0
	v_cvt_pk_bf16_f32 v104, v84, v85
	v_cvt_pk_bf16_f32 v105, v86, v87
	v_fma_f32 v84, v134, v158, v98
	v_fma_f32 v85, v135, v159, v99
	v_fma_f32 v86, v136, v160, v100
	v_fma_f32 v87, v137, v161, v101
	v_fmac_f32_dpp v84, v158, v130 row_shr:1 row_mask:0xf bank_mask:0xf bound_ctrl:1
	v_fmac_f32_dpp v85, v159, v131 row_shr:1 row_mask:0xf bank_mask:0xf bound_ctrl:1
	v_fmac_f32_dpp v86, v160, v132 row_shr:1 row_mask:0xf bank_mask:0xf bound_ctrl:1
	v_fmac_f32_dpp v87, v161, v133 row_shr:1 row_mask:0xf bank_mask:0xf bound_ctrl:1
	v_fmac_f32_dpp v84, v158, v126 row_shr:2 row_mask:0xf bank_mask:0xf bound_ctrl:1
	v_fmac_f32_dpp v85, v159, v127 row_shr:2 row_mask:0xf bank_mask:0xf bound_ctrl:1
	v_fmac_f32_dpp v86, v160, v128 row_shr:2 row_mask:0xf bank_mask:0xf bound_ctrl:1
	v_fmac_f32_dpp v87, v161, v129 row_shr:2 row_mask:0xf bank_mask:0xf bound_ctrl:1
	v_fmac_f32_dpp v84, v162, v242 row_ror:1 row_mask:0xf bank_mask:0xf
	v_fmac_f32_dpp v85, v163, v240 row_ror:1 row_mask:0xf bank_mask:0xf
	v_fmac_f32_dpp v86, v164, v238 row_ror:1 row_mask:0xf bank_mask:0xf
	v_fmac_f32_dpp v87, v165, v234 row_ror:1 row_mask:0xf bank_mask:0xf
; #define PG8_LAS __attribute__((address_space(3)))
; #define PG8_G __attribute__((address_space(1)))
;     PG8_NOPRE
;     __device__ __forceinline__ void operator()(const f32x4 (&acc_)[2][2][4][2], const Unit& u, int wr, int wc, int fr_, int fq_, int ui) const {
;     ...
;             for (int ai = 0; ai < 2; ++ai)
; #pragma unroll
;                 for (int m = 0; m < 4; ++m) {
;                     f32x4 c[2];
; #pragma unroll
;                     for (int bj = 0; bj < 2; ++bj) {
;                         f32x4 h1 = {0.f, 0.f, 0.f, 0.f}, h2 = {0.f, 0.f, 0.f, 0.f};
;                         if (m == 0 && !(ai == 0 && wr == 0)) { const int slot = ai == 0 ? 0 : (wr == 0 ? 1 : 2); const PG8_LAS float* b = xh + (((slot * 4 + wc) * 2) * 4 + fq) * 16 + n * 4 + bj * 8;
;                             h2 = *(const PG8_LAS f32x4*)b; h1 = *(const PG8_LAS f32x4*)(b + 64); }
; #pragma unroll
;                         for (int k = 0; k < 4; ++k) { const float cur = acc[ai][bj][m][n][k];
;                             float cc = fmaf(Wq[bj][2][k], cur, Wq[bj][3][k]);
;                             PG8_FMAC_DPP(cc, cur, Wq[bj][1][k], "row_shr:1 row_mask:0xf bank_mask:0xf bound_ctrl:1");
;                             PG8_FMAC_DPP(cc, cur, Wq[bj][0][k], "row_shr:2 row_mask:0xf bank_mask:0xf bound_ctrl:1");
;                             if (m == 0) { const float z = fr == 0 ? h2[k] : h1[k]; cc = fmaf(W1m[bj][k], h1[k], cc); cc = fmaf(W0m[bj][k], z, cc); }
;                             else { const float p = acc[ai][bj][m > 0 ? m - 1 : 0][n][k]; PG8_FMAC_DPP(cc, p, W1m[bj][k], "row_ror:1 row_mask:0xf bank_mask:0xf"); PG8_FMAC_DPP(cc, p, W0m[bj][k], "row_ror:2 row_mask:0xf bank_mask:0xf"); }
;                             c[bj][k] = cc; }
;     ...
;                         for (int k = 0; k < 4; ++k) ex[k] = __builtin_amdgcn_exp2f(-c[0][k]);
;                         const f32x4 den = ex + 1.0f, gv = c[0] * c[1]; f32x4 rc;
; #pragma unroll
;                         for (int k = 0; k < 4; ++k) rc[k] = __builtin_amdgcn_rcpf(den[k]);
;                         const f32x4 a = gv * rc;
;                         u32x2 w; w.x = cvt_pk_bf16(a[0], a[1]); w.y = cvt_pk_bf16(a[2], a[3]);
;                         if (n == 0) wkeep[ai][m] = w;
;                         else { const u32x4 w4 = {wkeep[ai][m].x, wkeep[ai][m].y, w.x, w.y}; *(PG8_G u32x4*)(ACT + (size_t)row * 5632 + ch0) = w4; }
	v_fmac_f32_dpp v84, v162, v241 row_ror:2 row_mask:0xf bank_mask:0xf
	v_fmac_f32_dpp v85, v163, v239 row_ror:2 row_mask:0xf bank_mask:0xf
	v_fmac_f32_dpp v86, v164, v237 row_ror:2 row_mask:0xf bank_mask:0xf
	v_fmac_f32_dpp v87, v165, v233 row_ror:2 row_mask:0xf bank_mask:0xf
	v_fma_f32 v88, v122, v150, v106
	v_fma_f32 v89, v123, v151, v107
	v_fma_f32 v90, v124, v152, v108
	v_fma_f32 v91, v125, v153, v109
	v_fmac_f32_dpp v88, v150, v114 row_shr:1 row_mask:0xf bank_mask:0xf bound_ctrl:1
	v_fmac_f32_dpp v89, v151, v115 row_shr:1 row_mask:0xf bank_mask:0xf bound_ctrl:1
	v_fmac_f32_dpp v90, v152, v116 row_shr:1 row_mask:0xf bank_mask:0xf bound_ctrl:1
	v_fmac_f32_dpp v91, v153, v117 row_shr:1 row_mask:0xf bank_mask:0xf bound_ctrl:1
	v_fmac_f32_dpp v88, v150, v110 row_shr:2 row_mask:0xf bank_mask:0xf bound_ctrl:1
	v_fmac_f32_dpp v89, v151, v111 row_shr:2 row_mask:0xf bank_mask:0xf bound_ctrl:1
	v_fmac_f32_dpp v90, v152, v112 row_shr:2 row_mask:0xf bank_mask:0xf bound_ctrl:1
	v_fmac_f32_dpp v91, v153, v113 row_shr:2 row_mask:0xf bank_mask:0xf bound_ctrl:1
	v_fmac_f32_dpp v88, v154, v236 row_ror:1 row_mask:0xf bank_mask:0xf
	v_fmac_f32_dpp v89, v155, v232 row_ror:1 row_mask:0xf bank_mask:0xf
	v_fmac_f32_dpp v90, v156, v224 row_ror:1 row_mask:0xf bank_mask:0xf
	v_fmac_f32_dpp v91, v157, v213 row_ror:1 row_mask:0xf bank_mask:0xf
	v_fmac_f32_dpp v88, v154, v235 row_ror:2 row_mask:0xf bank_mask:0xf
	v_fmac_f32_dpp v89, v155, v225 row_ror:2 row_mask:0xf bank_mask:0xf
	v_fmac_f32_dpp v90, v156, v223 row_ror:2 row_mask:0xf bank_mask:0xf
	v_fmac_f32_dpp v91, v157, v211 row_ror:2 row_mask:0xf bank_mask:0xf
	v_exp_f32_e64 v96, -v84
	v_exp_f32_e64 v97, -v85
	v_exp_f32_e64 v144, -v86
	v_exp_f32_e64 v145, -v87
	v_add_f32_e32 v96, 1.0, v96
	v_add_f32_e32 v97, 1.0, v97
	v_add_f32_e32 v144, 1.0, v144
	v_add_f32_e32 v145, 1.0, v145
	v_rcp_f32_e32 v96, v96
	v_rcp_f32_e32 v144, v144
	v_rcp_f32_e32 v145, v145
	v_rcp_f32_e32 v97, v97
	v_pk_mul_f32 v[86:87], v[86:87], v[90:91]
	v_pk_mul_f32 v[84:85], v[84:85], v[88:89]
	v_pk_mul_f32 v[86:87], v[144:145], v[86:87]
	v_pk_mul_f32 v[84:85], v[96:97], v[84:85]
	s_nop 0
	v_cvt_pk_bf16_f32 v96, v84, v85
	v_cvt_pk_bf16_f32 v97, v86, v87
	v_fma_f32 v84, v134, v170, v98
	v_fma_f32 v85, v135, v171, v99
	v_fma_f32 v86, v136, v172, v100
	v_fma_f32 v87, v137, v173, v101
	v_fmac_f32_dpp v84, v170, v130 row_shr:1 row_mask:0xf bank_mask:0xf bound_ctrl:1
	v_fmac_f32_dpp v85, v171, v131 row_shr:1 row_mask:0xf bank_mask:0xf bound_ctrl:1
	v_fmac_f32_dpp v86, v172, v132 row_shr:1 row_mask:0xf bank_mask:0xf bound_ctrl:1
	v_fmac_f32_dpp v87, v173, v133 row_shr:1 row_mask:0xf bank_mask:0xf bound_ctrl:1
	v_fmac_f32_dpp v84, v170, v126 row_shr:2 row_mask:0xf bank_mask:0xf bound_ctrl:1
	v_fmac_f32_dpp v85, v171, v127 row_shr:2 row_mask:0xf bank_mask:0xf bound_ctrl:1
	v_fmac_f32_dpp v86, v172, v128 row_shr:2 row_mask:0xf bank_mask:0xf bound_ctrl:1
	v_fmac_f32_dpp v87, v173, v129 row_shr:2 row_mask:0xf bank_mask:0xf bound_ctrl:1
	v_fmac_f32_dpp v84, v158, v242 row_ror:1 row_mask:0xf bank_mask:0xf
	v_fmac_f32_dpp v85, v159, v240 row_ror:1 row_mask:0xf bank_mask:0xf
	v_fmac_f32_dpp v86, v160, v238 row_ror:1 row_mask:0xf bank_mask:0xf
	v_fmac_f32_dpp v87, v161, v234 row_ror:1 row_mask:0xf bank_mask:0xf
	v_fmac_f32_dpp v84, v158, v241 row_ror:2 row_mask:0xf bank_mask:0xf
	v_fmac_f32_dpp v85, v159, v239 row_ror:2 row_mask:0xf bank_mask:0xf
	v_fmac_f32_dpp v86, v160, v237 row_ror:2 row_mask:0xf bank_mask:0xf
	v_fmac_f32_dpp v87, v161, v233 row_ror:2 row_mask:0xf bank_mask:0xf
	v_fma_f32 v88, v122, v166, v106
	v_fma_f32 v89, v123, v167, v107
	v_fma_f32 v90, v124, v168, v108
	v_fma_f32 v91, v125, v169, v109
	v_fmac_f32_dpp v88, v166, v114 row_shr:1 row_mask:0xf bank_mask:0xf bound_ctrl:1
	v_fmac_f32_dpp v89, v167, v115 row_shr:1 row_mask:0xf bank_mask:0xf bound_ctrl:1
	v_fmac_f32_dpp v90, v168, v116 row_shr:1 row_mask:0xf bank_mask:0xf bound_ctrl:1
	v_fmac_f32_dpp v91, v169, v117 row_shr:1 row_mask:0xf bank_mask:0xf bound_ctrl:1
	v_fmac_f32_dpp v88, v166, v110 row_shr:2 row_mask:0xf bank_mask:0xf bound_ctrl:1
	v_fmac_f32_dpp v89, v167, v111 row_shr:2 row_mask:0xf bank_mask:0xf bound_ctrl:1
	v_fmac_f32_dpp v90, v168, v112 row_shr:2 row_mask:0xf bank_mask:0xf bound_ctrl:1
	v_fmac_f32_dpp v91, v169, v113 row_shr:2 row_mask:0xf bank_mask:0xf bound_ctrl:1
	v_fmac_f32_dpp v88, v150, v236 row_ror:1 row_mask:0xf bank_mask:0xf
	v_fmac_f32_dpp v89, v151, v232 row_ror:1 row_mask:0xf bank_mask:0xf
	v_fmac_f32_dpp v90, v152, v224 row_ror:1 row_mask:0xf bank_mask:0xf
	v_fmac_f32_dpp v91, v153, v213 row_ror:1 row_mask:0xf bank_mask:0xf
	v_fmac_f32_dpp v88, v150, v235 row_ror:2 row_mask:0xf bank_mask:0xf
	v_fmac_f32_dpp v89, v151, v225 row_ror:2 row_mask:0xf bank_mask:0xf
	v_fmac_f32_dpp v90, v152, v223 row_ror:2 row_mask:0xf bank_mask:0xf
	v_fmac_f32_dpp v91, v153, v211 row_ror:2 row_mask:0xf bank_mask:0xf
	v_exp_f32_e64 v144, -v84
	v_exp_f32_e64 v145, -v85
	v_exp_f32_e64 v150, -v86
	v_exp_f32_e64 v151, -v87
	v_add_f32_e32 v144, 1.0, v144
	v_add_f32_e32 v145, 1.0, v145
	v_add_f32_e32 v150, 1.0, v150
	v_add_f32_e32 v151, 1.0, v151
	v_rcp_f32_e32 v144, v144
	v_rcp_f32_e32 v150, v150
	v_rcp_f32_e32 v151, v151
	v_rcp_f32_e32 v145, v145
	v_pk_mul_f32 v[86:87], v[86:87], v[90:91]
	v_pk_mul_f32 v[84:85], v[84:85], v[88:89]
	v_pk_mul_f32 v[86:87], v[150:151], v[86:87]
	v_pk_mul_f32 v[84:85], v[144:145], v[84:85]
	s_nop 0
	v_cvt_pk_bf16_f32 v90, v84, v85
	v_cvt_pk_bf16_f32 v91, v86, v87
	v_add_u32_e32 v144, s56, v243
	ds_read_b128 v[84:87], v144
	ds_read_b128 v[150:153], v144 offset:256
	v_fma_f32 v88, v134, v146, v98
	v_fmac_f32_dpp v88, v146, v130 row_shr:1 row_mask:0xf bank_mask:0xf bound_ctrl:1
	v_fma_f32 v89, v135, v147, v99
	v_fmac_f32_dpp v88, v146, v126 row_shr:2 row_mask:0xf bank_mask:0xf bound_ctrl:1
	v_fmac_f32_dpp v89, v147, v131 row_shr:1 row_mask:0xf bank_mask:0xf bound_ctrl:1
	v_fma_f32 v154, v136, v148, v100
	s_waitcnt lgkmcnt(0)
; #define PG8_LAS __attribute__((address_space(3)))
; __device__ __forceinline__ unsigned cvt_pk_bf16(float lo, float hi) { unsigned r; asm volatile("v_cvt_pk_bf16_f32 %0, %1, %2" : "=v"(r) : "v"(lo), "v"(hi)); return r; }
; #define PG8_G __attribute__((address_space(1)))
; #define PG8_FMAC_DPP(c_, x_, w_, ctrl_) asm("v_fmac_f32_dpp %0, %1, %2 " ctrl_ : "+v"(c_) : "v"(x_), "v"(w_))
;     PG8_NOPRE
;     __device__ __forceinline__ void operator()(const f32x4 (&acc_)[2][2][4][2], const Unit& u, int wr, int wc, int fr_, int fq_, int ui) const {
;     ...
;                         if (m == 0 && !(ai == 0 && wr == 0)) { const int slot = ai == 0 ? 0 : (wr == 0 ? 1 : 2); const PG8_LAS float* b = xh + (((slot * 4 + wc) * 2) * 4 + fq) * 16 + n * 4 + bj * 8;
;                             h2 = *(const PG8_LAS f32x4*)b; h1 = *(const PG8_LAS f32x4*)(b + 64); }
; #pragma unroll
;                         for (int k = 0; k < 4; ++k) { const float cur = acc[ai][bj][m][n][k];
;                             float cc = fmaf(Wq[bj][2][k], cur, Wq[bj][3][k]);
;                             PG8_FMAC_DPP(cc, cur, Wq[bj][1][k], "row_shr:1 row_mask:0xf bank_mask:0xf bound_ctrl:1");
;                             PG8_FMAC_DPP(cc, cur, Wq[bj][0][k], "row_shr:2 row_mask:0xf bank_mask:0xf bound_ctrl:1");
;                             if (m == 0) { const float z = fr == 0 ? h2[k] : h1[k]; cc = fmaf(W1m[bj][k], h1[k], cc); cc = fmaf(W0m[bj][k], z, cc); }
;                             else { const float p = acc[ai][bj][m > 0 ? m - 1 : 0][n][k]; PG8_FMAC_DPP(cc, p, W1m[bj][k], "row_ror:1 row_mask:0xf bank_mask:0xf"); PG8_FMAC_DPP(cc, p, W0m[bj][k], "row_ror:2 row_mask:0xf bank_mask:0xf"); }
;                             c[bj][k] = cc; }
;     ...
;                         for (int k = 0; k < 4; ++k) ex[k] = __builtin_amdgcn_exp2f(-c[0][k]);
;                         const f32x4 den = ex + 1.0f, gv = c[0] * c[1]; f32x4 rc;
; #pragma unroll
;                         for (int k = 0; k < 4; ++k) rc[k] = __builtin_amdgcn_rcpf(den[k]);
;                         const f32x4 a = gv * rc;
;                         u32x2 w; w.x = cvt_pk_bf16(a[0], a[1]); w.y = cvt_pk_bf16(a[2], a[3]);
;                         if (n == 0) wkeep[ai][m] = w;
;                         else { const u32x4 w4 = {wkeep[ai][m].x, wkeep[ai][m].y, w.x, w.y}; *(PG8_G u32x4*)(ACT + (size_t)row * 5632 + ch0) = w4; }
	v_cndmask_b32_e64 v84, v150, v84, s[10:11]
	v_fmac_f32_e32 v88, v242, v150
	v_fmac_f32_dpp v89, v147, v127 row_shr:2 row_mask:0xf bank_mask:0xf bound_ctrl:1
	v_fmac_f32_dpp v154, v148, v132 row_shr:1 row_mask:0xf bank_mask:0xf bound_ctrl:1
	v_fma_f32 v155, v137, v149, v101
	v_fmac_f32_e32 v88, v241, v84
	v_cndmask_b32_e64 v84, v151, v85, s[10:11]
	v_fmac_f32_e32 v89, v240, v151
	v_fmac_f32_dpp v154, v148, v128 row_shr:2 row_mask:0xf bank_mask:0xf bound_ctrl:1
	v_fmac_f32_dpp v155, v149, v133 row_shr:1 row_mask:0xf bank_mask:0xf bound_ctrl:1
	v_fmac_f32_e32 v89, v239, v84
	v_cndmask_b32_e64 v84, v152, v86, s[10:11]
	v_fmac_f32_e32 v154, v238, v152
	v_fmac_f32_dpp v155, v149, v129 row_shr:2 row_mask:0xf bank_mask:0xf bound_ctrl:1
	v_fmac_f32_e32 v154, v237, v84
	v_cndmask_b32_e64 v84, v153, v87, s[10:11]
	v_fmac_f32_e32 v155, v234, v153
	v_fmac_f32_e32 v155, v233, v84
	ds_read_b128 v[84:87], v144 offset:32
	ds_read_b128 v[150:153], v144 offset:288
	v_fma_f32 v156, v122, v140, v106
	v_fmac_f32_dpp v156, v140, v114 row_shr:1 row_mask:0xf bank_mask:0xf bound_ctrl:1
	v_fma_f32 v157, v123, v141, v107
	v_fmac_f32_dpp v156, v140, v110 row_shr:2 row_mask:0xf bank_mask:0xf bound_ctrl:1
	v_fmac_f32_dpp v157, v141, v115 row_shr:1 row_mask:0xf bank_mask:0xf bound_ctrl:1
	s_waitcnt lgkmcnt(0)
	v_cndmask_b32_e64 v84, v150, v84, s[10:11]
	v_fmac_f32_e32 v156, v236, v150
	v_fmac_f32_dpp v157, v141, v111 row_shr:2 row_mask:0xf bank_mask:0xf bound_ctrl:1
	v_fmac_f32_e32 v156, v235, v84
	v_cndmask_b32_e64 v84, v151, v85, s[10:11]
	v_fmac_f32_e32 v157, v232, v151
	v_fmac_f32_e32 v157, v225, v84
	v_fma_f32 v84, v124, v138, v108
	v_fmac_f32_dpp v84, v138, v116 row_shr:1 row_mask:0xf bank_mask:0xf bound_ctrl:1
	v_cndmask_b32_e64 v85, v152, v86, s[10:11]
	v_fmac_f32_dpp v84, v138, v112 row_shr:2 row_mask:0xf bank_mask:0xf bound_ctrl:1
	v_cndmask_b32_e64 v86, v153, v87, s[10:11]
	v_fmac_f32_e32 v84, v224, v152
	v_fmac_f32_e32 v84, v223, v85
	v_fma_f32 v85, v125, v139, v109
	v_fmac_f32_dpp v85, v139, v117 row_shr:1 row_mask:0xf bank_mask:0xf bound_ctrl:1
	s_nop 0
	v_fmac_f32_dpp v85, v139, v113 row_shr:2 row_mask:0xf bank_mask:0xf bound_ctrl:1
	s_nop 0
	v_fmac_f32_e32 v85, v213, v153
	v_fmac_f32_e32 v85, v211, v86
	v_exp_f32_e64 v145, -v154
	v_exp_f32_e64 v86, -v88
	v_exp_f32_e64 v87, -v89
	v_exp_f32_e64 v151, -v155
	v_add_f32_e32 v145, 1.0, v145
	v_add_f32_e32 v86, 1.0, v86
	v_add_f32_e32 v87, 1.0, v87
	v_rcp_f32_e32 v150, v145
	v_add_f32_e32 v145, 1.0, v151
	v_rcp_f32_e32 v86, v86
	v_rcp_f32_e32 v151, v145
	v_rcp_f32_e32 v87, v87
	v_pk_mul_f32 v[88:89], v[88:89], v[156:157]
	v_pk_mul_f32 v[84:85], v[154:155], v[84:85]
	v_pk_mul_f32 v[86:87], v[86:87], v[88:89]
	v_pk_mul_f32 v[84:85], v[150:151], v[84:85]
	v_cvt_pk_bf16_f32 v88, v86, v87
	s_nop 0
	v_cvt_pk_bf16_f32 v89, v84, v85
	v_fma_f32 v84, v134, v142, v98
	v_fma_f32 v85, v135, v143, v99
	v_fma_f32 v86, v136, v118, v100
	v_fma_f32 v87, v137, v119, v101
	v_fmac_f32_dpp v84, v142, v130 row_shr:1 row_mask:0xf bank_mask:0xf bound_ctrl:1
	v_fmac_f32_dpp v85, v143, v131 row_shr:1 row_mask:0xf bank_mask:0xf bound_ctrl:1
	v_fmac_f32_dpp v86, v118, v132 row_shr:1 row_mask:0xf bank_mask:0xf bound_ctrl:1
	v_fmac_f32_dpp v87, v119, v133 row_shr:1 row_mask:0xf bank_mask:0xf bound_ctrl:1
	v_fmac_f32_dpp v84, v142, v126 row_shr:2 row_mask:0xf bank_mask:0xf bound_ctrl:1
	v_fmac_f32_dpp v85, v143, v127 row_shr:2 row_mask:0xf bank_mask:0xf bound_ctrl:1
	v_fmac_f32_dpp v86, v118, v128 row_shr:2 row_mask:0xf bank_mask:0xf bound_ctrl:1
	v_fmac_f32_dpp v87, v119, v129 row_shr:2 row_mask:0xf bank_mask:0xf bound_ctrl:1
	v_fmac_f32_dpp v84, v146, v242 row_ror:1 row_mask:0xf bank_mask:0xf
	v_fmac_f32_dpp v85, v147, v240 row_ror:1 row_mask:0xf bank_mask:0xf
	v_fmac_f32_dpp v86, v148, v238 row_ror:1 row_mask:0xf bank_mask:0xf
	v_fmac_f32_dpp v87, v149, v234 row_ror:1 row_mask:0xf bank_mask:0xf
	v_fmac_f32_dpp v84, v146, v241 row_ror:2 row_mask:0xf bank_mask:0xf
	v_fmac_f32_dpp v85, v147, v239 row_ror:2 row_mask:0xf bank_mask:0xf
	v_fmac_f32_dpp v86, v148, v237 row_ror:2 row_mask:0xf bank_mask:0xf
	v_fmac_f32_dpp v87, v149, v233 row_ror:2 row_mask:0xf bank_mask:0xf
	v_fma_f32 v146, v122, v102, v106
	v_fma_f32 v147, v123, v103, v107
	v_fmac_f32_dpp v146, v102, v114 row_shr:1 row_mask:0xf bank_mask:0xf bound_ctrl:1
	v_fmac_f32_dpp v147, v103, v115 row_shr:1 row_mask:0xf bank_mask:0xf bound_ctrl:1
	s_nop 0
	v_fmac_f32_dpp v146, v102, v110 row_shr:2 row_mask:0xf bank_mask:0xf bound_ctrl:1
	v_fmac_f32_dpp v147, v103, v111 row_shr:2 row_mask:0xf bank_mask:0xf bound_ctrl:1
	s_nop 0
	v_fmac_f32_dpp v146, v140, v236 row_ror:1 row_mask:0xf bank_mask:0xf
	v_fmac_f32_dpp v147, v141, v232 row_ror:1 row_mask:0xf bank_mask:0xf
	s_nop 0
	v_fmac_f32_dpp v146, v140, v235 row_ror:2 row_mask:0xf bank_mask:0xf
	v_fmac_f32_dpp v147, v141, v225 row_ror:2 row_mask:0xf bank_mask:0xf
	v_fma_f32 v140, v124, v14, v108
	v_fma_f32 v141, v125, v15, v109
	v_fmac_f32_dpp v140, v14, v116 row_shr:1 row_mask:0xf bank_mask:0xf bound_ctrl:1
	v_fmac_f32_dpp v141, v15, v117 row_shr:1 row_mask:0xf bank_mask:0xf bound_ctrl:1
	s_nop 0
	v_fmac_f32_dpp v140, v14, v112 row_shr:2 row_mask:0xf bank_mask:0xf bound_ctrl:1
	v_fmac_f32_dpp v141, v15, v113 row_shr:2 row_mask:0xf bank_mask:0xf bound_ctrl:1
	s_nop 0
	v_fmac_f32_dpp v140, v138, v224 row_ror:1 row_mask:0xf bank_mask:0xf
	v_fmac_f32_dpp v141, v139, v213 row_ror:1 row_mask:0xf bank_mask:0xf
	s_nop 0
	v_fmac_f32_dpp v140, v138, v223 row_ror:2 row_mask:0xf bank_mask:0xf
	v_fmac_f32_dpp v141, v139, v211 row_ror:2 row_mask:0xf bank_mask:0xf
	v_exp_f32_e64 v145, -v86
	v_exp_f32_e64 v138, -v84
	v_exp_f32_e64 v139, -v85
; #define PG8_LAS __attribute__((address_space(3)))
; #define PG8_G __attribute__((address_space(1)))
;     PG8_NOPRE
;     __device__ __forceinline__ void operator()(const f32x4 (&acc_)[2][2][4][2], const Unit& u, int wr, int wc, int fr_, int fq_, int ui) const {
;     ...
;             for (int ai = 0; ai < 2; ++ai)
; #pragma unroll
;                 for (int m = 0; m < 4; ++m) {
;                     f32x4 c[2];
; #pragma unroll
;                     for (int bj = 0; bj < 2; ++bj) {
;                         f32x4 h1 = {0.f, 0.f, 0.f, 0.f}, h2 = {0.f, 0.f, 0.f, 0.f};
;                         if (m == 0 && !(ai == 0 && wr == 0)) { const int slot = ai == 0 ? 0 : (wr == 0 ? 1 : 2); const PG8_LAS float* b = xh + (((slot * 4 + wc) * 2) * 4 + fq) * 16 + n * 4 + bj * 8;
;                             h2 = *(const PG8_LAS f32x4*)b; h1 = *(const PG8_LAS f32x4*)(b + 64); }
; #pragma unroll
;                         for (int k = 0; k < 4; ++k) { const float cur = acc[ai][bj][m][n][k];
;                             float cc = fmaf(Wq[bj][2][k], cur, Wq[bj][3][k]);
;                             PG8_FMAC_DPP(cc, cur, Wq[bj][1][k], "row_shr:1 row_mask:0xf bank_mask:0xf bound_ctrl:1");
;                             PG8_FMAC_DPP(cc, cur, Wq[bj][0][k], "row_shr:2 row_mask:0xf bank_mask:0xf bound_ctrl:1");
;                             if (m == 0) { const float z = fr == 0 ? h2[k] : h1[k]; cc = fmaf(W1m[bj][k], h1[k], cc); cc = fmaf(W0m[bj][k], z, cc); }
;                             else { const float p = acc[ai][bj][m > 0 ? m - 1 : 0][n][k]; PG8_FMAC_DPP(cc, p, W1m[bj][k], "row_ror:1 row_mask:0xf bank_mask:0xf"); PG8_FMAC_DPP(cc, p, W0m[bj][k], "row_ror:2 row_mask:0xf bank_mask:0xf"); }
;                             c[bj][k] = cc; }
;     ...
;                         for (int k = 0; k < 4; ++k) ex[k] = __builtin_amdgcn_exp2f(-c[0][k]);
;                         const f32x4 den = ex + 1.0f, gv = c[0] * c[1]; f32x4 rc;
; #pragma unroll
;                         for (int k = 0; k < 4; ++k) rc[k] = __builtin_amdgcn_rcpf(den[k]);
;                         const f32x4 a = gv * rc;
;                         u32x2 w; w.x = cvt_pk_bf16(a[0], a[1]); w.y = cvt_pk_bf16(a[2], a[3]);
;                         if (n == 0) wkeep[ai][m] = w;
;                         else { const u32x4 w4 = {wkeep[ai][m].x, wkeep[ai][m].y, w.x, w.y}; *(PG8_G u32x4*)(ACT + (size_t)row * 5632 + ch0) = w4; }
	v_exp_f32_e64 v149, -v87
	v_add_f32_e32 v145, 1.0, v145
	v_add_f32_e32 v138, 1.0, v138
	v_add_f32_e32 v139, 1.0, v139
	v_rcp_f32_e32 v148, v145
	v_add_f32_e32 v145, 1.0, v149
	v_rcp_f32_e32 v138, v138
	v_rcp_f32_e32 v149, v145
	v_rcp_f32_e32 v139, v139
	v_pk_mul_f32 v[86:87], v[86:87], v[140:141]
	v_pk_mul_f32 v[84:85], v[84:85], v[146:147]
	v_pk_mul_f32 v[140:141], v[148:149], v[86:87]
	v_pk_mul_f32 v[84:85], v[138:139], v[84:85]
	s_nop 0
	v_cvt_pk_bf16_f32 v86, v84, v85
	v_cvt_pk_bf16_f32 v87, v140, v141
	v_fma_f32 v84, v134, v12, v98
	v_fma_f32 v85, v135, v13, v99
	v_fma_f32 v138, v136, v8, v100
	v_fma_f32 v139, v137, v9, v101
	v_fmac_f32_dpp v84, v12, v130 row_shr:1 row_mask:0xf bank_mask:0xf bound_ctrl:1
	v_fmac_f32_dpp v85, v13, v131 row_shr:1 row_mask:0xf bank_mask:0xf bound_ctrl:1
	v_fmac_f32_dpp v138, v8, v132 row_shr:1 row_mask:0xf bank_mask:0xf bound_ctrl:1
	v_fmac_f32_dpp v139, v9, v133 row_shr:1 row_mask:0xf bank_mask:0xf bound_ctrl:1
	v_fmac_f32_dpp v84, v12, v126 row_shr:2 row_mask:0xf bank_mask:0xf bound_ctrl:1
	v_fmac_f32_dpp v85, v13, v127 row_shr:2 row_mask:0xf bank_mask:0xf bound_ctrl:1
	v_fmac_f32_dpp v138, v8, v128 row_shr:2 row_mask:0xf bank_mask:0xf bound_ctrl:1
	v_fmac_f32_dpp v139, v9, v129 row_shr:2 row_mask:0xf bank_mask:0xf bound_ctrl:1
	v_fmac_f32_dpp v84, v142, v242 row_ror:1 row_mask:0xf bank_mask:0xf
	v_fmac_f32_dpp v85, v143, v240 row_ror:1 row_mask:0xf bank_mask:0xf
	v_fmac_f32_dpp v138, v118, v238 row_ror:1 row_mask:0xf bank_mask:0xf
	v_fmac_f32_dpp v139, v119, v234 row_ror:1 row_mask:0xf bank_mask:0xf
	v_fmac_f32_dpp v84, v142, v241 row_ror:2 row_mask:0xf bank_mask:0xf
	v_fmac_f32_dpp v85, v143, v239 row_ror:2 row_mask:0xf bank_mask:0xf
	v_fmac_f32_dpp v138, v118, v237 row_ror:2 row_mask:0xf bank_mask:0xf
	v_fmac_f32_dpp v139, v119, v233 row_ror:2 row_mask:0xf bank_mask:0xf
	v_fma_f32 v118, v122, v6, v106
	v_fma_f32 v119, v123, v7, v107
	v_fmac_f32_dpp v118, v6, v114 row_shr:1 row_mask:0xf bank_mask:0xf bound_ctrl:1
	v_fmac_f32_dpp v119, v7, v115 row_shr:1 row_mask:0xf bank_mask:0xf bound_ctrl:1
	s_nop 0
	v_fmac_f32_dpp v118, v6, v110 row_shr:2 row_mask:0xf bank_mask:0xf bound_ctrl:1
	v_fmac_f32_dpp v119, v7, v111 row_shr:2 row_mask:0xf bank_mask:0xf bound_ctrl:1
	s_nop 0
	v_fmac_f32_dpp v118, v102, v236 row_ror:1 row_mask:0xf bank_mask:0xf
	v_fmac_f32_dpp v119, v103, v232 row_ror:1 row_mask:0xf bank_mask:0xf
	s_nop 0
	v_fmac_f32_dpp v118, v102, v235 row_ror:2 row_mask:0xf bank_mask:0xf
	v_fmac_f32_dpp v119, v103, v225 row_ror:2 row_mask:0xf bank_mask:0xf
	v_fma_f32 v102, v124, v4, v108
	v_fma_f32 v103, v125, v5, v109
	v_fmac_f32_dpp v102, v4, v116 row_shr:1 row_mask:0xf bank_mask:0xf bound_ctrl:1
	v_fmac_f32_dpp v103, v5, v117 row_shr:1 row_mask:0xf bank_mask:0xf bound_ctrl:1
	s_nop 0
	v_fmac_f32_dpp v102, v4, v112 row_shr:2 row_mask:0xf bank_mask:0xf bound_ctrl:1
	v_fmac_f32_dpp v103, v5, v113 row_shr:2 row_mask:0xf bank_mask:0xf bound_ctrl:1
	s_nop 0
	v_fmac_f32_dpp v102, v14, v224 row_ror:1 row_mask:0xf bank_mask:0xf
	v_fmac_f32_dpp v103, v15, v213 row_ror:1 row_mask:0xf bank_mask:0xf
	s_nop 0
	v_fmac_f32_dpp v102, v14, v223 row_ror:2 row_mask:0xf bank_mask:0xf
	v_fmac_f32_dpp v103, v15, v211 row_ror:2 row_mask:0xf bank_mask:0xf
	v_exp_f32_e64 v14, -v84
	v_exp_f32_e64 v15, -v85
	v_exp_f32_e64 v140, -v138
	v_exp_f32_e64 v141, -v139
	v_add_f32_e32 v14, 1.0, v14
	v_add_f32_e32 v15, 1.0, v15
	v_add_f32_e32 v140, 1.0, v140
	v_add_f32_e32 v141, 1.0, v141
	v_rcp_f32_e32 v14, v14
	v_rcp_f32_e32 v140, v140
	v_rcp_f32_e32 v141, v141
	v_rcp_f32_e32 v15, v15
	v_pk_mul_f32 v[102:103], v[138:139], v[102:103]
	v_pk_mul_f32 v[84:85], v[84:85], v[118:119]
	v_pk_mul_f32 v[102:103], v[140:141], v[102:103]
	v_pk_mul_f32 v[14:15], v[14:15], v[84:85]
	s_nop 0
	v_cvt_pk_bf16_f32 v84, v14, v15
	v_cvt_pk_bf16_f32 v85, v102, v103
	v_fma_f32 v14, v134, v92, v98
	v_fma_f32 v15, v135, v93, v99
	v_fma_f32 v100, v136, v94, v100
	v_fmac_f32_e32 v101, v137, v95
	v_fmac_f32_dpp v14, v92, v130 row_shr:1 row_mask:0xf bank_mask:0xf bound_ctrl:1
	v_fmac_f32_dpp v15, v93, v131 row_shr:1 row_mask:0xf bank_mask:0xf bound_ctrl:1
	v_fmac_f32_dpp v100, v94, v132 row_shr:1 row_mask:0xf bank_mask:0xf bound_ctrl:1
	v_fmac_f32_dpp v101, v95, v133 row_shr:1 row_mask:0xf bank_mask:0xf bound_ctrl:1
	v_fmac_f32_dpp v14, v92, v126 row_shr:2 row_mask:0xf bank_mask:0xf bound_ctrl:1
	v_fmac_f32_dpp v15, v93, v127 row_shr:2 row_mask:0xf bank_mask:0xf bound_ctrl:1
; #define PG8_LAS __attribute__((address_space(3)))
; #define PG8_FMAC_DPP(c_, x_, w_, ctrl_) asm("v_fmac_f32_dpp %0, %1, %2 " ctrl_ : "+v"(c_) : "v"(x_), "v"(w_))
;     PG8_NOPRE
;     __device__ __forceinline__ void operator()(const f32x4 (&acc_)[2][2][4][2], const Unit& u, int wr, int wc, int fr_, int fq_, int ui) const {
;     ...
;                 for (int t = 0; t < 4; ++t) Wq[bj][t] = *(const PG8_LAS f32x4*)(cwb + t * 256 + bj * 128);
; #pragma unroll
;                 for (int k = 0; k < 4; ++k) { W1m[bj][k] = fr == 0 ? Wq[bj][1][k] : 0.f; W0m[bj][k] = fr < 2 ? Wq[bj][0][k] : 0.f; } }
; #pragma unroll
;             for (int ai = 0; ai < 2; ++ai)
; #pragma unroll
;                 for (int m = 0; m < 4; ++m) {
;                     f32x4 c[2];
; #pragma unroll
;                     for (int bj = 0; bj < 2; ++bj) {
;                         f32x4 h1 = {0.f, 0.f, 0.f, 0.f}, h2 = {0.f, 0.f, 0.f, 0.f};
;                         if (m == 0 && !(ai == 0 && wr == 0)) { const int slot = ai == 0 ? 0 : (wr == 0 ? 1 : 2); const PG8_LAS float* b = xh + (((slot * 4 + wc) * 2) * 4 + fq) * 16 + n * 4 + bj * 8;
;                             h2 = *(const PG8_LAS f32x4*)b; h1 = *(const PG8_LAS f32x4*)(b + 64); }
; #pragma unroll
;                         for (int k = 0; k < 4; ++k) { const float cur = acc[ai][bj][m][n][k];
;                             float cc = fmaf(Wq[bj][2][k], cur, Wq[bj][3][k]);
;                             PG8_FMAC_DPP(cc, cur, Wq[bj][1][k], "row_shr:1 row_mask:0xf bank_mask:0xf bound_ctrl:1");
;                             PG8_FMAC_DPP(cc, cur, Wq[bj][0][k], "row_shr:2 row_mask:0xf bank_mask:0xf bound_ctrl:1");
;                             if (m == 0) { const float z = fr == 0 ? h2[k] : h1[k]; cc = fmaf(W1m[bj][k], h1[k], cc); cc = fmaf(W0m[bj][k], z, cc); }
;                             else { const float p = acc[ai][bj][m > 0 ? m - 1 : 0][n][k]; PG8_FMAC_DPP(cc, p, W1m[bj][k], "row_ror:1 row_mask:0xf bank_mask:0xf"); PG8_FMAC_DPP(cc, p, W0m[bj][k], "row_ror:2 row_mask:0xf bank_mask:0xf"); }
;                             c[bj][k] = cc; }
	v_fmac_f32_dpp v100, v94, v128 row_shr:2 row_mask:0xf bank_mask:0xf bound_ctrl:1
	v_fmac_f32_dpp v101, v95, v129 row_shr:2 row_mask:0xf bank_mask:0xf bound_ctrl:1
	v_fmac_f32_dpp v14, v12, v242 row_ror:1 row_mask:0xf bank_mask:0xf
	v_fmac_f32_dpp v15, v13, v240 row_ror:1 row_mask:0xf bank_mask:0xf
	v_fmac_f32_dpp v100, v8, v238 row_ror:1 row_mask:0xf bank_mask:0xf
	v_fmac_f32_dpp v101, v9, v234 row_ror:1 row_mask:0xf bank_mask:0xf
	v_fmac_f32_dpp v14, v12, v241 row_ror:2 row_mask:0xf bank_mask:0xf
	v_fmac_f32_dpp v15, v13, v239 row_ror:2 row_mask:0xf bank_mask:0xf
	v_fmac_f32_dpp v100, v8, v237 row_ror:2 row_mask:0xf bank_mask:0xf
	v_fmac_f32_dpp v101, v9, v233 row_ror:2 row_mask:0xf bank_mask:0xf
	v_fma_f32 v8, v122, v80, v106
	v_fma_f32 v9, v123, v81, v107
	v_fma_f32 v108, v124, v82, v108
	v_fmac_f32_e32 v109, v125, v83
	v_fmac_f32_dpp v8, v80, v114 row_shr:1 row_mask:0xf bank_mask:0xf bound_ctrl:1
	v_fmac_f32_dpp v9, v81, v115 row_shr:1 row_mask:0xf bank_mask:0xf bound_ctrl:1
	v_fmac_f32_dpp v108, v82, v116 row_shr:1 row_mask:0xf bank_mask:0xf bound_ctrl:1
	v_fmac_f32_dpp v109, v83, v117 row_shr:1 row_mask:0xf bank_mask:0xf bound_ctrl:1
	v_fmac_f32_dpp v8, v80, v110 row_shr:2 row_mask:0xf bank_mask:0xf bound_ctrl:1
	v_fmac_f32_dpp v9, v81, v111 row_shr:2 row_mask:0xf bank_mask:0xf bound_ctrl:1
	v_fmac_f32_dpp v108, v82, v112 row_shr:2 row_mask:0xf bank_mask:0xf bound_ctrl:1
	v_fmac_f32_dpp v109, v83, v113 row_shr:2 row_mask:0xf bank_mask:0xf bound_ctrl:1
	v_fmac_f32_dpp v8, v6, v236 row_ror:1 row_mask:0xf bank_mask:0xf
	v_fmac_f32_dpp v9, v7, v232 row_ror:1 row_mask:0xf bank_mask:0xf
	v_fmac_f32_dpp v108, v4, v224 row_ror:1 row_mask:0xf bank_mask:0xf
	v_fmac_f32_dpp v109, v5, v213 row_ror:1 row_mask:0xf bank_mask:0xf
	v_fmac_f32_dpp v8, v6, v235 row_ror:2 row_mask:0xf bank_mask:0xf
	v_fmac_f32_dpp v9, v7, v225 row_ror:2 row_mask:0xf bank_mask:0xf
	v_fmac_f32_dpp v108, v4, v223 row_ror:2 row_mask:0xf bank_mask:0xf
	v_fmac_f32_dpp v109, v5, v211 row_ror:2 row_mask:0xf bank_mask:0xf
	v_exp_f32_e64 v4, -v14
	v_exp_f32_e64 v5, -v15
	v_exp_f32_e64 v6, -v100
	v_exp_f32_e64 v7, -v101
	v_add_f32_e32 v4, 1.0, v4
	v_add_f32_e32 v5, 1.0, v5
	v_add_f32_e32 v6, 1.0, v6
	v_add_f32_e32 v7, 1.0, v7
	v_rcp_f32_e32 v4, v4
	v_rcp_f32_e32 v6, v6
	v_rcp_f32_e32 v7, v7
	v_rcp_f32_e32 v5, v5
	v_pk_mul_f32 v[12:13], v[100:101], v[108:109]
	v_pk_mul_f32 v[8:9], v[14:15], v[8:9]
	v_pk_mul_f32 v[6:7], v[6:7], v[12:13]
	v_pk_mul_f32 v[4:5], v[4:5], v[8:9]
	s_nop 0
	v_cvt_pk_bf16_f32 v12, v4, v5
	v_cvt_pk_bf16_f32 v13, v6, v7
	ds_read_b128 v[124:127], v200 offset:16
	ds_read_b128 v[108:111], v200 offset:528
	ds_read_b128 v[128:131], v200 offset:1040
	ds_read_b128 v[112:115], v200 offset:1552
	ds_read_b128 v[132:135], v200 offset:2064
	ds_read_b128 v[116:119], v200 offset:2576
	ds_read_b128 v[80:83], v200 offset:3088
	ds_read_b128 v[100:103], v200 offset:3600
	v_mov_b32_e32 v6, 0
	s_and_b64 vcc, exec, s[14:15]
	v_mov_b32_e32 v92, 0
	v_mov_b32_e32 v93, 0
	v_mov_b32_e32 v94, 0
	v_mov_b32_e32 v95, 0
	v_mov_b32_e32 v136, 0
	v_mov_b32_e32 v137, 0
	v_mov_b32_e32 v138, 0
	v_mov_b32_e32 v139, 0
	s_cbranch_vccnz .LBB0_565
	ds_read_b128 v[136:139], v197 offset:16
	ds_read_b128 v[92:95], v197 offset:272
.LBB0_565:
	v_mov_b32_e32 v122, v216
	v_mov_b32_e32 v123, v216
	v_pk_mul_f32 v[98:99], v[74:75], v[122:123]
	v_pk_mul_f32 v[106:107], v[72:73], v[216:217]
	s_waitcnt lgkmcnt(0)
	v_fma_f32 v14, v134, v98, v82
	v_fma_f32 v4, v132, v106, v80
	v_fma_f32 v5, v133, v107, v81
	v_fma_f32 v15, v135, v99, v83
	v_fmac_f32_dpp v4, v106, v128 row_shr:1 row_mask:0xf bank_mask:0xf bound_ctrl:1
	v_fmac_f32_dpp v5, v107, v129 row_shr:1 row_mask:0xf bank_mask:0xf bound_ctrl:1
	v_fmac_f32_dpp v14, v98, v130 row_shr:1 row_mask:0xf bank_mask:0xf bound_ctrl:1
	v_fmac_f32_dpp v15, v99, v131 row_shr:1 row_mask:0xf bank_mask:0xf bound_ctrl:1
	v_fmac_f32_dpp v4, v106, v124 row_shr:2 row_mask:0xf bank_mask:0xf bound_ctrl:1
	v_fmac_f32_dpp v5, v107, v125 row_shr:2 row_mask:0xf bank_mask:0xf bound_ctrl:1
	v_fmac_f32_dpp v14, v98, v126 row_shr:2 row_mask:0xf bank_mask:0xf bound_ctrl:1
	v_fmac_f32_dpp v15, v99, v127 row_shr:2 row_mask:0xf bank_mask:0xf bound_ctrl:1
	s_and_b64 vcc, exec, s[14:15]
	v_mov_b32_e32 v7, 0
	v_mov_b32_e32 v8, 0
	v_mov_b32_e32 v9, 0
	v_mov_b32_e32 v72, 0
	v_mov_b32_e32 v73, 0
	v_mov_b32_e32 v74, 0
	v_mov_b32_e32 v75, 0
	s_cbranch_vccnz .LBB0_567
	ds_read_b128 v[72:75], v197 offset:48
	ds_read_b128 v[6:9], v197 offset:304

; #define PG8_LAS __attribute__((address_space(3)))
; #define PG8_G __attribute__((address_space(1)))
;     PG8_NOPRE
;     __device__ __forceinline__ void operator()(const f32x4 (&acc_)[2][2][4][2], const Unit& u, int wr, int wc, int fr_, int fq_, int ui) const {
;     ...
;             for (int ai = 0; ai < 2; ++ai)
; #pragma unroll
;                 for (int m = 0; m < 4; ++m) {
;                     f32x4 c[2];
; #pragma unroll
;                     for (int bj = 0; bj < 2; ++bj) {
;                         f32x4 h1 = {0.f, 0.f, 0.f, 0.f}, h2 = {0.f, 0.f, 0.f, 0.f};
;                         if (m == 0 && !(ai == 0 && wr == 0)) { const int slot = ai == 0 ? 0 : (wr == 0 ? 1 : 2); const PG8_LAS float* b = xh + (((slot * 4 + wc) * 2) * 4 + fq) * 16 + n * 4 + bj * 8;
;                             h2 = *(const PG8_LAS f32x4*)b; h1 = *(const PG8_LAS f32x4*)(b + 64); }
; #pragma unroll
;                         for (int k = 0; k < 4; ++k) { const float cur = acc[ai][bj][m][n][k];
;                             float cc = fmaf(Wq[bj][2][k], cur, Wq[bj][3][k]);
;                             PG8_FMAC_DPP(cc, cur, Wq[bj][1][k], "row_shr:1 row_mask:0xf bank_mask:0xf bound_ctrl:1");
;                             PG8_FMAC_DPP(cc, cur, Wq[bj][0][k], "row_shr:2 row_mask:0xf bank_mask:0xf bound_ctrl:1");
;                             if (m == 0) { const float z = fr == 0 ? h2[k] : h1[k]; cc = fmaf(W1m[bj][k], h1[k], cc); cc = fmaf(W0m[bj][k], z, cc); }
;                             else { const float p = acc[ai][bj][m > 0 ? m - 1 : 0][n][k]; PG8_FMAC_DPP(cc, p, W1m[bj][k], "row_ror:1 row_mask:0xf bank_mask:0xf"); PG8_FMAC_DPP(cc, p, W0m[bj][k], "row_ror:2 row_mask:0xf bank_mask:0xf"); }
;                             c[bj][k] = cc; }
;     ...
;                         for (int k = 0; k < 4; ++k) ex[k] = __builtin_amdgcn_exp2f(-c[0][k]);
;                         const f32x4 den = ex + 1.0f, gv = c[0] * c[1]; f32x4 rc;
; #pragma unroll
;                         for (int k = 0; k < 4; ++k) rc[k] = __builtin_amdgcn_rcpf(den[k]);
;                         const f32x4 a = gv * rc;
;                         u32x2 w; w.x = cvt_pk_bf16(a[0], a[1]); w.y = cvt_pk_bf16(a[2], a[3]);
;                         if (n == 0) wkeep[ai][m] = w;
;                         else { const u32x4 w4 = {wkeep[ai][m].x, wkeep[ai][m].y, w.x, w.y}; *(PG8_G u32x4*)(ACT + (size_t)row * 5632 + ch0) = w4; }
.LBB0_571:
	s_or_b64 exec, exec, s[12:13]
	v_mov_b32_e32 v213, v212
	v_mov_b32_e32 v211, v210
	v_mov_b32_e32 v4, v198
	v_mov_b32_e32 v5, v198
	v_mov_b32_e32 v6, v199
	v_mov_b32_e32 v7, v199
	v_mov_b32_e32 v197, v196
	v_mov_b32_e32 v8, v212
	v_mov_b32_e32 v9, v212
	v_mov_b32_e32 v10, v210
	v_mov_b32_e32 v11, v210
	v_mov_b32_e32 v14, v198
	v_mov_b32_e32 v15, v198
	v_mov_b32_e32 v198, v199
	v_mov_b32_e32 v64, v196
	v_mov_b32_e32 v65, v196
	v_pk_mul_f32 v[62:63], v[62:63], v[8:9]
	v_pk_mul_f32 v[60:61], v[60:61], v[212:213]
	v_pk_mul_f32 v[58:59], v[58:59], v[10:11]
	v_pk_mul_f32 v[56:57], v[56:57], v[210:211]
	v_pk_mul_f32 v[54:55], v[54:55], v[8:9]
	v_pk_mul_f32 v[52:53], v[52:53], v[212:213]
	v_pk_mul_f32 v[50:51], v[50:51], v[10:11]
	v_pk_mul_f32 v[48:49], v[48:49], v[210:211]
	v_pk_mul_f32 v[46:47], v[46:47], v[14:15]
	v_pk_mul_f32 v[44:45], v[44:45], v[4:5]
	v_pk_mul_f32 v[42:43], v[42:43], v[198:199]
	v_pk_mul_f32 v[40:41], v[40:41], v[6:7]
	v_pk_mul_f32 v[8:9], v[38:39], v[64:65]
	v_pk_mul_f32 v[10:11], v[36:37], v[196:197]
	v_pk_mul_f32 v[34:35], v[34:35], v[14:15]
	v_pk_mul_f32 v[32:33], v[32:33], v[4:5]
	v_pk_mul_f32 v[14:15], v[30:31], v[198:199]
	v_pk_mul_f32 v[28:29], v[28:29], v[6:7]
	v_pk_mul_f32 v[4:5], v[26:27], v[64:65]
	v_pk_mul_f32 v[6:7], v[24:25], v[196:197]
	v_add_u32_e32 v30, 0xb0, v153
	v_add_u32_e32 v31, 0xa0, v153
	v_add_u32_e32 v36, 0x90, v153
	v_add_u32_e32 v37, 0x80, v153
	v_add_u32_e32 v38, 48, v153
	v_add_u32_e32 v39, 32, v153
	v_add_u32_e32 v120, 16, v153
	v_fma_f32 v24, v132, v60, v80
	v_fma_f32 v25, v133, v61, v81
	v_fma_f32 v26, v134, v62, v82
	v_fma_f32 v27, v135, v63, v83
	v_fmac_f32_dpp v24, v60, v128 row_shr:1 row_mask:0xf bank_mask:0xf bound_ctrl:1
	v_fmac_f32_dpp v25, v61, v129 row_shr:1 row_mask:0xf bank_mask:0xf bound_ctrl:1
	v_fmac_f32_dpp v26, v62, v130 row_shr:1 row_mask:0xf bank_mask:0xf bound_ctrl:1
	v_fmac_f32_dpp v27, v63, v131 row_shr:1 row_mask:0xf bank_mask:0xf bound_ctrl:1
	v_fmac_f32_dpp v24, v60, v124 row_shr:2 row_mask:0xf bank_mask:0xf bound_ctrl:1
	v_fmac_f32_dpp v25, v61, v125 row_shr:2 row_mask:0xf bank_mask:0xf bound_ctrl:1
	v_fmac_f32_dpp v26, v62, v126 row_shr:2 row_mask:0xf bank_mask:0xf bound_ctrl:1
	v_fmac_f32_dpp v27, v63, v127 row_shr:2 row_mask:0xf bank_mask:0xf bound_ctrl:1
	v_fmac_f32_dpp v24, v106, v152 row_ror:1 row_mask:0xf bank_mask:0xf
	v_fmac_f32_dpp v25, v107, v150 row_ror:1 row_mask:0xf bank_mask:0xf
	v_fmac_f32_dpp v26, v98, v148 row_ror:1 row_mask:0xf bank_mask:0xf
	v_fmac_f32_dpp v27, v99, v143 row_ror:1 row_mask:0xf bank_mask:0xf
	v_fmac_f32_dpp v24, v106, v151 row_ror:2 row_mask:0xf bank_mask:0xf
	v_fmac_f32_dpp v25, v107, v149 row_ror:2 row_mask:0xf bank_mask:0xf
	v_fmac_f32_dpp v26, v98, v147 row_ror:2 row_mask:0xf bank_mask:0xf
	v_fmac_f32_dpp v27, v99, v141 row_ror:2 row_mask:0xf bank_mask:0xf
	v_fma_f32 v64, v116, v52, v100
	v_fma_f32 v65, v117, v53, v101
	v_fma_f32 v66, v118, v54, v102
	v_fma_f32 v67, v119, v55, v103
	v_fmac_f32_dpp v64, v52, v112 row_shr:1 row_mask:0xf bank_mask:0xf bound_ctrl:1
	v_fmac_f32_dpp v65, v53, v113 row_shr:1 row_mask:0xf bank_mask:0xf bound_ctrl:1
	v_fmac_f32_dpp v66, v54, v114 row_shr:1 row_mask:0xf bank_mask:0xf bound_ctrl:1
	v_fmac_f32_dpp v67, v55, v115 row_shr:1 row_mask:0xf bank_mask:0xf bound_ctrl:1
	v_fmac_f32_dpp v64, v52, v108 row_shr:2 row_mask:0xf bank_mask:0xf bound_ctrl:1
	v_fmac_f32_dpp v65, v53, v109 row_shr:2 row_mask:0xf bank_mask:0xf bound_ctrl:1
	v_fmac_f32_dpp v66, v54, v110 row_shr:2 row_mask:0xf bank_mask:0xf bound_ctrl:1
	v_fmac_f32_dpp v67, v55, v111 row_shr:2 row_mask:0xf bank_mask:0xf bound_ctrl:1
	v_fmac_f32_dpp v64, v94, v146 row_ror:1 row_mask:0xf bank_mask:0xf
	v_fmac_f32_dpp v65, v95, v142 row_ror:1 row_mask:0xf bank_mask:0xf
	v_fmac_f32_dpp v66, v92, v139 row_ror:1 row_mask:0xf bank_mask:0xf
	v_fmac_f32_dpp v67, v93, v137 row_ror:1 row_mask:0xf bank_mask:0xf
	v_fmac_f32_dpp v64, v94, v145 row_ror:2 row_mask:0xf bank_mask:0xf
	v_fmac_f32_dpp v65, v95, v140 row_ror:2 row_mask:0xf bank_mask:0xf
	v_fmac_f32_dpp v66, v92, v138 row_ror:2 row_mask:0xf bank_mask:0xf
	v_fmac_f32_dpp v67, v93, v136 row_ror:2 row_mask:0xf bank_mask:0xf
	v_exp_f32_e64 v72, -v24
	v_exp_f32_e64 v73, -v25
	v_exp_f32_e64 v74, -v26
	v_exp_f32_e64 v75, -v27
	v_add_f32_e32 v72, 1.0, v72
	v_add_f32_e32 v73, 1.0, v73
	v_rcp_f32_e32 v72, v72
	v_add_f32_e32 v74, 1.0, v74
	v_add_f32_e32 v75, 1.0, v75
	v_rcp_f32_e32 v73, v73
	v_rcp_f32_e32 v74, v74
	v_rcp_f32_e32 v75, v75
	v_pk_mul_f32 v[24:25], v[24:25], v[64:65]
	v_pk_mul_f32 v[26:27], v[26:27], v[66:67]
	v_pk_mul_f32 v[24:25], v[72:73], v[24:25]
	v_pk_mul_f32 v[26:27], v[74:75], v[26:27]
	v_cvt_pk_bf16_f32 v106, v24, v25
	v_mov_b64_e32 v[24:25], s[50:51]
	v_cvt_pk_bf16_f32 v107, v26, v27
	v_mad_i64_i32 v[64:65], s[12:13], v120, s47, v[24:25]
	v_lshlrev_b64 v[26:27], 1, v[194:195]
	v_lshl_add_u64 v[64:65], v[64:65], 0, v[26:27]
	global_store_dwordx4 v[64:65], v[104:107], off
	v_fma_f32 v64, v132, v56, v80
	v_fma_f32 v65, v133, v57, v81
	v_fmac_f32_dpp v64, v56, v128 row_shr:1 row_mask:0xf bank_mask:0xf bound_ctrl:1
	v_fmac_f32_dpp v65, v57, v129 row_shr:1 row_mask:0xf bank_mask:0xf bound_ctrl:1
	s_nop 0
	v_fmac_f32_dpp v64, v56, v124 row_shr:2 row_mask:0xf bank_mask:0xf bound_ctrl:1
	v_fmac_f32_dpp v65, v57, v125 row_shr:2 row_mask:0xf bank_mask:0xf bound_ctrl:1
	s_nop 0
	v_fmac_f32_dpp v64, v60, v152 row_ror:1 row_mask:0xf bank_mask:0xf
	v_fmac_f32_dpp v65, v61, v150 row_ror:1 row_mask:0xf bank_mask:0xf
	s_nop 0
	v_fmac_f32_dpp v64, v60, v151 row_ror:2 row_mask:0xf bank_mask:0xf
	v_fmac_f32_dpp v65, v61, v149 row_ror:2 row_mask:0xf bank_mask:0xf
	v_fma_f32 v60, v134, v58, v82
; #define PG8_LAS __attribute__((address_space(3)))
; #define PG8_G __attribute__((address_space(1)))
;     PG8_NOPRE
;     __device__ __forceinline__ void operator()(const f32x4 (&acc_)[2][2][4][2], const Unit& u, int wr, int wc, int fr_, int fq_, int ui) const {
;     ...
;             for (int ai = 0; ai < 2; ++ai)
; #pragma unroll
;                 for (int m = 0; m < 4; ++m) {
;                     f32x4 c[2];
; #pragma unroll
;                     for (int bj = 0; bj < 2; ++bj) {
;                         f32x4 h1 = {0.f, 0.f, 0.f, 0.f}, h2 = {0.f, 0.f, 0.f, 0.f};
;                         if (m == 0 && !(ai == 0 && wr == 0)) { const int slot = ai == 0 ? 0 : (wr == 0 ? 1 : 2); const PG8_LAS float* b = xh + (((slot * 4 + wc) * 2) * 4 + fq) * 16 + n * 4 + bj * 8;
;                             h2 = *(const PG8_LAS f32x4*)b; h1 = *(const PG8_LAS f32x4*)(b + 64); }
; #pragma unroll
;                         for (int k = 0; k < 4; ++k) { const float cur = acc[ai][bj][m][n][k];
;                             float cc = fmaf(Wq[bj][2][k], cur, Wq[bj][3][k]);
;                             PG8_FMAC_DPP(cc, cur, Wq[bj][1][k], "row_shr:1 row_mask:0xf bank_mask:0xf bound_ctrl:1");
;                             PG8_FMAC_DPP(cc, cur, Wq[bj][0][k], "row_shr:2 row_mask:0xf bank_mask:0xf bound_ctrl:1");
;                             if (m == 0) { const float z = fr == 0 ? h2[k] : h1[k]; cc = fmaf(W1m[bj][k], h1[k], cc); cc = fmaf(W0m[bj][k], z, cc); }
;                             else { const float p = acc[ai][bj][m > 0 ? m - 1 : 0][n][k]; PG8_FMAC_DPP(cc, p, W1m[bj][k], "row_ror:1 row_mask:0xf bank_mask:0xf"); PG8_FMAC_DPP(cc, p, W0m[bj][k], "row_ror:2 row_mask:0xf bank_mask:0xf"); }
;                             c[bj][k] = cc; }
;     ...
;                         for (int k = 0; k < 4; ++k) ex[k] = __builtin_amdgcn_exp2f(-c[0][k]);
;                         const f32x4 den = ex + 1.0f, gv = c[0] * c[1]; f32x4 rc;
; #pragma unroll
;                         for (int k = 0; k < 4; ++k) rc[k] = __builtin_amdgcn_rcpf(den[k]);
;                         const f32x4 a = gv * rc;
;                         u32x2 w; w.x = cvt_pk_bf16(a[0], a[1]); w.y = cvt_pk_bf16(a[2], a[3]);
;                         if (n == 0) wkeep[ai][m] = w;
;                         else { const u32x4 w4 = {wkeep[ai][m].x, wkeep[ai][m].y, w.x, w.y}; *(PG8_G u32x4*)(ACT + (size_t)row * 5632 + ch0) = w4; }
	v_fma_f32 v61, v135, v59, v83
	v_fmac_f32_dpp v60, v58, v130 row_shr:1 row_mask:0xf bank_mask:0xf bound_ctrl:1
	v_fmac_f32_dpp v61, v59, v131 row_shr:1 row_mask:0xf bank_mask:0xf bound_ctrl:1
	s_nop 0
	v_fmac_f32_dpp v60, v58, v126 row_shr:2 row_mask:0xf bank_mask:0xf bound_ctrl:1
	v_fmac_f32_dpp v61, v59, v127 row_shr:2 row_mask:0xf bank_mask:0xf bound_ctrl:1
	s_nop 0
	v_fmac_f32_dpp v60, v62, v148 row_ror:1 row_mask:0xf bank_mask:0xf
	v_fmac_f32_dpp v61, v63, v143 row_ror:1 row_mask:0xf bank_mask:0xf
	s_nop 0
	v_fmac_f32_dpp v60, v62, v147 row_ror:2 row_mask:0xf bank_mask:0xf
	v_fmac_f32_dpp v61, v63, v141 row_ror:2 row_mask:0xf bank_mask:0xf
	v_fma_f32 v62, v116, v48, v100
	v_fma_f32 v63, v117, v49, v101
	v_fmac_f32_dpp v62, v48, v112 row_shr:1 row_mask:0xf bank_mask:0xf bound_ctrl:1
	v_fmac_f32_dpp v63, v49, v113 row_shr:1 row_mask:0xf bank_mask:0xf bound_ctrl:1
	s_nop 0
	v_fmac_f32_dpp v62, v48, v108 row_shr:2 row_mask:0xf bank_mask:0xf bound_ctrl:1
	v_fmac_f32_dpp v63, v49, v109 row_shr:2 row_mask:0xf bank_mask:0xf bound_ctrl:1
	s_nop 0
	v_fmac_f32_dpp v62, v52, v146 row_ror:1 row_mask:0xf bank_mask:0xf
	v_fmac_f32_dpp v63, v53, v142 row_ror:1 row_mask:0xf bank_mask:0xf
	s_nop 0
	v_fmac_f32_dpp v62, v52, v145 row_ror:2 row_mask:0xf bank_mask:0xf
	v_fmac_f32_dpp v63, v53, v140 row_ror:2 row_mask:0xf bank_mask:0xf
	v_fma_f32 v52, v118, v50, v102
	v_fma_f32 v53, v119, v51, v103
	v_fmac_f32_dpp v52, v50, v114 row_shr:1 row_mask:0xf bank_mask:0xf bound_ctrl:1
	v_fmac_f32_dpp v53, v51, v115 row_shr:1 row_mask:0xf bank_mask:0xf bound_ctrl:1
	s_nop 0
	v_fmac_f32_dpp v52, v50, v110 row_shr:2 row_mask:0xf bank_mask:0xf bound_ctrl:1
	v_fmac_f32_dpp v53, v51, v111 row_shr:2 row_mask:0xf bank_mask:0xf bound_ctrl:1
	s_nop 0
	v_fmac_f32_dpp v52, v54, v139 row_ror:1 row_mask:0xf bank_mask:0xf
	v_fmac_f32_dpp v53, v55, v137 row_ror:1 row_mask:0xf bank_mask:0xf
	s_nop 0
	v_fmac_f32_dpp v52, v54, v138 row_ror:2 row_mask:0xf bank_mask:0xf
	v_fmac_f32_dpp v53, v55, v136 row_ror:2 row_mask:0xf bank_mask:0xf
	v_exp_f32_e64 v66, -v60
	v_exp_f32_e64 v67, -v61
	v_exp_f32_e64 v54, -v64
	v_exp_f32_e64 v55, -v65
	v_add_f32_e32 v66, 1.0, v66
	v_add_f32_e32 v67, 1.0, v67
	v_add_f32_e32 v54, 1.0, v54
	v_add_f32_e32 v55, 1.0, v55
	v_rcp_f32_e32 v66, v66
	v_rcp_f32_e32 v67, v67
	v_rcp_f32_e32 v54, v54
	v_rcp_f32_e32 v55, v55
	v_pk_mul_f32 v[52:53], v[60:61], v[52:53]
	v_pk_mul_f32 v[60:61], v[64:65], v[62:63]
	v_pk_mul_f32 v[52:53], v[66:67], v[52:53]
	v_pk_mul_f32 v[54:55], v[54:55], v[60:61]
	s_nop 0
	v_cvt_pk_bf16_f32 v98, v54, v55
	v_cvt_pk_bf16_f32 v99, v52, v53
	v_mad_i64_i32 v[52:53], s[12:13], v39, s47, v[24:25]
	v_lshl_add_u64 v[52:53], v[52:53], 0, v[26:27]
	global_store_dwordx4 v[52:53], v[96:99], off
	v_fma_f32 v52, v132, v76, v80
	v_fma_f32 v53, v133, v77, v81
	v_fma_f32 v54, v134, v78, v82
	v_fma_f32 v55, v135, v79, v83
	v_fmac_f32_dpp v52, v76, v128 row_shr:1 row_mask:0xf bank_mask:0xf bound_ctrl:1
	v_fmac_f32_dpp v53, v77, v129 row_shr:1 row_mask:0xf bank_mask:0xf bound_ctrl:1
	v_fmac_f32_dpp v54, v78, v130 row_shr:1 row_mask:0xf bank_mask:0xf bound_ctrl:1
	v_fmac_f32_dpp v55, v79, v131 row_shr:1 row_mask:0xf bank_mask:0xf bound_ctrl:1
	v_fmac_f32_dpp v52, v76, v124 row_shr:2 row_mask:0xf bank_mask:0xf bound_ctrl:1
	v_fmac_f32_dpp v53, v77, v125 row_shr:2 row_mask:0xf bank_mask:0xf bound_ctrl:1
	v_fmac_f32_dpp v54, v78, v126 row_shr:2 row_mask:0xf bank_mask:0xf bound_ctrl:1
	v_fmac_f32_dpp v55, v79, v127 row_shr:2 row_mask:0xf bank_mask:0xf bound_ctrl:1
	v_fmac_f32_dpp v52, v56, v152 row_ror:1 row_mask:0xf bank_mask:0xf
	v_fmac_f32_dpp v53, v57, v150 row_ror:1 row_mask:0xf bank_mask:0xf
	v_fmac_f32_dpp v54, v58, v148 row_ror:1 row_mask:0xf bank_mask:0xf
	v_fmac_f32_dpp v55, v59, v143 row_ror:1 row_mask:0xf bank_mask:0xf
	v_fmac_f32_dpp v52, v56, v151 row_ror:2 row_mask:0xf bank_mask:0xf
	v_fmac_f32_dpp v53, v57, v149 row_ror:2 row_mask:0xf bank_mask:0xf
	v_fmac_f32_dpp v54, v58, v147 row_ror:2 row_mask:0xf bank_mask:0xf
	v_fmac_f32_dpp v55, v59, v141 row_ror:2 row_mask:0xf bank_mask:0xf
	v_fma_f32 v56, v116, v68, v100
	v_fma_f32 v57, v117, v69, v101
	v_fmac_f32_dpp v56, v68, v112 row_shr:1 row_mask:0xf bank_mask:0xf bound_ctrl:1
	v_fmac_f32_dpp v57, v69, v113 row_shr:1 row_mask:0xf bank_mask:0xf bound_ctrl:1
	s_nop 0
	v_fmac_f32_dpp v56, v68, v108 row_shr:2 row_mask:0xf bank_mask:0xf bound_ctrl:1
	v_fmac_f32_dpp v57, v69, v109 row_shr:2 row_mask:0xf bank_mask:0xf bound_ctrl:1
	s_nop 0
	v_fmac_f32_dpp v56, v48, v146 row_ror:1 row_mask:0xf bank_mask:0xf
	v_fmac_f32_dpp v57, v49, v142 row_ror:1 row_mask:0xf bank_mask:0xf
	s_nop 0
	v_fmac_f32_dpp v56, v48, v145 row_ror:2 row_mask:0xf bank_mask:0xf
	v_fmac_f32_dpp v57, v49, v140 row_ror:2 row_mask:0xf bank_mask:0xf
	v_fma_f32 v48, v118, v70, v102
	v_fma_f32 v49, v119, v71, v103
	v_fmac_f32_dpp v48, v70, v114 row_shr:1 row_mask:0xf bank_mask:0xf bound_ctrl:1
	v_fmac_f32_dpp v49, v71, v115 row_shr:1 row_mask:0xf bank_mask:0xf bound_ctrl:1
	s_nop 0
	v_fmac_f32_dpp v48, v70, v110 row_shr:2 row_mask:0xf bank_mask:0xf bound_ctrl:1
	v_fmac_f32_dpp v49, v71, v111 row_shr:2 row_mask:0xf bank_mask:0xf bound_ctrl:1
	s_nop 0
	v_fmac_f32_dpp v48, v50, v139 row_ror:1 row_mask:0xf bank_mask:0xf
	v_fmac_f32_dpp v49, v51, v137 row_ror:1 row_mask:0xf bank_mask:0xf
	s_nop 0
	v_fmac_f32_dpp v48, v50, v138 row_ror:2 row_mask:0xf bank_mask:0xf
	v_fmac_f32_dpp v49, v51, v136 row_ror:2 row_mask:0xf bank_mask:0xf
	v_exp_f32_e64 v39, -v52
	v_exp_f32_e64 v51, -v53
	v_exp_f32_e64 v58, -v54
	v_exp_f32_e64 v59, -v55
	v_add_f32_e32 v39, 1.0, v39
	v_rcp_f32_e32 v50, v39
	v_add_f32_e32 v39, 1.0, v51
	v_add_f32_e32 v51, 1.0, v58
	v_rcp_f32_e32 v58, v51
	v_add_f32_e32 v51, 1.0, v59
	v_rcp_f32_e32 v59, v51
	v_rcp_f32_e32 v51, v39
	v_mad_i64_i32 v[38:39], s[12:13], v38, s47, v[24:25]
	v_pk_mul_f32 v[48:49], v[54:55], v[48:49]
	v_pk_mul_f32 v[52:53], v[52:53], v[56:57]
	v_lshl_add_u64 v[38:39], v[38:39], 0, v[26:27]
	v_pk_mul_f32 v[48:49], v[58:59], v[48:49]
	v_pk_mul_f32 v[50:51], v[50:51], v[52:53]
	s_nop 0
	v_cvt_pk_bf16_f32 v92, v50, v51
	v_cvt_pk_bf16_f32 v93, v48, v49
	global_store_dwordx4 v[38:39], v[90:93], off
	ds_read_b128 v[48:51], v144 offset:16
	ds_read_b128 v[52:55], v144 offset:272
	v_fma_f32 v38, v132, v44, v80
	v_fmac_f32_dpp v38, v44, v128 row_shr:1 row_mask:0xf bank_mask:0xf bound_ctrl:1
	v_fma_f32 v56, v134, v46, v82
	v_fmac_f32_dpp v38, v44, v124 row_shr:2 row_mask:0xf bank_mask:0xf bound_ctrl:1
	s_waitcnt lgkmcnt(0)
; #define PG8_LAS __attribute__((address_space(3)))
; __device__ __forceinline__ unsigned cvt_pk_bf16(float lo, float hi) { unsigned r; asm volatile("v_cvt_pk_bf16_f32 %0, %1, %2" : "=v"(r) : "v"(lo), "v"(hi)); return r; }
; #define PG8_G __attribute__((address_space(1)))
; #define PG8_FMAC_DPP(c_, x_, w_, ctrl_) asm("v_fmac_f32_dpp %0, %1, %2 " ctrl_ : "+v"(c_) : "v"(x_), "v"(w_))
;     PG8_NOPRE
;     __device__ __forceinline__ void operator()(const f32x4 (&acc_)[2][2][4][2], const Unit& u, int wr, int wc, int fr_, int fq_, int ui) const {
;     ...
;                         if (m == 0 && !(ai == 0 && wr == 0)) { const int slot = ai == 0 ? 0 : (wr == 0 ? 1 : 2); const PG8_LAS float* b = xh + (((slot * 4 + wc) * 2) * 4 + fq) * 16 + n * 4 + bj * 8;
;                             h2 = *(const PG8_LAS f32x4*)b; h1 = *(const PG8_LAS f32x4*)(b + 64); }
; #pragma unroll
;                         for (int k = 0; k < 4; ++k) { const float cur = acc[ai][bj][m][n][k];
;                             float cc = fmaf(Wq[bj][2][k], cur, Wq[bj][3][k]);
;                             PG8_FMAC_DPP(cc, cur, Wq[bj][1][k], "row_shr:1 row_mask:0xf bank_mask:0xf bound_ctrl:1");
;                             PG8_FMAC_DPP(cc, cur, Wq[bj][0][k], "row_shr:2 row_mask:0xf bank_mask:0xf bound_ctrl:1");
;                             if (m == 0) { const float z = fr == 0 ? h2[k] : h1[k]; cc = fmaf(W1m[bj][k], h1[k], cc); cc = fmaf(W0m[bj][k], z, cc); }
;                             else { const float p = acc[ai][bj][m > 0 ? m - 1 : 0][n][k]; PG8_FMAC_DPP(cc, p, W1m[bj][k], "row_ror:1 row_mask:0xf bank_mask:0xf"); PG8_FMAC_DPP(cc, p, W0m[bj][k], "row_ror:2 row_mask:0xf bank_mask:0xf"); }
;                             c[bj][k] = cc; }
;     ...
;                         for (int k = 0; k < 4; ++k) ex[k] = __builtin_amdgcn_exp2f(-c[0][k]);
;                         const f32x4 den = ex + 1.0f, gv = c[0] * c[1]; f32x4 rc;
; #pragma unroll
;                         for (int k = 0; k < 4; ++k) rc[k] = __builtin_amdgcn_rcpf(den[k]);
;                         const f32x4 a = gv * rc;
;                         u32x2 w; w.x = cvt_pk_bf16(a[0], a[1]); w.y = cvt_pk_bf16(a[2], a[3]);
;                         if (n == 0) wkeep[ai][m] = w;
;                         else { const u32x4 w4 = {wkeep[ai][m].x, wkeep[ai][m].y, w.x, w.y}; *(PG8_G u32x4*)(ACT + (size_t)row * 5632 + ch0) = w4; }
	v_cndmask_b32_e64 v39, v52, v48, s[10:11]
	v_fmac_f32_e32 v38, v152, v52
	v_fmac_f32_e32 v38, v151, v39
	v_fma_f32 v39, v133, v45, v81
	v_fmac_f32_dpp v39, v45, v129 row_shr:1 row_mask:0xf bank_mask:0xf bound_ctrl:1
	v_fmac_f32_dpp v56, v46, v130 row_shr:1 row_mask:0xf bank_mask:0xf bound_ctrl:1
	v_fma_f32 v57, v135, v47, v83
	v_fmac_f32_dpp v39, v45, v125 row_shr:2 row_mask:0xf bank_mask:0xf bound_ctrl:1
	v_cndmask_b32_e64 v48, v53, v49, s[10:11]
	v_fmac_f32_e32 v39, v150, v53
	v_fmac_f32_dpp v56, v46, v126 row_shr:2 row_mask:0xf bank_mask:0xf bound_ctrl:1
	v_fmac_f32_dpp v57, v47, v131 row_shr:1 row_mask:0xf bank_mask:0xf bound_ctrl:1
	v_fmac_f32_e32 v39, v149, v48
	v_cndmask_b32_e64 v48, v54, v50, s[10:11]
	v_fmac_f32_e32 v56, v148, v54
	v_fmac_f32_dpp v57, v47, v127 row_shr:2 row_mask:0xf bank_mask:0xf bound_ctrl:1
	v_fmac_f32_e32 v56, v147, v48
	v_cndmask_b32_e64 v48, v55, v51, s[10:11]
	v_fmac_f32_e32 v57, v143, v55
	v_fmac_f32_e32 v57, v141, v48
	ds_read_b128 v[48:51], v144 offset:48
	ds_read_b128 v[52:55], v144 offset:304
	v_fma_f32 v58, v116, v32, v100
	v_fmac_f32_dpp v58, v32, v112 row_shr:1 row_mask:0xf bank_mask:0xf bound_ctrl:1
	v_fma_f32 v59, v117, v33, v101
	v_fmac_f32_dpp v58, v32, v108 row_shr:2 row_mask:0xf bank_mask:0xf bound_ctrl:1
	v_fmac_f32_dpp v59, v33, v113 row_shr:1 row_mask:0xf bank_mask:0xf bound_ctrl:1
	s_waitcnt lgkmcnt(0)
	v_cndmask_b32_e64 v48, v52, v48, s[10:11]
	v_fmac_f32_e32 v58, v146, v52
	v_fmac_f32_dpp v59, v33, v109 row_shr:2 row_mask:0xf bank_mask:0xf bound_ctrl:1
	v_fmac_f32_e32 v58, v145, v48
	v_cndmask_b32_e64 v48, v53, v49, s[10:11]
	v_fmac_f32_e32 v59, v142, v53
	v_fmac_f32_e32 v59, v140, v48
	v_fma_f32 v48, v118, v34, v102
	v_fmac_f32_dpp v48, v34, v114 row_shr:1 row_mask:0xf bank_mask:0xf bound_ctrl:1
	v_cndmask_b32_e64 v49, v54, v50, s[10:11]
	v_fmac_f32_dpp v48, v34, v110 row_shr:2 row_mask:0xf bank_mask:0xf bound_ctrl:1
	v_cndmask_b32_e64 v50, v55, v51, s[10:11]
	v_fmac_f32_e32 v48, v139, v54
	v_fmac_f32_e32 v48, v138, v49
	v_fma_f32 v49, v119, v35, v103
	v_fmac_f32_dpp v49, v35, v115 row_shr:1 row_mask:0xf bank_mask:0xf bound_ctrl:1
	s_nop 0
	v_fmac_f32_dpp v49, v35, v111 row_shr:2 row_mask:0xf bank_mask:0xf bound_ctrl:1
	s_nop 0
	v_fmac_f32_e32 v49, v137, v55
	v_fmac_f32_e32 v49, v136, v50
	v_exp_f32_e64 v50, -v38
	v_exp_f32_e64 v51, -v39
	v_exp_f32_e64 v52, -v56
	v_exp_f32_e64 v53, -v57
	v_add_f32_e32 v50, 1.0, v50
	v_add_f32_e32 v51, 1.0, v51
	v_rcp_f32_e32 v50, v50
	v_rcp_f32_e32 v51, v51
	v_add_f32_e32 v52, 1.0, v52
	v_add_f32_e32 v53, 1.0, v53
	v_rcp_f32_e32 v52, v52
	v_rcp_f32_e32 v53, v53
	v_pk_mul_f32 v[38:39], v[38:39], v[58:59]
	v_pk_mul_f32 v[48:49], v[56:57], v[48:49]
	v_pk_mul_f32 v[38:39], v[50:51], v[38:39]
	v_pk_mul_f32 v[48:49], v[52:53], v[48:49]
	v_cvt_pk_bf16_f32 v90, v38, v39
	v_mad_i64_i32 v[38:39], s[10:11], v37, s47, v[24:25]
	v_lshl_add_u64 v[38:39], v[38:39], 0, v[26:27]
	v_cvt_pk_bf16_f32 v91, v48, v49
	global_store_dwordx4 v[38:39], v[88:91], off
	v_fma_f32 v38, v132, v40, v80
	v_fma_f32 v39, v133, v41, v81
	v_fmac_f32_dpp v38, v40, v128 row_shr:1 row_mask:0xf bank_mask:0xf bound_ctrl:1
	v_fmac_f32_dpp v39, v41, v129 row_shr:1 row_mask:0xf bank_mask:0xf bound_ctrl:1
	s_nop 0
	v_fmac_f32_dpp v38, v40, v124 row_shr:2 row_mask:0xf bank_mask:0xf bound_ctrl:1
	v_fmac_f32_dpp v39, v41, v125 row_shr:2 row_mask:0xf bank_mask:0xf bound_ctrl:1
	s_nop 0
	v_fmac_f32_dpp v38, v44, v152 row_ror:1 row_mask:0xf bank_mask:0xf
	v_fmac_f32_dpp v39, v45, v150 row_ror:1 row_mask:0xf bank_mask:0xf
	s_nop 0
	v_fmac_f32_dpp v38, v44, v151 row_ror:2 row_mask:0xf bank_mask:0xf
	v_fmac_f32_dpp v39, v45, v149 row_ror:2 row_mask:0xf bank_mask:0xf
	v_fma_f32 v44, v134, v42, v82
	v_fma_f32 v45, v135, v43, v83
	v_fmac_f32_dpp v44, v42, v130 row_shr:1 row_mask:0xf bank_mask:0xf bound_ctrl:1
	v_fmac_f32_dpp v45, v43, v131 row_shr:1 row_mask:0xf bank_mask:0xf bound_ctrl:1
	s_nop 0
	v_fmac_f32_dpp v44, v42, v126 row_shr:2 row_mask:0xf bank_mask:0xf bound_ctrl:1
	v_fmac_f32_dpp v45, v43, v127 row_shr:2 row_mask:0xf bank_mask:0xf bound_ctrl:1
	s_nop 0
	v_fmac_f32_dpp v44, v46, v148 row_ror:1 row_mask:0xf bank_mask:0xf
	v_fmac_f32_dpp v45, v47, v143 row_ror:1 row_mask:0xf bank_mask:0xf
	s_nop 0
	v_fmac_f32_dpp v44, v46, v147 row_ror:2 row_mask:0xf bank_mask:0xf
	v_fmac_f32_dpp v45, v47, v141 row_ror:2 row_mask:0xf bank_mask:0xf
	v_fma_f32 v46, v116, v28, v100
	v_fma_f32 v47, v117, v29, v101
	v_fmac_f32_dpp v46, v28, v112 row_shr:1 row_mask:0xf bank_mask:0xf bound_ctrl:1
	v_fmac_f32_dpp v47, v29, v113 row_shr:1 row_mask:0xf bank_mask:0xf bound_ctrl:1
	s_nop 0
	v_fmac_f32_dpp v46, v28, v108 row_shr:2 row_mask:0xf bank_mask:0xf bound_ctrl:1
	v_fmac_f32_dpp v47, v29, v109 row_shr:2 row_mask:0xf bank_mask:0xf bound_ctrl:1
	s_nop 0
	v_fmac_f32_dpp v46, v32, v146 row_ror:1 row_mask:0xf bank_mask:0xf
	v_fmac_f32_dpp v47, v33, v142 row_ror:1 row_mask:0xf bank_mask:0xf
	s_nop 0
	v_fmac_f32_dpp v46, v32, v145 row_ror:2 row_mask:0xf bank_mask:0xf
	v_fmac_f32_dpp v47, v33, v140 row_ror:2 row_mask:0xf bank_mask:0xf
	v_fma_f32 v32, v118, v14, v102
	v_fma_f32 v33, v119, v15, v103
	v_fmac_f32_dpp v32, v14, v114 row_shr:1 row_mask:0xf bank_mask:0xf bound_ctrl:1
	v_fmac_f32_dpp v33, v15, v115 row_shr:1 row_mask:0xf bank_mask:0xf bound_ctrl:1
	s_nop 0
	v_fmac_f32_dpp v32, v14, v110 row_shr:2 row_mask:0xf bank_mask:0xf bound_ctrl:1
	v_fmac_f32_dpp v33, v15, v111 row_shr:2 row_mask:0xf bank_mask:0xf bound_ctrl:1
	s_nop 0
	v_fmac_f32_dpp v32, v34, v139 row_ror:1 row_mask:0xf bank_mask:0xf
	v_fmac_f32_dpp v33, v35, v137 row_ror:1 row_mask:0xf bank_mask:0xf
	s_nop 0
	v_fmac_f32_dpp v32, v34, v138 row_ror:2 row_mask:0xf bank_mask:0xf
; #define PG8_LAS __attribute__((address_space(3)))
; #define PG8_G __attribute__((address_space(1)))
;     PG8_NOPRE
;     __device__ __forceinline__ void operator()(const f32x4 (&acc_)[2][2][4][2], const Unit& u, int wr, int wc, int fr_, int fq_, int ui) const {
;     ...
;             for (int ai = 0; ai < 2; ++ai)
; #pragma unroll
;                 for (int m = 0; m < 4; ++m) {
;                     f32x4 c[2];
; #pragma unroll
;                     for (int bj = 0; bj < 2; ++bj) {
;                         f32x4 h1 = {0.f, 0.f, 0.f, 0.f}, h2 = {0.f, 0.f, 0.f, 0.f};
;                         if (m == 0 && !(ai == 0 && wr == 0)) { const int slot = ai == 0 ? 0 : (wr == 0 ? 1 : 2); const PG8_LAS float* b = xh + (((slot * 4 + wc) * 2) * 4 + fq) * 16 + n * 4 + bj * 8;
;                             h2 = *(const PG8_LAS f32x4*)b; h1 = *(const PG8_LAS f32x4*)(b + 64); }
; #pragma unroll
;                         for (int k = 0; k < 4; ++k) { const float cur = acc[ai][bj][m][n][k];
;                             float cc = fmaf(Wq[bj][2][k], cur, Wq[bj][3][k]);
;                             PG8_FMAC_DPP(cc, cur, Wq[bj][1][k], "row_shr:1 row_mask:0xf bank_mask:0xf bound_ctrl:1");
;                             PG8_FMAC_DPP(cc, cur, Wq[bj][0][k], "row_shr:2 row_mask:0xf bank_mask:0xf bound_ctrl:1");
;                             if (m == 0) { const float z = fr == 0 ? h2[k] : h1[k]; cc = fmaf(W1m[bj][k], h1[k], cc); cc = fmaf(W0m[bj][k], z, cc); }
;                             else { const float p = acc[ai][bj][m > 0 ? m - 1 : 0][n][k]; PG8_FMAC_DPP(cc, p, W1m[bj][k], "row_ror:1 row_mask:0xf bank_mask:0xf"); PG8_FMAC_DPP(cc, p, W0m[bj][k], "row_ror:2 row_mask:0xf bank_mask:0xf"); }
;                             c[bj][k] = cc; }
;     ...
;                         for (int k = 0; k < 4; ++k) ex[k] = __builtin_amdgcn_exp2f(-c[0][k]);
;                         const f32x4 den = ex + 1.0f, gv = c[0] * c[1]; f32x4 rc;
; #pragma unroll
;                         for (int k = 0; k < 4; ++k) rc[k] = __builtin_amdgcn_rcpf(den[k]);
;                         const f32x4 a = gv * rc;
;                         u32x2 w; w.x = cvt_pk_bf16(a[0], a[1]); w.y = cvt_pk_bf16(a[2], a[3]);
;                         if (n == 0) wkeep[ai][m] = w;
;                         else { const u32x4 w4 = {wkeep[ai][m].x, wkeep[ai][m].y, w.x, w.y}; *(PG8_G u32x4*)(ACT + (size_t)row * 5632 + ch0) = w4; }
	v_fmac_f32_dpp v33, v35, v136 row_ror:2 row_mask:0xf bank_mask:0xf
	v_exp_f32_e64 v37, -v44
	v_exp_f32_e64 v49, -v45
	v_exp_f32_e64 v34, -v38
	v_exp_f32_e64 v35, -v39
	v_add_f32_e32 v37, 1.0, v37
	v_rcp_f32_e32 v48, v37
	v_add_f32_e32 v37, 1.0, v49
	v_add_f32_e32 v34, 1.0, v34
	v_add_f32_e32 v35, 1.0, v35
	v_rcp_f32_e32 v49, v37
	v_rcp_f32_e32 v34, v34
	v_rcp_f32_e32 v35, v35
	v_pk_mul_f32 v[32:33], v[44:45], v[32:33]
	v_pk_mul_f32 v[38:39], v[38:39], v[46:47]
	v_pk_mul_f32 v[32:33], v[48:49], v[32:33]
	v_pk_mul_f32 v[34:35], v[34:35], v[38:39]
	s_nop 0
	v_cvt_pk_bf16_f32 v88, v34, v35
	v_cvt_pk_bf16_f32 v89, v32, v33
	v_mad_i64_i32 v[32:33], s[10:11], v36, s47, v[24:25]
	v_lshl_add_u64 v[32:33], v[32:33], 0, v[26:27]
	global_store_dwordx4 v[32:33], v[86:89], off
	v_fma_f32 v32, v132, v10, v80
	v_fma_f32 v33, v133, v11, v81
	v_fma_f32 v34, v134, v8, v82
	v_fma_f32 v35, v135, v9, v83
	v_fmac_f32_dpp v32, v10, v128 row_shr:1 row_mask:0xf bank_mask:0xf bound_ctrl:1
	v_fmac_f32_dpp v33, v11, v129 row_shr:1 row_mask:0xf bank_mask:0xf bound_ctrl:1
	v_fmac_f32_dpp v34, v8, v130 row_shr:1 row_mask:0xf bank_mask:0xf bound_ctrl:1
	v_fmac_f32_dpp v35, v9, v131 row_shr:1 row_mask:0xf bank_mask:0xf bound_ctrl:1
	v_fmac_f32_dpp v32, v10, v124 row_shr:2 row_mask:0xf bank_mask:0xf bound_ctrl:1
	v_fmac_f32_dpp v33, v11, v125 row_shr:2 row_mask:0xf bank_mask:0xf bound_ctrl:1
	v_fmac_f32_dpp v34, v8, v126 row_shr:2 row_mask:0xf bank_mask:0xf bound_ctrl:1
	v_fmac_f32_dpp v35, v9, v127 row_shr:2 row_mask:0xf bank_mask:0xf bound_ctrl:1
	v_fmac_f32_dpp v32, v40, v152 row_ror:1 row_mask:0xf bank_mask:0xf
	v_fmac_f32_dpp v33, v41, v150 row_ror:1 row_mask:0xf bank_mask:0xf
	v_fmac_f32_dpp v34, v42, v148 row_ror:1 row_mask:0xf bank_mask:0xf
	v_fmac_f32_dpp v35, v43, v143 row_ror:1 row_mask:0xf bank_mask:0xf
	v_fmac_f32_dpp v32, v40, v151 row_ror:2 row_mask:0xf bank_mask:0xf
	v_fmac_f32_dpp v33, v41, v149 row_ror:2 row_mask:0xf bank_mask:0xf
	v_fmac_f32_dpp v34, v42, v147 row_ror:2 row_mask:0xf bank_mask:0xf
	v_fmac_f32_dpp v35, v43, v141 row_ror:2 row_mask:0xf bank_mask:0xf
	v_fma_f32 v36, v116, v6, v100
	v_fma_f32 v37, v117, v7, v101
	v_fmac_f32_dpp v36, v6, v112 row_shr:1 row_mask:0xf bank_mask:0xf bound_ctrl:1
	v_fmac_f32_dpp v37, v7, v113 row_shr:1 row_mask:0xf bank_mask:0xf bound_ctrl:1
	s_nop 0
	v_fmac_f32_dpp v36, v6, v108 row_shr:2 row_mask:0xf bank_mask:0xf bound_ctrl:1
	v_fmac_f32_dpp v37, v7, v109 row_shr:2 row_mask:0xf bank_mask:0xf bound_ctrl:1
	s_nop 0
	v_fmac_f32_dpp v36, v28, v146 row_ror:1 row_mask:0xf bank_mask:0xf
	v_fmac_f32_dpp v37, v29, v142 row_ror:1 row_mask:0xf bank_mask:0xf
	s_nop 0
	v_fmac_f32_dpp v36, v28, v145 row_ror:2 row_mask:0xf bank_mask:0xf
	v_fmac_f32_dpp v37, v29, v140 row_ror:2 row_mask:0xf bank_mask:0xf
	v_fma_f32 v28, v118, v4, v102
	v_fma_f32 v29, v119, v5, v103
	v_fmac_f32_dpp v28, v4, v114 row_shr:1 row_mask:0xf bank_mask:0xf bound_ctrl:1
	v_fmac_f32_dpp v29, v5, v115 row_shr:1 row_mask:0xf bank_mask:0xf bound_ctrl:1
	s_nop 0
	v_fmac_f32_dpp v28, v4, v110 row_shr:2 row_mask:0xf bank_mask:0xf bound_ctrl:1
	v_fmac_f32_dpp v29, v5, v111 row_shr:2 row_mask:0xf bank_mask:0xf bound_ctrl:1
	s_nop 0
	v_fmac_f32_dpp v28, v14, v139 row_ror:1 row_mask:0xf bank_mask:0xf
	v_fmac_f32_dpp v29, v15, v137 row_ror:1 row_mask:0xf bank_mask:0xf
	s_nop 0
	v_fmac_f32_dpp v28, v14, v138 row_ror:2 row_mask:0xf bank_mask:0xf
	v_fmac_f32_dpp v29, v15, v136 row_ror:2 row_mask:0xf bank_mask:0xf
	v_exp_f32_e64 v14, -v32
	v_exp_f32_e64 v15, -v33
	v_exp_f32_e64 v38, -v34
	v_exp_f32_e64 v39, -v35
	v_add_f32_e32 v14, 1.0, v14
	v_add_f32_e32 v15, 1.0, v15
	v_rcp_f32_e32 v14, v14
	v_rcp_f32_e32 v15, v15
	v_add_f32_e32 v38, 1.0, v38
	v_add_f32_e32 v39, 1.0, v39
	v_rcp_f32_e32 v38, v38
	v_rcp_f32_e32 v39, v39
	v_pk_mul_f32 v[32:33], v[32:33], v[36:37]
;     PG8_NOPRE
;     __device__ __forceinline__ void operator()(const f32x4 (&acc_)[2][2][4][2], const Unit& u, int wr, int wc, int fr_, int fq_, int ui) const {
;     ...
;             for (int ai = 0; ai < 2; ++ai)
; #pragma unroll
;                 for (int m = 0; m < 4; ++m) {
;                     f32x4 c[2];
; #pragma unroll
;                     for (int bj = 0; bj < 2; ++bj) {
;                         f32x4 h1 = {0.f, 0.f, 0.f, 0.f}, h2 = {0.f, 0.f, 0.f, 0.f};
;                         if (m == 0 && !(ai == 0 && wr == 0)) { const int slot = ai == 0 ? 0 : (wr == 0 ? 1 : 2); const PG8_LAS float* b = xh + (((slot * 4 + wc) * 2) * 4 + fq) * 16 + n * 4 + bj * 8;
;                             h2 = *(const PG8_LAS f32x4*)b; h1 = *(const PG8_LAS f32x4*)(b + 64); }
; #pragma unroll
;                         for (int k = 0; k < 4; ++k) { const float cur = acc[ai][bj][m][n][k];
;                             float cc = fmaf(Wq[bj][2][k], cur, Wq[bj][3][k]);
;                             PG8_FMAC_DPP(cc, cur, Wq[bj][1][k], "row_shr:1 row_mask:0xf bank_mask:0xf bound_ctrl:1");
;                             PG8_FMAC_DPP(cc, cur, Wq[bj][0][k], "row_shr:2 row_mask:0xf bank_mask:0xf bound_ctrl:1");
;                             if (m == 0) { const float z = fr == 0 ? h2[k] : h1[k]; cc = fmaf(W1m[bj][k], h1[k], cc); cc = fmaf(W0m[bj][k], z, cc); }
;                             else { const float p = acc[ai][bj][m > 0 ? m - 1 : 0][n][k]; PG8_FMAC_DPP(cc, p, W1m[bj][k], "row_ror:1 row_mask:0xf bank_mask:0xf"); PG8_FMAC_DPP(cc, p, W0m[bj][k], "row_ror:2 row_mask:0xf bank_mask:0xf"); }
;                             c[bj][k] = cc; }
;                         __builtin_amdgcn_sched_barrier(0);
;                     }
;                     const int row = u.pm * BM + ai * HALF + wr * 64 + m * 16 + fr;
;                     if (ai == 0 && m == 0 && wr == 0 && fixtile && fr < 2) {
;                         float* fp = FIX + ((size_t)u.pm * 2 + fr) * 11264 + ch0 + n * 4;
;                         *(PG8_G f32x4*)fp = c[0] * 0.6931471805599453f; *(PG8_G f32x4*)(fp + 5632) = c[1] * 1.4426950408889634f;
;                     } else {
;                         f32x4 ex;
; #pragma unroll
;                         for (int k = 0; k < 4; ++k) ex[k] = __builtin_amdgcn_exp2f(-c[0][k]);
;                         const f32x4 den = ex + 1.0f, gv = c[0] * c[1]; f32x4 rc;
; #pragma unroll
	v_pk_mul_f32 v[28:29], v[34:35], v[28:29]
	v_pk_mul_f32 v[14:15], v[14:15], v[32:33]
	v_pk_mul_f32 v[28:29], v[38:39], v[28:29]
	v_cvt_pk_bf16_f32 v86, v14, v15
	v_mad_i64_i32 v[14:15], s[10:11], v31, s47, v[24:25]
	v_lshl_add_u64 v[14:15], v[14:15], 0, v[26:27]
	v_cvt_pk_bf16_f32 v87, v28, v29
	global_store_dwordx4 v[14:15], v[84:87], off
	v_fma_f32 v14, v132, v20, v80
	v_fma_f32 v15, v133, v21, v81
	v_fma_f32 v82, v134, v22, v82
	v_fmac_f32_e32 v83, v135, v23
	v_fmac_f32_dpp v14, v20, v128 row_shr:1 row_mask:0xf bank_mask:0xf bound_ctrl:1
	v_fmac_f32_dpp v15, v21, v129 row_shr:1 row_mask:0xf bank_mask:0xf bound_ctrl:1
	v_fmac_f32_dpp v82, v22, v130 row_shr:1 row_mask:0xf bank_mask:0xf bound_ctrl:1
	v_fmac_f32_dpp v83, v23, v131 row_shr:1 row_mask:0xf bank_mask:0xf bound_ctrl:1
	v_fmac_f32_dpp v14, v20, v124 row_shr:2 row_mask:0xf bank_mask:0xf bound_ctrl:1
	v_fmac_f32_dpp v15, v21, v125 row_shr:2 row_mask:0xf bank_mask:0xf bound_ctrl:1
	v_fmac_f32_dpp v82, v22, v126 row_shr:2 row_mask:0xf bank_mask:0xf bound_ctrl:1
	v_fmac_f32_dpp v83, v23, v127 row_shr:2 row_mask:0xf bank_mask:0xf bound_ctrl:1
	v_fmac_f32_dpp v14, v10, v152 row_ror:1 row_mask:0xf bank_mask:0xf
	v_fmac_f32_dpp v15, v11, v150 row_ror:1 row_mask:0xf bank_mask:0xf
	v_fmac_f32_dpp v82, v8, v148 row_ror:1 row_mask:0xf bank_mask:0xf
	v_fmac_f32_dpp v83, v9, v143 row_ror:1 row_mask:0xf bank_mask:0xf
	v_fmac_f32_dpp v14, v10, v151 row_ror:2 row_mask:0xf bank_mask:0xf
	v_fmac_f32_dpp v15, v11, v149 row_ror:2 row_mask:0xf bank_mask:0xf
	v_fmac_f32_dpp v82, v8, v147 row_ror:2 row_mask:0xf bank_mask:0xf
	v_fmac_f32_dpp v83, v9, v141 row_ror:2 row_mask:0xf bank_mask:0xf
	v_fma_f32 v8, v116, v16, v100
	v_fma_f32 v9, v117, v17, v101
	v_fma_f32 v102, v118, v18, v102
	v_fmac_f32_e32 v103, v119, v19
	v_fmac_f32_dpp v8, v16, v112 row_shr:1 row_mask:0xf bank_mask:0xf bound_ctrl:1
	v_fmac_f32_dpp v9, v17, v113 row_shr:1 row_mask:0xf bank_mask:0xf bound_ctrl:1
	v_fmac_f32_dpp v102, v18, v114 row_shr:1 row_mask:0xf bank_mask:0xf bound_ctrl:1
	v_fmac_f32_dpp v103, v19, v115 row_shr:1 row_mask:0xf bank_mask:0xf bound_ctrl:1
	v_fmac_f32_dpp v8, v16, v108 row_shr:2 row_mask:0xf bank_mask:0xf bound_ctrl:1
	v_fmac_f32_dpp v9, v17, v109 row_shr:2 row_mask:0xf bank_mask:0xf bound_ctrl:1
	v_fmac_f32_dpp v102, v18, v110 row_shr:2 row_mask:0xf bank_mask:0xf bound_ctrl:1
	v_fmac_f32_dpp v103, v19, v111 row_shr:2 row_mask:0xf bank_mask:0xf bound_ctrl:1
	v_fmac_f32_dpp v8, v6, v146 row_ror:1 row_mask:0xf bank_mask:0xf
	v_fmac_f32_dpp v9, v7, v142 row_ror:1 row_mask:0xf bank_mask:0xf
	v_fmac_f32_dpp v102, v4, v139 row_ror:1 row_mask:0xf bank_mask:0xf
	v_fmac_f32_dpp v103, v5, v137 row_ror:1 row_mask:0xf bank_mask:0xf
	v_fmac_f32_dpp v8, v6, v145 row_ror:2 row_mask:0xf bank_mask:0xf
	v_fmac_f32_dpp v9, v7, v140 row_ror:2 row_mask:0xf bank_mask:0xf
	v_fmac_f32_dpp v102, v4, v138 row_ror:2 row_mask:0xf bank_mask:0xf
	v_fmac_f32_dpp v103, v5, v136 row_ror:2 row_mask:0xf bank_mask:0xf
	v_exp_f32_e64 v4, -v14
	v_exp_f32_e64 v5, -v15
	v_exp_f32_e64 v6, -v82
	v_exp_f32_e64 v7, -v83
	v_add_f32_e32 v4, 1.0, v4
	v_add_f32_e32 v5, 1.0, v5
	v_rcp_f32_e32 v4, v4
	v_rcp_f32_e32 v5, v5
	v_add_f32_e32 v6, 1.0, v6
	v_add_f32_e32 v7, 1.0, v7
	v_rcp_f32_e32 v6, v6
	v_rcp_f32_e32 v7, v7
	v_pk_mul_f32 v[8:9], v[14:15], v[8:9]
	v_pk_mul_f32 v[10:11], v[82:83], v[102:103]
	v_pk_mul_f32 v[4:5], v[4:5], v[8:9]
	v_pk_mul_f32 v[6:7], v[6:7], v[10:11]
	v_cvt_pk_bf16_f32 v14, v4, v5
	v_mad_i64_i32 v[4:5], s[10:11], v30, s47, v[24:25]
	v_lshl_add_u64 v[4:5], v[4:5], 0, v[26:27]
	v_cvt_pk_bf16_f32 v15, v6, v7
	global_store_dwordx4 v[4:5], v[12:15], off
	s_andn2_b64 vcc, exec, s[8:9]
	s_mov_b64 s[8:9], -1
	s_cbranch_vccnz .LBB0_538
	s_andn2_b64 vcc, exec, s[60:61]
	s_cbranch_vccnz .LBB0_537
	s_barrier
	s_branch .LBB0_537

; #define PG8_LAS __attribute__((address_space(3)))
; #define PG8_FMAC_DPP(c_, x_, w_, ctrl_) asm("v_fmac_f32_dpp %0, %1, %2 " ctrl_ : "+v"(c_) : "v"(x_), "v"(w_))
;     PG8_NOPRE
;     __device__ __forceinline__ void operator()(const f32x4 (&acc_)[2][2][4][2], const Unit& u, int wr, int wc, int fr_, int fq_, int ui) const {
;     ...
;         const bool fixtile = (u.pm & 15) != 0;
;     ...
;         u32x2 wkeep[2][4];
; #pragma unroll
;         for (int n = 0; n < 2; ++n) {
;             const PG8_LAS float* cwb = cwc + wc * 32 + fq * 8 + n * 4;
;             f32x4 Wq[2][4], W1m[2], W0m[2];
; #pragma unroll
;             for (int bj = 0; bj < 2; ++bj) {
; #pragma unroll
;                 for (int t = 0; t < 4; ++t) Wq[bj][t] = *(const PG8_LAS f32x4*)(cwb + t * 256 + bj * 128);
; #pragma unroll
;                 for (int k = 0; k < 4; ++k) { W1m[bj][k] = fr == 0 ? Wq[bj][1][k] : 0.f; W0m[bj][k] = fr < 2 ? Wq[bj][0][k] : 0.f; } }
; #pragma unroll
;             for (int ai = 0; ai < 2; ++ai)
; #pragma unroll
;                 for (int m = 0; m < 4; ++m) {
;                     f32x4 c[2];
; #pragma unroll
;                     for (int bj = 0; bj < 2; ++bj) {
;                         f32x4 h1 = {0.f, 0.f, 0.f, 0.f}, h2 = {0.f, 0.f, 0.f, 0.f};
;                         if (m == 0 && !(ai == 0 && wr == 0)) { const int slot = ai == 0 ? 0 : (wr == 0 ? 1 : 2); const PG8_LAS float* b = xh + (((slot * 4 + wc) * 2) * 4 + fq) * 16 + n * 4 + bj * 8;
;                             h2 = *(const PG8_LAS f32x4*)b; h1 = *(const PG8_LAS f32x4*)(b + 64); }
; #pragma unroll
;                         for (int k = 0; k < 4; ++k) { const float cur = acc[ai][bj][m][n][k];
;                             float cc = fmaf(Wq[bj][2][k], cur, Wq[bj][3][k]);
;                             PG8_FMAC_DPP(cc, cur, Wq[bj][1][k], "row_shr:1 row_mask:0xf bank_mask:0xf bound_ctrl:1");
;                             PG8_FMAC_DPP(cc, cur, Wq[bj][0][k], "row_shr:2 row_mask:0xf bank_mask:0xf bound_ctrl:1");
;                             if (m == 0) { const float z = fr == 0 ? h2[k] : h1[k]; cc = fmaf(W1m[bj][k], h1[k], cc); cc = fmaf(W0m[bj][k], z, cc); }
.LBB0_1100:
	s_and_b32 s8, s24, 15
	v_pk_mul_f32 v[96:97], v[6:7], v[216:217] op_sel_hi:[1,0]
	v_pk_mul_f32 v[218:219], v[4:5], v[216:217] op_sel_hi:[1,0]
	s_cmp_lg_u32 s8, 0
	s_waitcnt lgkmcnt(0)
	v_fma_f32 v4, v134, v218, v98
	v_fma_f32 v5, v135, v219, v99
	v_fma_f32 v6, v136, v96, v100
	v_fma_f32 v7, v137, v97, v101
	s_cselect_b64 s[68:69], -1, 0
	v_fmac_f32_dpp v4, v218, v130 row_shr:1 row_mask:0xf bank_mask:0xf bound_ctrl:1
	v_fmac_f32_dpp v5, v219, v131 row_shr:1 row_mask:0xf bank_mask:0xf bound_ctrl:1
	v_fmac_f32_dpp v6, v96, v132 row_shr:1 row_mask:0xf bank_mask:0xf bound_ctrl:1
	v_fmac_f32_dpp v7, v97, v133 row_shr:1 row_mask:0xf bank_mask:0xf bound_ctrl:1
	v_fmac_f32_dpp v4, v218, v126 row_shr:2 row_mask:0xf bank_mask:0xf bound_ctrl:1
	v_fmac_f32_dpp v5, v219, v127 row_shr:2 row_mask:0xf bank_mask:0xf bound_ctrl:1
	v_fmac_f32_dpp v6, v96, v128 row_shr:2 row_mask:0xf bank_mask:0xf bound_ctrl:1
	v_fmac_f32_dpp v7, v97, v129 row_shr:2 row_mask:0xf bank_mask:0xf bound_ctrl:1
	v_cndmask_b32_e64 v119, 0, 1, s[62:63]
	v_cmp_ne_u32_e64 s[12:13], 1, v119
	s_andn2_b64 vcc, exec, s[62:63]
	s_cbranch_vccnz .LBB0_1102
	ds_read_b128 v[178:181], v197 offset:32
	ds_read_b128 v[118:121], v197 offset:288
	s_mov_b64 s[68:69], 0
	s_branch .LBB0_1103

;     PG8_NOPRE
;     __device__ __forceinline__ void operator()(const f32x4 (&acc_)[2][2][4][2], const Unit& u, int wr, int wc, int fr_, int fq_, int ui) const {
;     ...
;                     for (int bj = 0; bj < 2; ++bj) {
;                         f32x4 h1 = {0.f, 0.f, 0.f, 0.f}, h2 = {0.f, 0.f, 0.f, 0.f};
;                         if (m == 0 && !(ai == 0 && wr == 0)) { const int slot = ai == 0 ? 0 : (wr == 0 ? 1 : 2); const PG8_LAS float* b = xh + (((slot * 4 + wc) * 2) * 4 + fq) * 16 + n * 4 + bj * 8;
;                             h2 = *(const PG8_LAS f32x4*)b; h1 = *(const PG8_LAS f32x4*)(b + 64); }
; #pragma unroll
;                         for (int k = 0; k < 4; ++k) { const float cur = acc[ai][bj][m][n][k];
;                             float cc = fmaf(Wq[bj][2][k], cur, Wq[bj][3][k]);
;                             PG8_FMAC_DPP(cc, cur, Wq[bj][1][k], "row_shr:1 row_mask:0xf bank_mask:0xf bound_ctrl:1");
;                             PG8_FMAC_DPP(cc, cur, Wq[bj][0][k], "row_shr:2 row_mask:0xf bank_mask:0xf bound_ctrl:1");
;                             if (m == 0) { const float z = fr == 0 ? h2[k] : h1[k]; cc = fmaf(W1m[bj][k], h1[k], cc); cc = fmaf(W0m[bj][k], z, cc); }
;                             else { const float p = acc[ai][bj][m > 0 ? m - 1 : 0][n][k]; PG8_FMAC_DPP(cc, p, W1m[bj][k], "row_ror:1 row_mask:0xf bank_mask:0xf"); PG8_FMAC_DPP(cc, p, W0m[bj][k], "row_ror:2 row_mask:0xf bank_mask:0xf"); }
;                             c[bj][k] = cc; }
;                         __builtin_amdgcn_sched_barrier(0);
;                     }
;                     const int row = u.pm * BM + ai * HALF + wr * 64 + m * 16 + fr;
;                     if (ai == 0 && m == 0 && wr == 0 && fixtile && fr < 2) {
;                         float* fp = FIX + ((size_t)u.pm * 2 + fr) * 11264 + ch0 + n * 4;
;                         *(PG8_G f32x4*)fp = c[0] * 0.6931471805599453f; *(PG8_G f32x4*)(fp + 5632) = c[1] * 1.4426950408889634f;
;                     } else {
;                         f32x4 ex;
; #pragma unroll
;                         for (int k = 0; k < 4; ++k) ex[k] = __builtin_amdgcn_exp2f(-c[0][k]);
;                         const f32x4 den = ex + 1.0f, gv = c[0] * c[1]; f32x4 rc;
; #pragma unroll
;                         for (int k = 0; k < 4; ++k) rc[k] = __builtin_amdgcn_rcpf(den[k]);
;                         const f32x4 a = gv * rc;
.LBB0_1107:
	s_or_b64 exec, exec, s[82:83]
	s_nop 0
	v_mov_b32_e32 v4, v199
	v_pk_mul_f32 v[118:119], v[144:145], v[4:5] op_sel_hi:[1,0]
	v_pk_mul_f32 v[8:9], v[140:141], v[196:197] op_sel_hi:[1,0]
	v_pk_mul_f32 v[12:13], v[138:139], v[196:197] op_sel_hi:[1,0]
	v_pk_mul_f32 v[138:139], v[104:105], v[198:199] op_sel_hi:[1,0]
	v_pk_mul_f32 v[140:141], v[102:103], v[198:199] op_sel_hi:[1,0]
	v_pk_mul_f32 v[102:103], v[88:89], v[4:5] op_sel_hi:[1,0]
	v_pk_mul_f32 v[6:7], v[84:85], v[196:197] op_sel_hi:[1,0]
	v_pk_mul_f32 v[164:165], v[164:165], v[212:213] op_sel_hi:[1,0]
	v_pk_mul_f32 v[162:163], v[162:163], v[212:213] op_sel_hi:[1,0]
	v_pk_mul_f32 v[160:161], v[160:161], v[210:211] op_sel_hi:[1,0]
	v_pk_mul_f32 v[158:159], v[158:159], v[210:211] op_sel_hi:[1,0]
	v_pk_mul_f32 v[156:157], v[156:157], v[212:213] op_sel_hi:[1,0]
	v_pk_mul_f32 v[154:155], v[154:155], v[212:213] op_sel_hi:[1,0]
	v_pk_mul_f32 v[152:153], v[152:153], v[210:211] op_sel_hi:[1,0]
	v_pk_mul_f32 v[150:151], v[150:151], v[210:211] op_sel_hi:[1,0]
	v_pk_mul_f32 v[148:149], v[148:149], v[198:199] op_sel_hi:[1,0]
	v_pk_mul_f32 v[146:147], v[146:147], v[198:199] op_sel_hi:[1,0]
	v_pk_mul_f32 v[142:143], v[142:143], v[4:5] op_sel_hi:[1,0]
	v_pk_mul_f32 v[14:15], v[90:91], v[4:5] op_sel_hi:[1,0]
	v_pk_mul_f32 v[4:5], v[86:87], v[196:197] op_sel_hi:[1,0]
	v_fma_f32 v84, v134, v162, v98
	v_fma_f32 v85, v135, v163, v99
	v_fma_f32 v86, v136, v164, v100
	v_fma_f32 v87, v137, v165, v101
	v_fmac_f32_dpp v84, v162, v130 row_shr:1 row_mask:0xf bank_mask:0xf bound_ctrl:1
	v_fmac_f32_dpp v85, v163, v131 row_shr:1 row_mask:0xf bank_mask:0xf bound_ctrl:1
	v_fmac_f32_dpp v86, v164, v132 row_shr:1 row_mask:0xf bank_mask:0xf bound_ctrl:1
	v_fmac_f32_dpp v87, v165, v133 row_shr:1 row_mask:0xf bank_mask:0xf bound_ctrl:1
	v_fmac_f32_dpp v84, v162, v126 row_shr:2 row_mask:0xf bank_mask:0xf bound_ctrl:1
	v_fmac_f32_dpp v85, v163, v127 row_shr:2 row_mask:0xf bank_mask:0xf bound_ctrl:1
	v_fmac_f32_dpp v86, v164, v128 row_shr:2 row_mask:0xf bank_mask:0xf bound_ctrl:1
	v_fmac_f32_dpp v87, v165, v129 row_shr:2 row_mask:0xf bank_mask:0xf bound_ctrl:1
	v_fmac_f32_dpp v84, v218, v242 row_ror:1 row_mask:0xf bank_mask:0xf
	v_fmac_f32_dpp v85, v219, v240 row_ror:1 row_mask:0xf bank_mask:0xf
	v_fmac_f32_dpp v86, v96, v238 row_ror:1 row_mask:0xf bank_mask:0xf
	v_fmac_f32_dpp v87, v97, v234 row_ror:1 row_mask:0xf bank_mask:0xf
	v_fmac_f32_dpp v84, v218, v241 row_ror:2 row_mask:0xf bank_mask:0xf
	v_fmac_f32_dpp v85, v219, v239 row_ror:2 row_mask:0xf bank_mask:0xf
	v_fmac_f32_dpp v86, v96, v237 row_ror:2 row_mask:0xf bank_mask:0xf
	v_fmac_f32_dpp v87, v97, v233 row_ror:2 row_mask:0xf bank_mask:0xf
	v_fma_f32 v88, v122, v154, v106
	v_fma_f32 v89, v123, v155, v107
	v_fma_f32 v90, v124, v156, v108
	v_fma_f32 v91, v125, v157, v109
	v_fmac_f32_dpp v88, v154, v114 row_shr:1 row_mask:0xf bank_mask:0xf bound_ctrl:1
	v_fmac_f32_dpp v89, v155, v115 row_shr:1 row_mask:0xf bank_mask:0xf bound_ctrl:1
	v_fmac_f32_dpp v90, v156, v116 row_shr:1 row_mask:0xf bank_mask:0xf bound_ctrl:1
	v_fmac_f32_dpp v91, v157, v117 row_shr:1 row_mask:0xf bank_mask:0xf bound_ctrl:1
	v_fmac_f32_dpp v88, v154, v110 row_shr:2 row_mask:0xf bank_mask:0xf bound_ctrl:1
	v_fmac_f32_dpp v89, v155, v111 row_shr:2 row_mask:0xf bank_mask:0xf bound_ctrl:1
	v_fmac_f32_dpp v90, v156, v112 row_shr:2 row_mask:0xf bank_mask:0xf bound_ctrl:1
	v_fmac_f32_dpp v91, v157, v113 row_shr:2 row_mask:0xf bank_mask:0xf bound_ctrl:1
	v_fmac_f32_dpp v88, v176, v236 row_ror:1 row_mask:0xf bank_mask:0xf
	v_fmac_f32_dpp v89, v177, v232 row_ror:1 row_mask:0xf bank_mask:0xf
	v_fmac_f32_dpp v90, v174, v224 row_ror:1 row_mask:0xf bank_mask:0xf
	v_fmac_f32_dpp v91, v175, v213 row_ror:1 row_mask:0xf bank_mask:0xf
	v_fmac_f32_dpp v88, v176, v235 row_ror:2 row_mask:0xf bank_mask:0xf
	v_fmac_f32_dpp v89, v177, v225 row_ror:2 row_mask:0xf bank_mask:0xf
	v_fmac_f32_dpp v90, v174, v223 row_ror:2 row_mask:0xf bank_mask:0xf
	v_fmac_f32_dpp v91, v175, v211 row_ror:2 row_mask:0xf bank_mask:0xf
	v_exp_f32_e64 v96, -v84
	v_exp_f32_e64 v97, -v85
	v_exp_f32_e64 v104, -v86
	v_exp_f32_e64 v105, -v87
	v_add_f32_e32 v96, 1.0, v96
	v_add_f32_e32 v97, 1.0, v97
	v_add_f32_e32 v104, 1.0, v104
	v_add_f32_e32 v105, 1.0, v105
	v_rcp_f32_e32 v96, v96
	v_rcp_f32_e32 v104, v104
	v_rcp_f32_e32 v105, v105
	v_rcp_f32_e32 v97, v97
	v_pk_mul_f32 v[86:87], v[86:87], v[90:91]
	v_pk_mul_f32 v[84:85], v[84:85], v[88:89]
	v_pk_mul_f32 v[86:87], v[104:105], v[86:87]
	v_pk_mul_f32 v[84:85], v[96:97], v[84:85]
	s_nop 0
	v_cvt_pk_bf16_f32 v104, v84, v85
	v_cvt_pk_bf16_f32 v105, v86, v87
	v_fma_f32 v84, v134, v158, v98
	v_fma_f32 v85, v135, v159, v99
	v_fma_f32 v86, v136, v160, v100
	v_fma_f32 v87, v137, v161, v101
	v_fmac_f32_dpp v84, v158, v130 row_shr:1 row_mask:0xf bank_mask:0xf bound_ctrl:1
	v_fmac_f32_dpp v85, v159, v131 row_shr:1 row_mask:0xf bank_mask:0xf bound_ctrl:1
	v_fmac_f32_dpp v86, v160, v132 row_shr:1 row_mask:0xf bank_mask:0xf bound_ctrl:1
	v_fmac_f32_dpp v87, v161, v133 row_shr:1 row_mask:0xf bank_mask:0xf bound_ctrl:1
	v_fmac_f32_dpp v84, v158, v126 row_shr:2 row_mask:0xf bank_mask:0xf bound_ctrl:1
	v_fmac_f32_dpp v85, v159, v127 row_shr:2 row_mask:0xf bank_mask:0xf bound_ctrl:1
	v_fmac_f32_dpp v86, v160, v128 row_shr:2 row_mask:0xf bank_mask:0xf bound_ctrl:1
	v_fmac_f32_dpp v87, v161, v129 row_shr:2 row_mask:0xf bank_mask:0xf bound_ctrl:1
	v_fmac_f32_dpp v84, v162, v242 row_ror:1 row_mask:0xf bank_mask:0xf
	v_fmac_f32_dpp v85, v163, v240 row_ror:1 row_mask:0xf bank_mask:0xf
	v_fmac_f32_dpp v86, v164, v238 row_ror:1 row_mask:0xf bank_mask:0xf
	v_fmac_f32_dpp v87, v165, v234 row_ror:1 row_mask:0xf bank_mask:0xf
;     PG8_NOPRE
;     __device__ __forceinline__ void operator()(const f32x4 (&acc_)[2][2][4][2], const Unit& u, int wr, int wc, int fr_, int fq_, int ui) const {
;     ...
;                     for (int bj = 0; bj < 2; ++bj) {
;                         f32x4 h1 = {0.f, 0.f, 0.f, 0.f}, h2 = {0.f, 0.f, 0.f, 0.f};
;                         if (m == 0 && !(ai == 0 && wr == 0)) { const int slot = ai == 0 ? 0 : (wr == 0 ? 1 : 2); const PG8_LAS float* b = xh + (((slot * 4 + wc) * 2) * 4 + fq) * 16 + n * 4 + bj * 8;
;                             h2 = *(const PG8_LAS f32x4*)b; h1 = *(const PG8_LAS f32x4*)(b + 64); }
; #pragma unroll
;                         for (int k = 0; k < 4; ++k) { const float cur = acc[ai][bj][m][n][k];
;                             float cc = fmaf(Wq[bj][2][k], cur, Wq[bj][3][k]);
;                             PG8_FMAC_DPP(cc, cur, Wq[bj][1][k], "row_shr:1 row_mask:0xf bank_mask:0xf bound_ctrl:1");
;                             PG8_FMAC_DPP(cc, cur, Wq[bj][0][k], "row_shr:2 row_mask:0xf bank_mask:0xf bound_ctrl:1");
;                             if (m == 0) { const float z = fr == 0 ? h2[k] : h1[k]; cc = fmaf(W1m[bj][k], h1[k], cc); cc = fmaf(W0m[bj][k], z, cc); }
;                             else { const float p = acc[ai][bj][m > 0 ? m - 1 : 0][n][k]; PG8_FMAC_DPP(cc, p, W1m[bj][k], "row_ror:1 row_mask:0xf bank_mask:0xf"); PG8_FMAC_DPP(cc, p, W0m[bj][k], "row_ror:2 row_mask:0xf bank_mask:0xf"); }
;                             c[bj][k] = cc; }
;                         __builtin_amdgcn_sched_barrier(0);
;                     }
;                     const int row = u.pm * BM + ai * HALF + wr * 64 + m * 16 + fr;
;                     if (ai == 0 && m == 0 && wr == 0 && fixtile && fr < 2) {
;                         float* fp = FIX + ((size_t)u.pm * 2 + fr) * 11264 + ch0 + n * 4;
;                         *(PG8_G f32x4*)fp = c[0] * 0.6931471805599453f; *(PG8_G f32x4*)(fp + 5632) = c[1] * 1.4426950408889634f;
;                     } else {
;                         f32x4 ex;
; #pragma unroll
;                         for (int k = 0; k < 4; ++k) ex[k] = __builtin_amdgcn_exp2f(-c[0][k]);
;                         const f32x4 den = ex + 1.0f, gv = c[0] * c[1]; f32x4 rc;
; #pragma unroll
;                         for (int k = 0; k < 4; ++k) rc[k] = __builtin_amdgcn_rcpf(den[k]);
;                         const f32x4 a = gv * rc;
	v_fmac_f32_dpp v84, v162, v241 row_ror:2 row_mask:0xf bank_mask:0xf
	v_fmac_f32_dpp v85, v163, v239 row_ror:2 row_mask:0xf bank_mask:0xf
	v_fmac_f32_dpp v86, v164, v237 row_ror:2 row_mask:0xf bank_mask:0xf
	v_fmac_f32_dpp v87, v165, v233 row_ror:2 row_mask:0xf bank_mask:0xf
	v_fma_f32 v88, v122, v150, v106
	v_fma_f32 v89, v123, v151, v107
	v_fma_f32 v90, v124, v152, v108
	v_fma_f32 v91, v125, v153, v109
	v_fmac_f32_dpp v88, v150, v114 row_shr:1 row_mask:0xf bank_mask:0xf bound_ctrl:1
	v_fmac_f32_dpp v89, v151, v115 row_shr:1 row_mask:0xf bank_mask:0xf bound_ctrl:1
	v_fmac_f32_dpp v90, v152, v116 row_shr:1 row_mask:0xf bank_mask:0xf bound_ctrl:1
	v_fmac_f32_dpp v91, v153, v117 row_shr:1 row_mask:0xf bank_mask:0xf bound_ctrl:1
	v_fmac_f32_dpp v88, v150, v110 row_shr:2 row_mask:0xf bank_mask:0xf bound_ctrl:1
	v_fmac_f32_dpp v89, v151, v111 row_shr:2 row_mask:0xf bank_mask:0xf bound_ctrl:1
	v_fmac_f32_dpp v90, v152, v112 row_shr:2 row_mask:0xf bank_mask:0xf bound_ctrl:1
	v_fmac_f32_dpp v91, v153, v113 row_shr:2 row_mask:0xf bank_mask:0xf bound_ctrl:1
	v_fmac_f32_dpp v88, v154, v236 row_ror:1 row_mask:0xf bank_mask:0xf
	v_fmac_f32_dpp v89, v155, v232 row_ror:1 row_mask:0xf bank_mask:0xf
	v_fmac_f32_dpp v90, v156, v224 row_ror:1 row_mask:0xf bank_mask:0xf
	v_fmac_f32_dpp v91, v157, v213 row_ror:1 row_mask:0xf bank_mask:0xf
	v_fmac_f32_dpp v88, v154, v235 row_ror:2 row_mask:0xf bank_mask:0xf
	v_fmac_f32_dpp v89, v155, v225 row_ror:2 row_mask:0xf bank_mask:0xf
	v_fmac_f32_dpp v90, v156, v223 row_ror:2 row_mask:0xf bank_mask:0xf
	v_fmac_f32_dpp v91, v157, v211 row_ror:2 row_mask:0xf bank_mask:0xf
	v_exp_f32_e64 v96, -v84
	v_exp_f32_e64 v97, -v85
	v_exp_f32_e64 v144, -v86
	v_exp_f32_e64 v145, -v87
	v_add_f32_e32 v96, 1.0, v96
	v_add_f32_e32 v97, 1.0, v97
	v_add_f32_e32 v144, 1.0, v144
	v_add_f32_e32 v145, 1.0, v145
	v_rcp_f32_e32 v96, v96
	v_rcp_f32_e32 v144, v144
	v_rcp_f32_e32 v145, v145
	v_rcp_f32_e32 v97, v97
	v_pk_mul_f32 v[86:87], v[86:87], v[90:91]
	v_pk_mul_f32 v[84:85], v[84:85], v[88:89]
	v_pk_mul_f32 v[86:87], v[144:145], v[86:87]
	v_pk_mul_f32 v[84:85], v[96:97], v[84:85]
	s_nop 0
	v_cvt_pk_bf16_f32 v96, v84, v85
	v_cvt_pk_bf16_f32 v97, v86, v87
	v_fma_f32 v84, v134, v170, v98
	v_fma_f32 v85, v135, v171, v99
	v_fma_f32 v86, v136, v172, v100
	v_fma_f32 v87, v137, v173, v101
	v_fmac_f32_dpp v84, v170, v130 row_shr:1 row_mask:0xf bank_mask:0xf bound_ctrl:1
	v_fmac_f32_dpp v85, v171, v131 row_shr:1 row_mask:0xf bank_mask:0xf bound_ctrl:1
	v_fmac_f32_dpp v86, v172, v132 row_shr:1 row_mask:0xf bank_mask:0xf bound_ctrl:1
	v_fmac_f32_dpp v87, v173, v133 row_shr:1 row_mask:0xf bank_mask:0xf bound_ctrl:1
	v_fmac_f32_dpp v84, v170, v126 row_shr:2 row_mask:0xf bank_mask:0xf bound_ctrl:1
	v_fmac_f32_dpp v85, v171, v127 row_shr:2 row_mask:0xf bank_mask:0xf bound_ctrl:1
	v_fmac_f32_dpp v86, v172, v128 row_shr:2 row_mask:0xf bank_mask:0xf bound_ctrl:1
	v_fmac_f32_dpp v87, v173, v129 row_shr:2 row_mask:0xf bank_mask:0xf bound_ctrl:1
	v_fmac_f32_dpp v84, v158, v242 row_ror:1 row_mask:0xf bank_mask:0xf
	v_fmac_f32_dpp v85, v159, v240 row_ror:1 row_mask:0xf bank_mask:0xf
	v_fmac_f32_dpp v86, v160, v238 row_ror:1 row_mask:0xf bank_mask:0xf
	v_fmac_f32_dpp v87, v161, v234 row_ror:1 row_mask:0xf bank_mask:0xf
	v_fmac_f32_dpp v84, v158, v241 row_ror:2 row_mask:0xf bank_mask:0xf
	v_fmac_f32_dpp v85, v159, v239 row_ror:2 row_mask:0xf bank_mask:0xf
	v_fmac_f32_dpp v86, v160, v237 row_ror:2 row_mask:0xf bank_mask:0xf
	v_fmac_f32_dpp v87, v161, v233 row_ror:2 row_mask:0xf bank_mask:0xf
	v_fma_f32 v88, v122, v166, v106
	v_fma_f32 v89, v123, v167, v107
	v_fma_f32 v90, v124, v168, v108
	v_fma_f32 v91, v125, v169, v109
	v_fmac_f32_dpp v88, v166, v114 row_shr:1 row_mask:0xf bank_mask:0xf bound_ctrl:1
	v_fmac_f32_dpp v89, v167, v115 row_shr:1 row_mask:0xf bank_mask:0xf bound_ctrl:1
	v_fmac_f32_dpp v90, v168, v116 row_shr:1 row_mask:0xf bank_mask:0xf bound_ctrl:1
	v_fmac_f32_dpp v91, v169, v117 row_shr:1 row_mask:0xf bank_mask:0xf bound_ctrl:1
	v_fmac_f32_dpp v88, v166, v110 row_shr:2 row_mask:0xf bank_mask:0xf bound_ctrl:1
	v_fmac_f32_dpp v89, v167, v111 row_shr:2 row_mask:0xf bank_mask:0xf bound_ctrl:1
	v_fmac_f32_dpp v90, v168, v112 row_shr:2 row_mask:0xf bank_mask:0xf bound_ctrl:1
	v_fmac_f32_dpp v91, v169, v113 row_shr:2 row_mask:0xf bank_mask:0xf bound_ctrl:1
	v_fmac_f32_dpp v88, v150, v236 row_ror:1 row_mask:0xf bank_mask:0xf
	v_fmac_f32_dpp v89, v151, v232 row_ror:1 row_mask:0xf bank_mask:0xf
	v_fmac_f32_dpp v90, v152, v224 row_ror:1 row_mask:0xf bank_mask:0xf
	v_fmac_f32_dpp v91, v153, v213 row_ror:1 row_mask:0xf bank_mask:0xf
	v_fmac_f32_dpp v88, v150, v235 row_ror:2 row_mask:0xf bank_mask:0xf
	v_fmac_f32_dpp v89, v151, v225 row_ror:2 row_mask:0xf bank_mask:0xf
	v_fmac_f32_dpp v90, v152, v223 row_ror:2 row_mask:0xf bank_mask:0xf
	v_fmac_f32_dpp v91, v153, v211 row_ror:2 row_mask:0xf bank_mask:0xf
	v_exp_f32_e64 v144, -v84
	v_exp_f32_e64 v145, -v85
	v_exp_f32_e64 v150, -v86
	v_exp_f32_e64 v151, -v87
	v_add_f32_e32 v144, 1.0, v144
	v_add_f32_e32 v145, 1.0, v145
	v_add_f32_e32 v150, 1.0, v150
	v_add_f32_e32 v151, 1.0, v151
	v_rcp_f32_e32 v144, v144
	v_rcp_f32_e32 v150, v150
	v_rcp_f32_e32 v151, v151
	v_rcp_f32_e32 v145, v145
	v_pk_mul_f32 v[86:87], v[86:87], v[90:91]
	v_pk_mul_f32 v[84:85], v[84:85], v[88:89]
	v_pk_mul_f32 v[86:87], v[150:151], v[86:87]
	v_pk_mul_f32 v[84:85], v[144:145], v[84:85]
	s_nop 0
	v_cvt_pk_bf16_f32 v90, v84, v85
	v_cvt_pk_bf16_f32 v91, v86, v87
	v_add_u32_e32 v144, s54, v243
	ds_read_b128 v[84:87], v144
	ds_read_b128 v[150:153], v144 offset:256
	v_fma_f32 v88, v134, v146, v98
	v_fmac_f32_dpp v88, v146, v130 row_shr:1 row_mask:0xf bank_mask:0xf bound_ctrl:1
	v_fma_f32 v89, v135, v147, v99
	v_fmac_f32_dpp v88, v146, v126 row_shr:2 row_mask:0xf bank_mask:0xf bound_ctrl:1
	v_fmac_f32_dpp v89, v147, v131 row_shr:1 row_mask:0xf bank_mask:0xf bound_ctrl:1
	v_fma_f32 v154, v136, v148, v100
	s_waitcnt lgkmcnt(0)
;     PG8_NOPRE
;     __device__ __forceinline__ void operator()(const f32x4 (&acc_)[2][2][4][2], const Unit& u, int wr, int wc, int fr_, int fq_, int ui) const {
;     ...
;                     for (int bj = 0; bj < 2; ++bj) {
;                         f32x4 h1 = {0.f, 0.f, 0.f, 0.f}, h2 = {0.f, 0.f, 0.f, 0.f};
;                         if (m == 0 && !(ai == 0 && wr == 0)) { const int slot = ai == 0 ? 0 : (wr == 0 ? 1 : 2); const PG8_LAS float* b = xh + (((slot * 4 + wc) * 2) * 4 + fq) * 16 + n * 4 + bj * 8;
;                             h2 = *(const PG8_LAS f32x4*)b; h1 = *(const PG8_LAS f32x4*)(b + 64); }
; #pragma unroll
;                         for (int k = 0; k < 4; ++k) { const float cur = acc[ai][bj][m][n][k];
;                             float cc = fmaf(Wq[bj][2][k], cur, Wq[bj][3][k]);
;                             PG8_FMAC_DPP(cc, cur, Wq[bj][1][k], "row_shr:1 row_mask:0xf bank_mask:0xf bound_ctrl:1");
;                             PG8_FMAC_DPP(cc, cur, Wq[bj][0][k], "row_shr:2 row_mask:0xf bank_mask:0xf bound_ctrl:1");
;                             if (m == 0) { const float z = fr == 0 ? h2[k] : h1[k]; cc = fmaf(W1m[bj][k], h1[k], cc); cc = fmaf(W0m[bj][k], z, cc); }
;                             else { const float p = acc[ai][bj][m > 0 ? m - 1 : 0][n][k]; PG8_FMAC_DPP(cc, p, W1m[bj][k], "row_ror:1 row_mask:0xf bank_mask:0xf"); PG8_FMAC_DPP(cc, p, W0m[bj][k], "row_ror:2 row_mask:0xf bank_mask:0xf"); }
;                             c[bj][k] = cc; }
;                         __builtin_amdgcn_sched_barrier(0);
;                     }
;                     const int row = u.pm * BM + ai * HALF + wr * 64 + m * 16 + fr;
;                     if (ai == 0 && m == 0 && wr == 0 && fixtile && fr < 2) {
;                         float* fp = FIX + ((size_t)u.pm * 2 + fr) * 11264 + ch0 + n * 4;
;                         *(PG8_G f32x4*)fp = c[0] * 0.6931471805599453f; *(PG8_G f32x4*)(fp + 5632) = c[1] * 1.4426950408889634f;
;                     } else {
;                         f32x4 ex;
; #pragma unroll
;                         for (int k = 0; k < 4; ++k) ex[k] = __builtin_amdgcn_exp2f(-c[0][k]);
;                         const f32x4 den = ex + 1.0f, gv = c[0] * c[1]; f32x4 rc;
; #pragma unroll
;                         for (int k = 0; k < 4; ++k) rc[k] = __builtin_amdgcn_rcpf(den[k]);
;                         const f32x4 a = gv * rc;
	v_cndmask_b32_e64 v84, v150, v84, s[8:9]
	v_fmac_f32_e32 v88, v242, v150
	v_fmac_f32_dpp v89, v147, v127 row_shr:2 row_mask:0xf bank_mask:0xf bound_ctrl:1
	v_fmac_f32_dpp v154, v148, v132 row_shr:1 row_mask:0xf bank_mask:0xf bound_ctrl:1
	v_fma_f32 v155, v137, v149, v101
	v_fmac_f32_e32 v88, v241, v84
	v_cndmask_b32_e64 v84, v151, v85, s[8:9]
	v_fmac_f32_e32 v89, v240, v151
	v_fmac_f32_dpp v154, v148, v128 row_shr:2 row_mask:0xf bank_mask:0xf bound_ctrl:1
	v_fmac_f32_dpp v155, v149, v133 row_shr:1 row_mask:0xf bank_mask:0xf bound_ctrl:1
	v_fmac_f32_e32 v89, v239, v84
	v_cndmask_b32_e64 v84, v152, v86, s[8:9]
	v_fmac_f32_e32 v154, v238, v152
	v_fmac_f32_dpp v155, v149, v129 row_shr:2 row_mask:0xf bank_mask:0xf bound_ctrl:1
	v_fmac_f32_e32 v154, v237, v84
	v_cndmask_b32_e64 v84, v153, v87, s[8:9]
	v_fmac_f32_e32 v155, v234, v153
	v_fmac_f32_e32 v155, v233, v84
	ds_read_b128 v[84:87], v144 offset:32
	ds_read_b128 v[150:153], v144 offset:288
	v_fma_f32 v156, v122, v140, v106
	v_fmac_f32_dpp v156, v140, v114 row_shr:1 row_mask:0xf bank_mask:0xf bound_ctrl:1
	v_fma_f32 v157, v123, v141, v107
	v_fmac_f32_dpp v156, v140, v110 row_shr:2 row_mask:0xf bank_mask:0xf bound_ctrl:1
	v_fmac_f32_dpp v157, v141, v115 row_shr:1 row_mask:0xf bank_mask:0xf bound_ctrl:1
	s_waitcnt lgkmcnt(0)
	v_cndmask_b32_e64 v84, v150, v84, s[8:9]
	v_fmac_f32_e32 v156, v236, v150
	v_fmac_f32_dpp v157, v141, v111 row_shr:2 row_mask:0xf bank_mask:0xf bound_ctrl:1
	v_fmac_f32_e32 v156, v235, v84
	v_cndmask_b32_e64 v84, v151, v85, s[8:9]
	v_fmac_f32_e32 v157, v232, v151
	v_fmac_f32_e32 v157, v225, v84
	v_fma_f32 v84, v124, v138, v108
	v_fmac_f32_dpp v84, v138, v116 row_shr:1 row_mask:0xf bank_mask:0xf bound_ctrl:1
	v_cndmask_b32_e64 v85, v152, v86, s[8:9]
	v_fmac_f32_dpp v84, v138, v112 row_shr:2 row_mask:0xf bank_mask:0xf bound_ctrl:1
	v_cndmask_b32_e64 v86, v153, v87, s[8:9]
	v_fmac_f32_e32 v84, v224, v152
	v_fmac_f32_e32 v84, v223, v85
	v_fma_f32 v85, v125, v139, v109
	v_fmac_f32_dpp v85, v139, v117 row_shr:1 row_mask:0xf bank_mask:0xf bound_ctrl:1
	s_nop 0
	v_fmac_f32_dpp v85, v139, v113 row_shr:2 row_mask:0xf bank_mask:0xf bound_ctrl:1
	s_nop 0
	v_fmac_f32_e32 v85, v213, v153
	v_fmac_f32_e32 v85, v211, v86
	v_exp_f32_e64 v145, -v154
	v_exp_f32_e64 v86, -v88
	v_exp_f32_e64 v87, -v89
	v_exp_f32_e64 v151, -v155
	v_add_f32_e32 v145, 1.0, v145
	v_add_f32_e32 v86, 1.0, v86
	v_add_f32_e32 v87, 1.0, v87
	v_rcp_f32_e32 v150, v145
	v_add_f32_e32 v145, 1.0, v151
	v_rcp_f32_e32 v86, v86
	v_rcp_f32_e32 v151, v145
	v_rcp_f32_e32 v87, v87
	v_pk_mul_f32 v[88:89], v[88:89], v[156:157]
	v_pk_mul_f32 v[84:85], v[154:155], v[84:85]
	v_pk_mul_f32 v[86:87], v[86:87], v[88:89]
	v_pk_mul_f32 v[84:85], v[150:151], v[84:85]
	v_cvt_pk_bf16_f32 v88, v86, v87
	s_nop 0
	v_cvt_pk_bf16_f32 v89, v84, v85
	v_fma_f32 v84, v134, v142, v98
	v_fma_f32 v85, v135, v143, v99
	v_fma_f32 v86, v136, v118, v100
	v_fma_f32 v87, v137, v119, v101
	v_fmac_f32_dpp v84, v142, v130 row_shr:1 row_mask:0xf bank_mask:0xf bound_ctrl:1
	v_fmac_f32_dpp v85, v143, v131 row_shr:1 row_mask:0xf bank_mask:0xf bound_ctrl:1
	v_fmac_f32_dpp v86, v118, v132 row_shr:1 row_mask:0xf bank_mask:0xf bound_ctrl:1
	v_fmac_f32_dpp v87, v119, v133 row_shr:1 row_mask:0xf bank_mask:0xf bound_ctrl:1
	v_fmac_f32_dpp v84, v142, v126 row_shr:2 row_mask:0xf bank_mask:0xf bound_ctrl:1
	v_fmac_f32_dpp v85, v143, v127 row_shr:2 row_mask:0xf bank_mask:0xf bound_ctrl:1
	v_fmac_f32_dpp v86, v118, v128 row_shr:2 row_mask:0xf bank_mask:0xf bound_ctrl:1
	v_fmac_f32_dpp v87, v119, v129 row_shr:2 row_mask:0xf bank_mask:0xf bound_ctrl:1
	v_fmac_f32_dpp v84, v146, v242 row_ror:1 row_mask:0xf bank_mask:0xf
	v_fmac_f32_dpp v85, v147, v240 row_ror:1 row_mask:0xf bank_mask:0xf
	v_fmac_f32_dpp v86, v148, v238 row_ror:1 row_mask:0xf bank_mask:0xf
	v_fmac_f32_dpp v87, v149, v234 row_ror:1 row_mask:0xf bank_mask:0xf
	v_fmac_f32_dpp v84, v146, v241 row_ror:2 row_mask:0xf bank_mask:0xf
	v_fmac_f32_dpp v85, v147, v239 row_ror:2 row_mask:0xf bank_mask:0xf
	v_fmac_f32_dpp v86, v148, v237 row_ror:2 row_mask:0xf bank_mask:0xf
	v_fmac_f32_dpp v87, v149, v233 row_ror:2 row_mask:0xf bank_mask:0xf
	v_fma_f32 v146, v122, v102, v106
	v_fma_f32 v147, v123, v103, v107
	v_fmac_f32_dpp v146, v102, v114 row_shr:1 row_mask:0xf bank_mask:0xf bound_ctrl:1
	v_fmac_f32_dpp v147, v103, v115 row_shr:1 row_mask:0xf bank_mask:0xf bound_ctrl:1
	s_nop 0
	v_fmac_f32_dpp v146, v102, v110 row_shr:2 row_mask:0xf bank_mask:0xf bound_ctrl:1
	v_fmac_f32_dpp v147, v103, v111 row_shr:2 row_mask:0xf bank_mask:0xf bound_ctrl:1
	s_nop 0
	v_fmac_f32_dpp v146, v140, v236 row_ror:1 row_mask:0xf bank_mask:0xf
	v_fmac_f32_dpp v147, v141, v232 row_ror:1 row_mask:0xf bank_mask:0xf
	s_nop 0
	v_fmac_f32_dpp v146, v140, v235 row_ror:2 row_mask:0xf bank_mask:0xf
	v_fmac_f32_dpp v147, v141, v225 row_ror:2 row_mask:0xf bank_mask:0xf
	v_fma_f32 v140, v124, v14, v108
	v_fma_f32 v141, v125, v15, v109
	v_fmac_f32_dpp v140, v14, v116 row_shr:1 row_mask:0xf bank_mask:0xf bound_ctrl:1
	v_fmac_f32_dpp v141, v15, v117 row_shr:1 row_mask:0xf bank_mask:0xf bound_ctrl:1
	s_nop 0
	v_fmac_f32_dpp v140, v14, v112 row_shr:2 row_mask:0xf bank_mask:0xf bound_ctrl:1
	v_fmac_f32_dpp v141, v15, v113 row_shr:2 row_mask:0xf bank_mask:0xf bound_ctrl:1
	s_nop 0
	v_fmac_f32_dpp v140, v138, v224 row_ror:1 row_mask:0xf bank_mask:0xf
	v_fmac_f32_dpp v141, v139, v213 row_ror:1 row_mask:0xf bank_mask:0xf
	s_nop 0
	v_fmac_f32_dpp v140, v138, v223 row_ror:2 row_mask:0xf bank_mask:0xf
	v_fmac_f32_dpp v141, v139, v211 row_ror:2 row_mask:0xf bank_mask:0xf
	v_exp_f32_e64 v145, -v86
	v_exp_f32_e64 v138, -v84
	v_exp_f32_e64 v139, -v85
	v_exp_f32_e64 v149, -v87
;     PG8_NOPRE
;     __device__ __forceinline__ void operator()(const f32x4 (&acc_)[2][2][4][2], const Unit& u, int wr, int wc, int fr_, int fq_, int ui) const {
;     ...
;                     for (int bj = 0; bj < 2; ++bj) {
;                         f32x4 h1 = {0.f, 0.f, 0.f, 0.f}, h2 = {0.f, 0.f, 0.f, 0.f};
;                         if (m == 0 && !(ai == 0 && wr == 0)) { const int slot = ai == 0 ? 0 : (wr == 0 ? 1 : 2); const PG8_LAS float* b = xh + (((slot * 4 + wc) * 2) * 4 + fq) * 16 + n * 4 + bj * 8;
;                             h2 = *(const PG8_LAS f32x4*)b; h1 = *(const PG8_LAS f32x4*)(b + 64); }
; #pragma unroll
;                         for (int k = 0; k < 4; ++k) { const float cur = acc[ai][bj][m][n][k];
;                             float cc = fmaf(Wq[bj][2][k], cur, Wq[bj][3][k]);
;                             PG8_FMAC_DPP(cc, cur, Wq[bj][1][k], "row_shr:1 row_mask:0xf bank_mask:0xf bound_ctrl:1");
;                             PG8_FMAC_DPP(cc, cur, Wq[bj][0][k], "row_shr:2 row_mask:0xf bank_mask:0xf bound_ctrl:1");
;                             if (m == 0) { const float z = fr == 0 ? h2[k] : h1[k]; cc = fmaf(W1m[bj][k], h1[k], cc); cc = fmaf(W0m[bj][k], z, cc); }
;                             else { const float p = acc[ai][bj][m > 0 ? m - 1 : 0][n][k]; PG8_FMAC_DPP(cc, p, W1m[bj][k], "row_ror:1 row_mask:0xf bank_mask:0xf"); PG8_FMAC_DPP(cc, p, W0m[bj][k], "row_ror:2 row_mask:0xf bank_mask:0xf"); }
;                             c[bj][k] = cc; }
;                         __builtin_amdgcn_sched_barrier(0);
;                     }
;                     const int row = u.pm * BM + ai * HALF + wr * 64 + m * 16 + fr;
;                     if (ai == 0 && m == 0 && wr == 0 && fixtile && fr < 2) {
;                         float* fp = FIX + ((size_t)u.pm * 2 + fr) * 11264 + ch0 + n * 4;
;                         *(PG8_G f32x4*)fp = c[0] * 0.6931471805599453f; *(PG8_G f32x4*)(fp + 5632) = c[1] * 1.4426950408889634f;
;                     } else {
;                         f32x4 ex;
; #pragma unroll
;                         for (int k = 0; k < 4; ++k) ex[k] = __builtin_amdgcn_exp2f(-c[0][k]);
;                         const f32x4 den = ex + 1.0f, gv = c[0] * c[1]; f32x4 rc;
; #pragma unroll
;                         for (int k = 0; k < 4; ++k) rc[k] = __builtin_amdgcn_rcpf(den[k]);
;                         const f32x4 a = gv * rc;
	v_add_f32_e32 v145, 1.0, v145
	v_add_f32_e32 v138, 1.0, v138
	v_add_f32_e32 v139, 1.0, v139
	v_rcp_f32_e32 v148, v145
	v_add_f32_e32 v145, 1.0, v149
	v_rcp_f32_e32 v138, v138
	v_rcp_f32_e32 v149, v145
	v_rcp_f32_e32 v139, v139
	v_pk_mul_f32 v[86:87], v[86:87], v[140:141]
	v_pk_mul_f32 v[84:85], v[84:85], v[146:147]
	v_pk_mul_f32 v[140:141], v[148:149], v[86:87]
	v_pk_mul_f32 v[84:85], v[138:139], v[84:85]
	s_nop 0
	v_cvt_pk_bf16_f32 v86, v84, v85
	v_cvt_pk_bf16_f32 v87, v140, v141
	v_fma_f32 v84, v134, v12, v98
	v_fma_f32 v85, v135, v13, v99
	v_fma_f32 v138, v136, v8, v100
	v_fma_f32 v139, v137, v9, v101
	v_fmac_f32_dpp v84, v12, v130 row_shr:1 row_mask:0xf bank_mask:0xf bound_ctrl:1
	v_fmac_f32_dpp v85, v13, v131 row_shr:1 row_mask:0xf bank_mask:0xf bound_ctrl:1
	v_fmac_f32_dpp v138, v8, v132 row_shr:1 row_mask:0xf bank_mask:0xf bound_ctrl:1
	v_fmac_f32_dpp v139, v9, v133 row_shr:1 row_mask:0xf bank_mask:0xf bound_ctrl:1
	v_fmac_f32_dpp v84, v12, v126 row_shr:2 row_mask:0xf bank_mask:0xf bound_ctrl:1
	v_fmac_f32_dpp v85, v13, v127 row_shr:2 row_mask:0xf bank_mask:0xf bound_ctrl:1
	v_fmac_f32_dpp v138, v8, v128 row_shr:2 row_mask:0xf bank_mask:0xf bound_ctrl:1
	v_fmac_f32_dpp v139, v9, v129 row_shr:2 row_mask:0xf bank_mask:0xf bound_ctrl:1
	v_fmac_f32_dpp v84, v142, v242 row_ror:1 row_mask:0xf bank_mask:0xf
	v_fmac_f32_dpp v85, v143, v240 row_ror:1 row_mask:0xf bank_mask:0xf
	v_fmac_f32_dpp v138, v118, v238 row_ror:1 row_mask:0xf bank_mask:0xf
	v_fmac_f32_dpp v139, v119, v234 row_ror:1 row_mask:0xf bank_mask:0xf
	v_fmac_f32_dpp v84, v142, v241 row_ror:2 row_mask:0xf bank_mask:0xf
	v_fmac_f32_dpp v85, v143, v239 row_ror:2 row_mask:0xf bank_mask:0xf
	v_fmac_f32_dpp v138, v118, v237 row_ror:2 row_mask:0xf bank_mask:0xf
	v_fmac_f32_dpp v139, v119, v233 row_ror:2 row_mask:0xf bank_mask:0xf
	v_fma_f32 v118, v122, v6, v106
	v_fma_f32 v119, v123, v7, v107
	v_fmac_f32_dpp v118, v6, v114 row_shr:1 row_mask:0xf bank_mask:0xf bound_ctrl:1
	v_fmac_f32_dpp v119, v7, v115 row_shr:1 row_mask:0xf bank_mask:0xf bound_ctrl:1
	s_nop 0
	v_fmac_f32_dpp v118, v6, v110 row_shr:2 row_mask:0xf bank_mask:0xf bound_ctrl:1
	v_fmac_f32_dpp v119, v7, v111 row_shr:2 row_mask:0xf bank_mask:0xf bound_ctrl:1
	s_nop 0
	v_fmac_f32_dpp v118, v102, v236 row_ror:1 row_mask:0xf bank_mask:0xf
	v_fmac_f32_dpp v119, v103, v232 row_ror:1 row_mask:0xf bank_mask:0xf
	s_nop 0
	v_fmac_f32_dpp v118, v102, v235 row_ror:2 row_mask:0xf bank_mask:0xf
	v_fmac_f32_dpp v119, v103, v225 row_ror:2 row_mask:0xf bank_mask:0xf
	v_fma_f32 v102, v124, v4, v108
	v_fma_f32 v103, v125, v5, v109
	v_fmac_f32_dpp v102, v4, v116 row_shr:1 row_mask:0xf bank_mask:0xf bound_ctrl:1
	v_fmac_f32_dpp v103, v5, v117 row_shr:1 row_mask:0xf bank_mask:0xf bound_ctrl:1
	s_nop 0
	v_fmac_f32_dpp v102, v4, v112 row_shr:2 row_mask:0xf bank_mask:0xf bound_ctrl:1
	v_fmac_f32_dpp v103, v5, v113 row_shr:2 row_mask:0xf bank_mask:0xf bound_ctrl:1
	s_nop 0
	v_fmac_f32_dpp v102, v14, v224 row_ror:1 row_mask:0xf bank_mask:0xf
	v_fmac_f32_dpp v103, v15, v213 row_ror:1 row_mask:0xf bank_mask:0xf
	s_nop 0
	v_fmac_f32_dpp v102, v14, v223 row_ror:2 row_mask:0xf bank_mask:0xf
	v_fmac_f32_dpp v103, v15, v211 row_ror:2 row_mask:0xf bank_mask:0xf
	v_exp_f32_e64 v14, -v84
	v_exp_f32_e64 v15, -v85
	v_exp_f32_e64 v140, -v138
	v_exp_f32_e64 v141, -v139
	v_add_f32_e32 v14, 1.0, v14
	v_add_f32_e32 v15, 1.0, v15
	v_add_f32_e32 v140, 1.0, v140
	v_add_f32_e32 v141, 1.0, v141
	v_rcp_f32_e32 v14, v14
	v_rcp_f32_e32 v140, v140
	v_rcp_f32_e32 v141, v141
	v_rcp_f32_e32 v15, v15
	v_pk_mul_f32 v[102:103], v[138:139], v[102:103]
	v_pk_mul_f32 v[84:85], v[84:85], v[118:119]
	v_pk_mul_f32 v[102:103], v[140:141], v[102:103]
	v_pk_mul_f32 v[14:15], v[14:15], v[84:85]
	s_nop 0
	v_cvt_pk_bf16_f32 v84, v14, v15
	v_cvt_pk_bf16_f32 v85, v102, v103
	v_fma_f32 v14, v134, v92, v98
	v_fma_f32 v15, v135, v93, v99
	v_fma_f32 v100, v136, v94, v100
	v_fmac_f32_e32 v101, v137, v95
	v_fmac_f32_dpp v14, v92, v130 row_shr:1 row_mask:0xf bank_mask:0xf bound_ctrl:1
	v_fmac_f32_dpp v15, v93, v131 row_shr:1 row_mask:0xf bank_mask:0xf bound_ctrl:1
	v_fmac_f32_dpp v100, v94, v132 row_shr:1 row_mask:0xf bank_mask:0xf bound_ctrl:1
	v_fmac_f32_dpp v101, v95, v133 row_shr:1 row_mask:0xf bank_mask:0xf bound_ctrl:1
	v_fmac_f32_dpp v14, v92, v126 row_shr:2 row_mask:0xf bank_mask:0xf bound_ctrl:1
	v_fmac_f32_dpp v15, v93, v127 row_shr:2 row_mask:0xf bank_mask:0xf bound_ctrl:1
; #define PG8_LAS __attribute__((address_space(3)))
; #define PG8_FMAC_DPP(c_, x_, w_, ctrl_) asm("v_fmac_f32_dpp %0, %1, %2 " ctrl_ : "+v"(c_) : "v"(x_), "v"(w_))
;     PG8_NOPRE
;     __device__ __forceinline__ void operator()(const f32x4 (&acc_)[2][2][4][2], const Unit& u, int wr, int wc, int fr_, int fq_, int ui) const {
;     ...
;             for (int bj = 0; bj < 2; ++bj) {
; #pragma unroll
;                 for (int t = 0; t < 4; ++t) Wq[bj][t] = *(const PG8_LAS f32x4*)(cwb + t * 256 + bj * 128);
; #pragma unroll
;                 for (int k = 0; k < 4; ++k) { W1m[bj][k] = fr == 0 ? Wq[bj][1][k] : 0.f; W0m[bj][k] = fr < 2 ? Wq[bj][0][k] : 0.f; } }
; #pragma unroll
;             for (int ai = 0; ai < 2; ++ai)
; #pragma unroll
;                 for (int m = 0; m < 4; ++m) {
;                     f32x4 c[2];
; #pragma unroll
;                     for (int bj = 0; bj < 2; ++bj) {
;                         f32x4 h1 = {0.f, 0.f, 0.f, 0.f}, h2 = {0.f, 0.f, 0.f, 0.f};
;                         if (m == 0 && !(ai == 0 && wr == 0)) { const int slot = ai == 0 ? 0 : (wr == 0 ? 1 : 2); const PG8_LAS float* b = xh + (((slot * 4 + wc) * 2) * 4 + fq) * 16 + n * 4 + bj * 8;
;                             h2 = *(const PG8_LAS f32x4*)b; h1 = *(const PG8_LAS f32x4*)(b + 64); }
; #pragma unroll
;                         for (int k = 0; k < 4; ++k) { const float cur = acc[ai][bj][m][n][k];
;                             float cc = fmaf(Wq[bj][2][k], cur, Wq[bj][3][k]);
;                             PG8_FMAC_DPP(cc, cur, Wq[bj][1][k], "row_shr:1 row_mask:0xf bank_mask:0xf bound_ctrl:1");
;                             PG8_FMAC_DPP(cc, cur, Wq[bj][0][k], "row_shr:2 row_mask:0xf bank_mask:0xf bound_ctrl:1");
;                             if (m == 0) { const float z = fr == 0 ? h2[k] : h1[k]; cc = fmaf(W1m[bj][k], h1[k], cc); cc = fmaf(W0m[bj][k], z, cc); }
;                             else { const float p = acc[ai][bj][m > 0 ? m - 1 : 0][n][k]; PG8_FMAC_DPP(cc, p, W1m[bj][k], "row_ror:1 row_mask:0xf bank_mask:0xf"); PG8_FMAC_DPP(cc, p, W0m[bj][k], "row_ror:2 row_mask:0xf bank_mask:0xf"); }
;                             c[bj][k] = cc; }
	v_fmac_f32_dpp v100, v94, v128 row_shr:2 row_mask:0xf bank_mask:0xf bound_ctrl:1
	v_fmac_f32_dpp v101, v95, v129 row_shr:2 row_mask:0xf bank_mask:0xf bound_ctrl:1
	v_fmac_f32_dpp v14, v12, v242 row_ror:1 row_mask:0xf bank_mask:0xf
	v_fmac_f32_dpp v15, v13, v240 row_ror:1 row_mask:0xf bank_mask:0xf
	v_fmac_f32_dpp v100, v8, v238 row_ror:1 row_mask:0xf bank_mask:0xf
	v_fmac_f32_dpp v101, v9, v234 row_ror:1 row_mask:0xf bank_mask:0xf
	v_fmac_f32_dpp v14, v12, v241 row_ror:2 row_mask:0xf bank_mask:0xf
	v_fmac_f32_dpp v15, v13, v239 row_ror:2 row_mask:0xf bank_mask:0xf
	v_fmac_f32_dpp v100, v8, v237 row_ror:2 row_mask:0xf bank_mask:0xf
	v_fmac_f32_dpp v101, v9, v233 row_ror:2 row_mask:0xf bank_mask:0xf
	v_fma_f32 v8, v122, v80, v106
	v_fma_f32 v9, v123, v81, v107
	v_fma_f32 v108, v124, v82, v108
	v_fmac_f32_e32 v109, v125, v83
	v_fmac_f32_dpp v8, v80, v114 row_shr:1 row_mask:0xf bank_mask:0xf bound_ctrl:1
	v_fmac_f32_dpp v9, v81, v115 row_shr:1 row_mask:0xf bank_mask:0xf bound_ctrl:1
	v_fmac_f32_dpp v108, v82, v116 row_shr:1 row_mask:0xf bank_mask:0xf bound_ctrl:1
	v_fmac_f32_dpp v109, v83, v117 row_shr:1 row_mask:0xf bank_mask:0xf bound_ctrl:1
	v_fmac_f32_dpp v8, v80, v110 row_shr:2 row_mask:0xf bank_mask:0xf bound_ctrl:1
	v_fmac_f32_dpp v9, v81, v111 row_shr:2 row_mask:0xf bank_mask:0xf bound_ctrl:1
	v_fmac_f32_dpp v108, v82, v112 row_shr:2 row_mask:0xf bank_mask:0xf bound_ctrl:1
	v_fmac_f32_dpp v109, v83, v113 row_shr:2 row_mask:0xf bank_mask:0xf bound_ctrl:1
	v_fmac_f32_dpp v8, v6, v236 row_ror:1 row_mask:0xf bank_mask:0xf
	v_fmac_f32_dpp v9, v7, v232 row_ror:1 row_mask:0xf bank_mask:0xf
	v_fmac_f32_dpp v108, v4, v224 row_ror:1 row_mask:0xf bank_mask:0xf
	v_fmac_f32_dpp v109, v5, v213 row_ror:1 row_mask:0xf bank_mask:0xf
	v_fmac_f32_dpp v8, v6, v235 row_ror:2 row_mask:0xf bank_mask:0xf
	v_fmac_f32_dpp v9, v7, v225 row_ror:2 row_mask:0xf bank_mask:0xf
	v_fmac_f32_dpp v108, v4, v223 row_ror:2 row_mask:0xf bank_mask:0xf
	v_fmac_f32_dpp v109, v5, v211 row_ror:2 row_mask:0xf bank_mask:0xf
	v_exp_f32_e64 v4, -v14
	v_exp_f32_e64 v5, -v15
	v_exp_f32_e64 v6, -v100
	v_exp_f32_e64 v7, -v101
	v_add_f32_e32 v4, 1.0, v4
	v_add_f32_e32 v5, 1.0, v5
	v_add_f32_e32 v6, 1.0, v6
	v_add_f32_e32 v7, 1.0, v7
	v_rcp_f32_e32 v4, v4
	v_rcp_f32_e32 v6, v6
	v_rcp_f32_e32 v7, v7
	v_rcp_f32_e32 v5, v5
	v_pk_mul_f32 v[12:13], v[100:101], v[108:109]
	v_pk_mul_f32 v[8:9], v[14:15], v[8:9]
	v_pk_mul_f32 v[6:7], v[6:7], v[12:13]
	v_pk_mul_f32 v[4:5], v[4:5], v[8:9]
	s_nop 0
	v_cvt_pk_bf16_f32 v12, v4, v5
	v_cvt_pk_bf16_f32 v13, v6, v7
	ds_read_b128 v[124:127], v200 offset:16
	ds_read_b128 v[108:111], v200 offset:528
	ds_read_b128 v[128:131], v200 offset:1040
	ds_read_b128 v[112:115], v200 offset:1552
	ds_read_b128 v[132:135], v200 offset:2064
	ds_read_b128 v[116:119], v200 offset:2576
	ds_read_b128 v[80:83], v200 offset:3088
	ds_read_b128 v[100:103], v200 offset:3600
	v_mov_b32_e32 v6, 0
	s_and_b64 vcc, exec, s[12:13]
	v_mov_b32_e32 v92, 0
	v_mov_b32_e32 v93, 0
	v_mov_b32_e32 v94, 0
	v_mov_b32_e32 v95, 0
	v_mov_b32_e32 v136, 0
	v_mov_b32_e32 v137, 0
	v_mov_b32_e32 v138, 0
	v_mov_b32_e32 v139, 0
	s_cbranch_vccnz .LBB0_1109
	ds_read_b128 v[136:139], v197 offset:16
	ds_read_b128 v[92:95], v197 offset:272
.LBB0_1109:
	v_mov_b32_e32 v122, v216
	v_mov_b32_e32 v123, v216
	v_pk_mul_f32 v[98:99], v[74:75], v[122:123]
	v_pk_mul_f32 v[106:107], v[72:73], v[216:217]
	s_waitcnt lgkmcnt(0)
	v_fma_f32 v14, v134, v98, v82
	v_fma_f32 v4, v132, v106, v80
	v_fma_f32 v5, v133, v107, v81
	v_fma_f32 v15, v135, v99, v83
	v_fmac_f32_dpp v4, v106, v128 row_shr:1 row_mask:0xf bank_mask:0xf bound_ctrl:1
	v_fmac_f32_dpp v5, v107, v129 row_shr:1 row_mask:0xf bank_mask:0xf bound_ctrl:1
	v_fmac_f32_dpp v14, v98, v130 row_shr:1 row_mask:0xf bank_mask:0xf bound_ctrl:1
	v_fmac_f32_dpp v15, v99, v131 row_shr:1 row_mask:0xf bank_mask:0xf bound_ctrl:1
	v_fmac_f32_dpp v4, v106, v124 row_shr:2 row_mask:0xf bank_mask:0xf bound_ctrl:1
	v_fmac_f32_dpp v5, v107, v125 row_shr:2 row_mask:0xf bank_mask:0xf bound_ctrl:1
	v_fmac_f32_dpp v14, v98, v126 row_shr:2 row_mask:0xf bank_mask:0xf bound_ctrl:1
	v_fmac_f32_dpp v15, v99, v127 row_shr:2 row_mask:0xf bank_mask:0xf bound_ctrl:1
	s_and_b64 vcc, exec, s[12:13]
	v_mov_b32_e32 v7, 0
	v_mov_b32_e32 v8, 0
	v_mov_b32_e32 v9, 0
	v_mov_b32_e32 v72, 0
	v_mov_b32_e32 v73, 0
	v_mov_b32_e32 v74, 0
	v_mov_b32_e32 v75, 0
	s_cbranch_vccnz .LBB0_1111
	ds_read_b128 v[72:75], v197 offset:48
	ds_read_b128 v[6:9], v197 offset:304

; __device__ __forceinline__ unsigned cvt_pk_bf16(float lo, float hi) { unsigned r; asm volatile("v_cvt_pk_bf16_f32 %0, %1, %2" : "=v"(r) : "v"(lo), "v"(hi)); return r; }
;     PG8_NOPRE
;     __device__ __forceinline__ void operator()(const f32x4 (&acc_)[2][2][4][2], const Unit& u, int wr, int wc, int fr_, int fq_, int ui) const {
;     ...
;                         for (int k = 0; k < 4; ++k) { const float cur = acc[ai][bj][m][n][k];
;                             float cc = fmaf(Wq[bj][2][k], cur, Wq[bj][3][k]);
;                             PG8_FMAC_DPP(cc, cur, Wq[bj][1][k], "row_shr:1 row_mask:0xf bank_mask:0xf bound_ctrl:1");
;                             PG8_FMAC_DPP(cc, cur, Wq[bj][0][k], "row_shr:2 row_mask:0xf bank_mask:0xf bound_ctrl:1");
;                             if (m == 0) { const float z = fr == 0 ? h2[k] : h1[k]; cc = fmaf(W1m[bj][k], h1[k], cc); cc = fmaf(W0m[bj][k], z, cc); }
;                             else { const float p = acc[ai][bj][m > 0 ? m - 1 : 0][n][k]; PG8_FMAC_DPP(cc, p, W1m[bj][k], "row_ror:1 row_mask:0xf bank_mask:0xf"); PG8_FMAC_DPP(cc, p, W0m[bj][k], "row_ror:2 row_mask:0xf bank_mask:0xf"); }
;                             c[bj][k] = cc; }
;                         __builtin_amdgcn_sched_barrier(0);
;                     }
;                     const int row = u.pm * BM + ai * HALF + wr * 64 + m * 16 + fr;
;                     if (ai == 0 && m == 0 && wr == 0 && fixtile && fr < 2) {
;                         float* fp = FIX + ((size_t)u.pm * 2 + fr) * 11264 + ch0 + n * 4;
;                         *(PG8_G f32x4*)fp = c[0] * 0.6931471805599453f; *(PG8_G f32x4*)(fp + 5632) = c[1] * 1.4426950408889634f;
;                     } else {
;                         f32x4 ex;
; #pragma unroll
;                         for (int k = 0; k < 4; ++k) ex[k] = __builtin_amdgcn_exp2f(-c[0][k]);
;                         const f32x4 den = ex + 1.0f, gv = c[0] * c[1]; f32x4 rc;
; #pragma unroll
;                         for (int k = 0; k < 4; ++k) rc[k] = __builtin_amdgcn_rcpf(den[k]);
;                         const f32x4 a = gv * rc;
;                         u32x2 w; w.x = cvt_pk_bf16(a[0], a[1]); w.y = cvt_pk_bf16(a[2], a[3]);
;                         if (n == 0) wkeep[ai][m] = w;
;                         else { const u32x4 w4 = {wkeep[ai][m].x, wkeep[ai][m].y, w.x, w.y}; *(PG8_G u32x4*)(ACT + (size_t)row * 5632 + ch0) = w4; }
.LBB0_1115:
	s_or_b64 exec, exec, s[10:11]
	v_mov_b32_e32 v213, v212
	v_mov_b32_e32 v211, v210
	v_mov_b32_e32 v4, v198
	v_mov_b32_e32 v5, v198
	v_mov_b32_e32 v6, v199
	v_mov_b32_e32 v7, v199
	v_mov_b32_e32 v197, v196
	v_mov_b32_e32 v8, v212
	v_mov_b32_e32 v9, v212
	v_mov_b32_e32 v10, v210
	v_mov_b32_e32 v11, v210
	v_mov_b32_e32 v14, v198
	v_mov_b32_e32 v15, v198
	v_mov_b32_e32 v198, v199
	v_mov_b32_e32 v64, v196
	v_mov_b32_e32 v65, v196
	v_pk_mul_f32 v[62:63], v[62:63], v[8:9]
	v_pk_mul_f32 v[60:61], v[60:61], v[212:213]
	v_pk_mul_f32 v[58:59], v[58:59], v[10:11]
	v_pk_mul_f32 v[56:57], v[56:57], v[210:211]
	v_pk_mul_f32 v[54:55], v[54:55], v[8:9]
	v_pk_mul_f32 v[52:53], v[52:53], v[212:213]
	v_pk_mul_f32 v[50:51], v[50:51], v[10:11]
	v_pk_mul_f32 v[48:49], v[48:49], v[210:211]
	v_pk_mul_f32 v[46:47], v[46:47], v[14:15]
	v_pk_mul_f32 v[44:45], v[44:45], v[4:5]
	v_pk_mul_f32 v[42:43], v[42:43], v[198:199]
	v_pk_mul_f32 v[40:41], v[40:41], v[6:7]
	v_pk_mul_f32 v[8:9], v[38:39], v[64:65]
	v_pk_mul_f32 v[10:11], v[36:37], v[196:197]
	v_pk_mul_f32 v[34:35], v[34:35], v[14:15]
	v_pk_mul_f32 v[32:33], v[32:33], v[4:5]
	v_pk_mul_f32 v[14:15], v[30:31], v[198:199]
	v_pk_mul_f32 v[28:29], v[28:29], v[6:7]
	v_pk_mul_f32 v[4:5], v[26:27], v[64:65]
	v_pk_mul_f32 v[6:7], v[24:25], v[196:197]
	v_add_u32_e32 v30, 0xb0, v153
	v_add_u32_e32 v31, 0xa0, v153
	v_add_u32_e32 v36, 0x90, v153
	v_add_u32_e32 v37, 0x80, v153
	v_add_u32_e32 v38, 48, v153
	v_add_u32_e32 v39, 32, v153
	v_add_u32_e32 v120, 16, v153
	v_fma_f32 v24, v132, v60, v80
	v_fma_f32 v25, v133, v61, v81
	v_fma_f32 v26, v134, v62, v82
	v_fma_f32 v27, v135, v63, v83
	v_fmac_f32_dpp v24, v60, v128 row_shr:1 row_mask:0xf bank_mask:0xf bound_ctrl:1
	v_fmac_f32_dpp v25, v61, v129 row_shr:1 row_mask:0xf bank_mask:0xf bound_ctrl:1
	v_fmac_f32_dpp v26, v62, v130 row_shr:1 row_mask:0xf bank_mask:0xf bound_ctrl:1
	v_fmac_f32_dpp v27, v63, v131 row_shr:1 row_mask:0xf bank_mask:0xf bound_ctrl:1
	v_fmac_f32_dpp v24, v60, v124 row_shr:2 row_mask:0xf bank_mask:0xf bound_ctrl:1
	v_fmac_f32_dpp v25, v61, v125 row_shr:2 row_mask:0xf bank_mask:0xf bound_ctrl:1
	v_fmac_f32_dpp v26, v62, v126 row_shr:2 row_mask:0xf bank_mask:0xf bound_ctrl:1
	v_fmac_f32_dpp v27, v63, v127 row_shr:2 row_mask:0xf bank_mask:0xf bound_ctrl:1
	v_fmac_f32_dpp v24, v106, v152 row_ror:1 row_mask:0xf bank_mask:0xf
	v_fmac_f32_dpp v25, v107, v150 row_ror:1 row_mask:0xf bank_mask:0xf
	v_fmac_f32_dpp v26, v98, v148 row_ror:1 row_mask:0xf bank_mask:0xf
	v_fmac_f32_dpp v27, v99, v143 row_ror:1 row_mask:0xf bank_mask:0xf
	v_fmac_f32_dpp v24, v106, v151 row_ror:2 row_mask:0xf bank_mask:0xf
	v_fmac_f32_dpp v25, v107, v149 row_ror:2 row_mask:0xf bank_mask:0xf
	v_fmac_f32_dpp v26, v98, v147 row_ror:2 row_mask:0xf bank_mask:0xf
	v_fmac_f32_dpp v27, v99, v141 row_ror:2 row_mask:0xf bank_mask:0xf
	v_fma_f32 v64, v116, v52, v100
	v_fma_f32 v65, v117, v53, v101
	v_fma_f32 v66, v118, v54, v102
	v_fma_f32 v67, v119, v55, v103
	v_fmac_f32_dpp v64, v52, v112 row_shr:1 row_mask:0xf bank_mask:0xf bound_ctrl:1
	v_fmac_f32_dpp v65, v53, v113 row_shr:1 row_mask:0xf bank_mask:0xf bound_ctrl:1
	v_fmac_f32_dpp v66, v54, v114 row_shr:1 row_mask:0xf bank_mask:0xf bound_ctrl:1
	v_fmac_f32_dpp v67, v55, v115 row_shr:1 row_mask:0xf bank_mask:0xf bound_ctrl:1
	v_fmac_f32_dpp v64, v52, v108 row_shr:2 row_mask:0xf bank_mask:0xf bound_ctrl:1
	v_fmac_f32_dpp v65, v53, v109 row_shr:2 row_mask:0xf bank_mask:0xf bound_ctrl:1
	v_fmac_f32_dpp v66, v54, v110 row_shr:2 row_mask:0xf bank_mask:0xf bound_ctrl:1
	v_fmac_f32_dpp v67, v55, v111 row_shr:2 row_mask:0xf bank_mask:0xf bound_ctrl:1
	v_fmac_f32_dpp v64, v94, v146 row_ror:1 row_mask:0xf bank_mask:0xf
	v_fmac_f32_dpp v65, v95, v142 row_ror:1 row_mask:0xf bank_mask:0xf
	v_fmac_f32_dpp v66, v92, v139 row_ror:1 row_mask:0xf bank_mask:0xf
	v_fmac_f32_dpp v67, v93, v137 row_ror:1 row_mask:0xf bank_mask:0xf
	v_fmac_f32_dpp v64, v94, v145 row_ror:2 row_mask:0xf bank_mask:0xf
	v_fmac_f32_dpp v65, v95, v140 row_ror:2 row_mask:0xf bank_mask:0xf
	v_fmac_f32_dpp v66, v92, v138 row_ror:2 row_mask:0xf bank_mask:0xf
	v_fmac_f32_dpp v67, v93, v136 row_ror:2 row_mask:0xf bank_mask:0xf
	v_exp_f32_e64 v72, -v24
	v_exp_f32_e64 v73, -v25
	v_exp_f32_e64 v74, -v26
	v_exp_f32_e64 v75, -v27
	v_add_f32_e32 v72, 1.0, v72
	v_add_f32_e32 v73, 1.0, v73
	v_rcp_f32_e32 v72, v72
	v_add_f32_e32 v74, 1.0, v74
	v_add_f32_e32 v75, 1.0, v75
	v_rcp_f32_e32 v73, v73
	v_rcp_f32_e32 v74, v74
	v_rcp_f32_e32 v75, v75
	v_pk_mul_f32 v[24:25], v[24:25], v[64:65]
	v_pk_mul_f32 v[26:27], v[26:27], v[66:67]
	v_pk_mul_f32 v[24:25], v[72:73], v[24:25]
	v_pk_mul_f32 v[26:27], v[74:75], v[26:27]
	v_cvt_pk_bf16_f32 v106, v24, v25
	v_mov_b64_e32 v[24:25], s[14:15]
	v_cvt_pk_bf16_f32 v107, v26, v27
	v_mad_i64_i32 v[64:65], s[10:11], v120, s47, v[24:25]
	v_lshlrev_b64 v[26:27], 1, v[194:195]
	v_lshl_add_u64 v[64:65], v[64:65], 0, v[26:27]
	global_store_dwordx4 v[64:65], v[104:107], off
	v_fma_f32 v64, v132, v56, v80
	v_fma_f32 v65, v133, v57, v81
	v_fmac_f32_dpp v64, v56, v128 row_shr:1 row_mask:0xf bank_mask:0xf bound_ctrl:1
	v_fmac_f32_dpp v65, v57, v129 row_shr:1 row_mask:0xf bank_mask:0xf bound_ctrl:1
	s_nop 0
	v_fmac_f32_dpp v64, v56, v124 row_shr:2 row_mask:0xf bank_mask:0xf bound_ctrl:1
	v_fmac_f32_dpp v65, v57, v125 row_shr:2 row_mask:0xf bank_mask:0xf bound_ctrl:1
	s_nop 0
	v_fmac_f32_dpp v64, v60, v152 row_ror:1 row_mask:0xf bank_mask:0xf
	v_fmac_f32_dpp v65, v61, v150 row_ror:1 row_mask:0xf bank_mask:0xf
	s_nop 0
	v_fmac_f32_dpp v64, v60, v151 row_ror:2 row_mask:0xf bank_mask:0xf
	v_fmac_f32_dpp v65, v61, v149 row_ror:2 row_mask:0xf bank_mask:0xf
	v_fma_f32 v60, v134, v58, v82
; __device__ __forceinline__ unsigned cvt_pk_bf16(float lo, float hi) { unsigned r; asm volatile("v_cvt_pk_bf16_f32 %0, %1, %2" : "=v"(r) : "v"(lo), "v"(hi)); return r; }
;     PG8_NOPRE
;     __device__ __forceinline__ void operator()(const f32x4 (&acc_)[2][2][4][2], const Unit& u, int wr, int wc, int fr_, int fq_, int ui) const {
;     ...
;                         for (int k = 0; k < 4; ++k) { const float cur = acc[ai][bj][m][n][k];
;                             float cc = fmaf(Wq[bj][2][k], cur, Wq[bj][3][k]);
;                             PG8_FMAC_DPP(cc, cur, Wq[bj][1][k], "row_shr:1 row_mask:0xf bank_mask:0xf bound_ctrl:1");
;                             PG8_FMAC_DPP(cc, cur, Wq[bj][0][k], "row_shr:2 row_mask:0xf bank_mask:0xf bound_ctrl:1");
;                             if (m == 0) { const float z = fr == 0 ? h2[k] : h1[k]; cc = fmaf(W1m[bj][k], h1[k], cc); cc = fmaf(W0m[bj][k], z, cc); }
;                             else { const float p = acc[ai][bj][m > 0 ? m - 1 : 0][n][k]; PG8_FMAC_DPP(cc, p, W1m[bj][k], "row_ror:1 row_mask:0xf bank_mask:0xf"); PG8_FMAC_DPP(cc, p, W0m[bj][k], "row_ror:2 row_mask:0xf bank_mask:0xf"); }
;                             c[bj][k] = cc; }
;                         __builtin_amdgcn_sched_barrier(0);
;                     }
;                     const int row = u.pm * BM + ai * HALF + wr * 64 + m * 16 + fr;
;                     if (ai == 0 && m == 0 && wr == 0 && fixtile && fr < 2) {
;                         float* fp = FIX + ((size_t)u.pm * 2 + fr) * 11264 + ch0 + n * 4;
;                         *(PG8_G f32x4*)fp = c[0] * 0.6931471805599453f; *(PG8_G f32x4*)(fp + 5632) = c[1] * 1.4426950408889634f;
;                     } else {
;                         f32x4 ex;
; #pragma unroll
;                         for (int k = 0; k < 4; ++k) ex[k] = __builtin_amdgcn_exp2f(-c[0][k]);
;                         const f32x4 den = ex + 1.0f, gv = c[0] * c[1]; f32x4 rc;
; #pragma unroll
;                         for (int k = 0; k < 4; ++k) rc[k] = __builtin_amdgcn_rcpf(den[k]);
;                         const f32x4 a = gv * rc;
;                         u32x2 w; w.x = cvt_pk_bf16(a[0], a[1]); w.y = cvt_pk_bf16(a[2], a[3]);
;                         if (n == 0) wkeep[ai][m] = w;
;                         else { const u32x4 w4 = {wkeep[ai][m].x, wkeep[ai][m].y, w.x, w.y}; *(PG8_G u32x4*)(ACT + (size_t)row * 5632 + ch0) = w4; }
	v_fma_f32 v61, v135, v59, v83
	v_fmac_f32_dpp v60, v58, v130 row_shr:1 row_mask:0xf bank_mask:0xf bound_ctrl:1
	v_fmac_f32_dpp v61, v59, v131 row_shr:1 row_mask:0xf bank_mask:0xf bound_ctrl:1
	s_nop 0
	v_fmac_f32_dpp v60, v58, v126 row_shr:2 row_mask:0xf bank_mask:0xf bound_ctrl:1
	v_fmac_f32_dpp v61, v59, v127 row_shr:2 row_mask:0xf bank_mask:0xf bound_ctrl:1
	s_nop 0
	v_fmac_f32_dpp v60, v62, v148 row_ror:1 row_mask:0xf bank_mask:0xf
	v_fmac_f32_dpp v61, v63, v143 row_ror:1 row_mask:0xf bank_mask:0xf
	s_nop 0
	v_fmac_f32_dpp v60, v62, v147 row_ror:2 row_mask:0xf bank_mask:0xf
	v_fmac_f32_dpp v61, v63, v141 row_ror:2 row_mask:0xf bank_mask:0xf
	v_fma_f32 v62, v116, v48, v100
	v_fma_f32 v63, v117, v49, v101
	v_fmac_f32_dpp v62, v48, v112 row_shr:1 row_mask:0xf bank_mask:0xf bound_ctrl:1
	v_fmac_f32_dpp v63, v49, v113 row_shr:1 row_mask:0xf bank_mask:0xf bound_ctrl:1
	s_nop 0
	v_fmac_f32_dpp v62, v48, v108 row_shr:2 row_mask:0xf bank_mask:0xf bound_ctrl:1
	v_fmac_f32_dpp v63, v49, v109 row_shr:2 row_mask:0xf bank_mask:0xf bound_ctrl:1
	s_nop 0
	v_fmac_f32_dpp v62, v52, v146 row_ror:1 row_mask:0xf bank_mask:0xf
	v_fmac_f32_dpp v63, v53, v142 row_ror:1 row_mask:0xf bank_mask:0xf
	s_nop 0
	v_fmac_f32_dpp v62, v52, v145 row_ror:2 row_mask:0xf bank_mask:0xf
	v_fmac_f32_dpp v63, v53, v140 row_ror:2 row_mask:0xf bank_mask:0xf
	v_fma_f32 v52, v118, v50, v102
	v_fma_f32 v53, v119, v51, v103
	v_fmac_f32_dpp v52, v50, v114 row_shr:1 row_mask:0xf bank_mask:0xf bound_ctrl:1
	v_fmac_f32_dpp v53, v51, v115 row_shr:1 row_mask:0xf bank_mask:0xf bound_ctrl:1
	s_nop 0
	v_fmac_f32_dpp v52, v50, v110 row_shr:2 row_mask:0xf bank_mask:0xf bound_ctrl:1
	v_fmac_f32_dpp v53, v51, v111 row_shr:2 row_mask:0xf bank_mask:0xf bound_ctrl:1
	s_nop 0
	v_fmac_f32_dpp v52, v54, v139 row_ror:1 row_mask:0xf bank_mask:0xf
	v_fmac_f32_dpp v53, v55, v137 row_ror:1 row_mask:0xf bank_mask:0xf
	s_nop 0
	v_fmac_f32_dpp v52, v54, v138 row_ror:2 row_mask:0xf bank_mask:0xf
	v_fmac_f32_dpp v53, v55, v136 row_ror:2 row_mask:0xf bank_mask:0xf
	v_exp_f32_e64 v66, -v60
	v_exp_f32_e64 v67, -v61
	v_exp_f32_e64 v54, -v64
	v_exp_f32_e64 v55, -v65
	v_add_f32_e32 v66, 1.0, v66
	v_add_f32_e32 v67, 1.0, v67
	v_add_f32_e32 v54, 1.0, v54
	v_add_f32_e32 v55, 1.0, v55
	v_rcp_f32_e32 v66, v66
	v_rcp_f32_e32 v67, v67
	v_rcp_f32_e32 v54, v54
	v_rcp_f32_e32 v55, v55
	v_pk_mul_f32 v[52:53], v[60:61], v[52:53]
	v_pk_mul_f32 v[60:61], v[64:65], v[62:63]
	v_pk_mul_f32 v[52:53], v[66:67], v[52:53]
	v_pk_mul_f32 v[54:55], v[54:55], v[60:61]
	s_nop 0
	v_cvt_pk_bf16_f32 v98, v54, v55
	v_cvt_pk_bf16_f32 v99, v52, v53
	v_mad_i64_i32 v[52:53], s[10:11], v39, s47, v[24:25]
	v_lshl_add_u64 v[52:53], v[52:53], 0, v[26:27]
	global_store_dwordx4 v[52:53], v[96:99], off
	v_fma_f32 v52, v132, v76, v80
	v_fma_f32 v53, v133, v77, v81
	v_fma_f32 v54, v134, v78, v82
	v_fma_f32 v55, v135, v79, v83
	v_fmac_f32_dpp v52, v76, v128 row_shr:1 row_mask:0xf bank_mask:0xf bound_ctrl:1
	v_fmac_f32_dpp v53, v77, v129 row_shr:1 row_mask:0xf bank_mask:0xf bound_ctrl:1
	v_fmac_f32_dpp v54, v78, v130 row_shr:1 row_mask:0xf bank_mask:0xf bound_ctrl:1
	v_fmac_f32_dpp v55, v79, v131 row_shr:1 row_mask:0xf bank_mask:0xf bound_ctrl:1
	v_fmac_f32_dpp v52, v76, v124 row_shr:2 row_mask:0xf bank_mask:0xf bound_ctrl:1
	v_fmac_f32_dpp v53, v77, v125 row_shr:2 row_mask:0xf bank_mask:0xf bound_ctrl:1
	v_fmac_f32_dpp v54, v78, v126 row_shr:2 row_mask:0xf bank_mask:0xf bound_ctrl:1
	v_fmac_f32_dpp v55, v79, v127 row_shr:2 row_mask:0xf bank_mask:0xf bound_ctrl:1
	v_fmac_f32_dpp v52, v56, v152 row_ror:1 row_mask:0xf bank_mask:0xf
	v_fmac_f32_dpp v53, v57, v150 row_ror:1 row_mask:0xf bank_mask:0xf
	v_fmac_f32_dpp v54, v58, v148 row_ror:1 row_mask:0xf bank_mask:0xf
	v_fmac_f32_dpp v55, v59, v143 row_ror:1 row_mask:0xf bank_mask:0xf
	v_fmac_f32_dpp v52, v56, v151 row_ror:2 row_mask:0xf bank_mask:0xf
	v_fmac_f32_dpp v53, v57, v149 row_ror:2 row_mask:0xf bank_mask:0xf
	v_fmac_f32_dpp v54, v58, v147 row_ror:2 row_mask:0xf bank_mask:0xf
	v_fmac_f32_dpp v55, v59, v141 row_ror:2 row_mask:0xf bank_mask:0xf
	v_fma_f32 v56, v116, v68, v100
	v_fma_f32 v57, v117, v69, v101
	v_fmac_f32_dpp v56, v68, v112 row_shr:1 row_mask:0xf bank_mask:0xf bound_ctrl:1
	v_fmac_f32_dpp v57, v69, v113 row_shr:1 row_mask:0xf bank_mask:0xf bound_ctrl:1
	s_nop 0
	v_fmac_f32_dpp v56, v68, v108 row_shr:2 row_mask:0xf bank_mask:0xf bound_ctrl:1
	v_fmac_f32_dpp v57, v69, v109 row_shr:2 row_mask:0xf bank_mask:0xf bound_ctrl:1
	s_nop 0
	v_fmac_f32_dpp v56, v48, v146 row_ror:1 row_mask:0xf bank_mask:0xf
	v_fmac_f32_dpp v57, v49, v142 row_ror:1 row_mask:0xf bank_mask:0xf
	s_nop 0
	v_fmac_f32_dpp v56, v48, v145 row_ror:2 row_mask:0xf bank_mask:0xf
	v_fmac_f32_dpp v57, v49, v140 row_ror:2 row_mask:0xf bank_mask:0xf
	v_fma_f32 v48, v118, v70, v102
	v_fma_f32 v49, v119, v71, v103
	v_fmac_f32_dpp v48, v70, v114 row_shr:1 row_mask:0xf bank_mask:0xf bound_ctrl:1
	v_fmac_f32_dpp v49, v71, v115 row_shr:1 row_mask:0xf bank_mask:0xf bound_ctrl:1
	s_nop 0
	v_fmac_f32_dpp v48, v70, v110 row_shr:2 row_mask:0xf bank_mask:0xf bound_ctrl:1
	v_fmac_f32_dpp v49, v71, v111 row_shr:2 row_mask:0xf bank_mask:0xf bound_ctrl:1
	s_nop 0
	v_fmac_f32_dpp v48, v50, v139 row_ror:1 row_mask:0xf bank_mask:0xf
	v_fmac_f32_dpp v49, v51, v137 row_ror:1 row_mask:0xf bank_mask:0xf
	s_nop 0
	v_fmac_f32_dpp v48, v50, v138 row_ror:2 row_mask:0xf bank_mask:0xf
	v_fmac_f32_dpp v49, v51, v136 row_ror:2 row_mask:0xf bank_mask:0xf
	v_exp_f32_e64 v39, -v52
	v_exp_f32_e64 v51, -v53
	v_exp_f32_e64 v58, -v54
	v_exp_f32_e64 v59, -v55
	v_add_f32_e32 v39, 1.0, v39
	v_rcp_f32_e32 v50, v39
	v_add_f32_e32 v39, 1.0, v51
	v_add_f32_e32 v51, 1.0, v58
	v_rcp_f32_e32 v58, v51
	v_add_f32_e32 v51, 1.0, v59
	v_rcp_f32_e32 v59, v51
	v_rcp_f32_e32 v51, v39
	v_mad_i64_i32 v[38:39], s[10:11], v38, s47, v[24:25]
	v_pk_mul_f32 v[48:49], v[54:55], v[48:49]
	v_pk_mul_f32 v[52:53], v[52:53], v[56:57]
	v_lshl_add_u64 v[38:39], v[38:39], 0, v[26:27]
	v_pk_mul_f32 v[48:49], v[58:59], v[48:49]
	v_pk_mul_f32 v[50:51], v[50:51], v[52:53]
	s_nop 0
	v_cvt_pk_bf16_f32 v92, v50, v51
	v_cvt_pk_bf16_f32 v93, v48, v49
	global_store_dwordx4 v[38:39], v[90:93], off
	ds_read_b128 v[48:51], v144 offset:16
	ds_read_b128 v[52:55], v144 offset:272
	v_fma_f32 v38, v132, v44, v80
	v_fmac_f32_dpp v38, v44, v128 row_shr:1 row_mask:0xf bank_mask:0xf bound_ctrl:1
	v_fma_f32 v56, v134, v46, v82
	v_fmac_f32_dpp v38, v44, v124 row_shr:2 row_mask:0xf bank_mask:0xf bound_ctrl:1
	s_waitcnt lgkmcnt(0)
;     PG8_NOPRE
;     __device__ __forceinline__ void operator()(const f32x4 (&acc_)[2][2][4][2], const Unit& u, int wr, int wc, int fr_, int fq_, int ui) const {
;     ...
;                     for (int bj = 0; bj < 2; ++bj) {
;                         f32x4 h1 = {0.f, 0.f, 0.f, 0.f}, h2 = {0.f, 0.f, 0.f, 0.f};
;                         if (m == 0 && !(ai == 0 && wr == 0)) { const int slot = ai == 0 ? 0 : (wr == 0 ? 1 : 2); const PG8_LAS float* b = xh + (((slot * 4 + wc) * 2) * 4 + fq) * 16 + n * 4 + bj * 8;
;                             h2 = *(const PG8_LAS f32x4*)b; h1 = *(const PG8_LAS f32x4*)(b + 64); }
; #pragma unroll
;                         for (int k = 0; k < 4; ++k) { const float cur = acc[ai][bj][m][n][k];
;                             float cc = fmaf(Wq[bj][2][k], cur, Wq[bj][3][k]);
;                             PG8_FMAC_DPP(cc, cur, Wq[bj][1][k], "row_shr:1 row_mask:0xf bank_mask:0xf bound_ctrl:1");
;                             PG8_FMAC_DPP(cc, cur, Wq[bj][0][k], "row_shr:2 row_mask:0xf bank_mask:0xf bound_ctrl:1");
;                             if (m == 0) { const float z = fr == 0 ? h2[k] : h1[k]; cc = fmaf(W1m[bj][k], h1[k], cc); cc = fmaf(W0m[bj][k], z, cc); }
;                             else { const float p = acc[ai][bj][m > 0 ? m - 1 : 0][n][k]; PG8_FMAC_DPP(cc, p, W1m[bj][k], "row_ror:1 row_mask:0xf bank_mask:0xf"); PG8_FMAC_DPP(cc, p, W0m[bj][k], "row_ror:2 row_mask:0xf bank_mask:0xf"); }
;                             c[bj][k] = cc; }
;                         __builtin_amdgcn_sched_barrier(0);
;                     }
;                     const int row = u.pm * BM + ai * HALF + wr * 64 + m * 16 + fr;
;                     if (ai == 0 && m == 0 && wr == 0 && fixtile && fr < 2) {
;                         float* fp = FIX + ((size_t)u.pm * 2 + fr) * 11264 + ch0 + n * 4;
;                         *(PG8_G f32x4*)fp = c[0] * 0.6931471805599453f; *(PG8_G f32x4*)(fp + 5632) = c[1] * 1.4426950408889634f;
;                     } else {
;                         f32x4 ex;
; #pragma unroll
;                         for (int k = 0; k < 4; ++k) ex[k] = __builtin_amdgcn_exp2f(-c[0][k]);
;                         const f32x4 den = ex + 1.0f, gv = c[0] * c[1]; f32x4 rc;
; #pragma unroll
;                         for (int k = 0; k < 4; ++k) rc[k] = __builtin_amdgcn_rcpf(den[k]);
;                         const f32x4 a = gv * rc;
	v_cndmask_b32_e64 v39, v52, v48, s[8:9]
	v_fmac_f32_e32 v38, v152, v52
	v_fmac_f32_e32 v38, v151, v39
	v_fma_f32 v39, v133, v45, v81
	v_fmac_f32_dpp v39, v45, v129 row_shr:1 row_mask:0xf bank_mask:0xf bound_ctrl:1
	v_fmac_f32_dpp v56, v46, v130 row_shr:1 row_mask:0xf bank_mask:0xf bound_ctrl:1
	v_fma_f32 v57, v135, v47, v83
	v_fmac_f32_dpp v39, v45, v125 row_shr:2 row_mask:0xf bank_mask:0xf bound_ctrl:1
	v_cndmask_b32_e64 v48, v53, v49, s[8:9]
	v_fmac_f32_e32 v39, v150, v53
	v_fmac_f32_dpp v56, v46, v126 row_shr:2 row_mask:0xf bank_mask:0xf bound_ctrl:1
	v_fmac_f32_dpp v57, v47, v131 row_shr:1 row_mask:0xf bank_mask:0xf bound_ctrl:1
	v_fmac_f32_e32 v39, v149, v48
	v_cndmask_b32_e64 v48, v54, v50, s[8:9]
	v_fmac_f32_e32 v56, v148, v54
	v_fmac_f32_dpp v57, v47, v127 row_shr:2 row_mask:0xf bank_mask:0xf bound_ctrl:1
	v_fmac_f32_e32 v56, v147, v48
	v_cndmask_b32_e64 v48, v55, v51, s[8:9]
	v_fmac_f32_e32 v57, v143, v55
	v_fmac_f32_e32 v57, v141, v48
	ds_read_b128 v[48:51], v144 offset:48
	ds_read_b128 v[52:55], v144 offset:304
	v_fma_f32 v58, v116, v32, v100
	v_fmac_f32_dpp v58, v32, v112 row_shr:1 row_mask:0xf bank_mask:0xf bound_ctrl:1
	v_fma_f32 v59, v117, v33, v101
	v_fmac_f32_dpp v58, v32, v108 row_shr:2 row_mask:0xf bank_mask:0xf bound_ctrl:1
	v_fmac_f32_dpp v59, v33, v113 row_shr:1 row_mask:0xf bank_mask:0xf bound_ctrl:1
	s_waitcnt lgkmcnt(0)
	v_cndmask_b32_e64 v48, v52, v48, s[8:9]
	v_fmac_f32_e32 v58, v146, v52
	v_fmac_f32_dpp v59, v33, v109 row_shr:2 row_mask:0xf bank_mask:0xf bound_ctrl:1
	v_fmac_f32_e32 v58, v145, v48
	v_cndmask_b32_e64 v48, v53, v49, s[8:9]
	v_fmac_f32_e32 v59, v142, v53
	v_fmac_f32_e32 v59, v140, v48
	v_fma_f32 v48, v118, v34, v102
	v_fmac_f32_dpp v48, v34, v114 row_shr:1 row_mask:0xf bank_mask:0xf bound_ctrl:1
	v_cndmask_b32_e64 v49, v54, v50, s[8:9]
	v_fmac_f32_dpp v48, v34, v110 row_shr:2 row_mask:0xf bank_mask:0xf bound_ctrl:1
	v_cndmask_b32_e64 v50, v55, v51, s[8:9]
	v_fmac_f32_e32 v48, v139, v54
	v_fmac_f32_e32 v48, v138, v49
	v_fma_f32 v49, v119, v35, v103
	v_fmac_f32_dpp v49, v35, v115 row_shr:1 row_mask:0xf bank_mask:0xf bound_ctrl:1
	s_nop 0
	v_fmac_f32_dpp v49, v35, v111 row_shr:2 row_mask:0xf bank_mask:0xf bound_ctrl:1
	s_nop 0
	v_fmac_f32_e32 v49, v137, v55
	v_fmac_f32_e32 v49, v136, v50
	v_exp_f32_e64 v50, -v38
	v_exp_f32_e64 v51, -v39
	v_exp_f32_e64 v52, -v56
	v_exp_f32_e64 v53, -v57
	v_add_f32_e32 v50, 1.0, v50
	v_add_f32_e32 v51, 1.0, v51
	v_rcp_f32_e32 v50, v50
	v_rcp_f32_e32 v51, v51
	v_add_f32_e32 v52, 1.0, v52
	v_add_f32_e32 v53, 1.0, v53
	v_rcp_f32_e32 v52, v52
	v_rcp_f32_e32 v53, v53
	v_pk_mul_f32 v[38:39], v[38:39], v[58:59]
	v_pk_mul_f32 v[48:49], v[56:57], v[48:49]
	v_pk_mul_f32 v[38:39], v[50:51], v[38:39]
	v_pk_mul_f32 v[48:49], v[52:53], v[48:49]
	v_cvt_pk_bf16_f32 v90, v38, v39
	v_mad_i64_i32 v[38:39], s[8:9], v37, s47, v[24:25]
	v_lshl_add_u64 v[38:39], v[38:39], 0, v[26:27]
	v_cvt_pk_bf16_f32 v91, v48, v49
	global_store_dwordx4 v[38:39], v[88:91], off
	v_fma_f32 v38, v132, v40, v80
	v_fma_f32 v39, v133, v41, v81
	v_fmac_f32_dpp v38, v40, v128 row_shr:1 row_mask:0xf bank_mask:0xf bound_ctrl:1
	v_fmac_f32_dpp v39, v41, v129 row_shr:1 row_mask:0xf bank_mask:0xf bound_ctrl:1
	s_nop 0
	v_fmac_f32_dpp v38, v40, v124 row_shr:2 row_mask:0xf bank_mask:0xf bound_ctrl:1
	v_fmac_f32_dpp v39, v41, v125 row_shr:2 row_mask:0xf bank_mask:0xf bound_ctrl:1
	s_nop 0
	v_fmac_f32_dpp v38, v44, v152 row_ror:1 row_mask:0xf bank_mask:0xf
	v_fmac_f32_dpp v39, v45, v150 row_ror:1 row_mask:0xf bank_mask:0xf
	s_nop 0
	v_fmac_f32_dpp v38, v44, v151 row_ror:2 row_mask:0xf bank_mask:0xf
	v_fmac_f32_dpp v39, v45, v149 row_ror:2 row_mask:0xf bank_mask:0xf
	v_fma_f32 v44, v134, v42, v82
	v_fma_f32 v45, v135, v43, v83
	v_fmac_f32_dpp v44, v42, v130 row_shr:1 row_mask:0xf bank_mask:0xf bound_ctrl:1
	v_fmac_f32_dpp v45, v43, v131 row_shr:1 row_mask:0xf bank_mask:0xf bound_ctrl:1
	s_nop 0
	v_fmac_f32_dpp v44, v42, v126 row_shr:2 row_mask:0xf bank_mask:0xf bound_ctrl:1
	v_fmac_f32_dpp v45, v43, v127 row_shr:2 row_mask:0xf bank_mask:0xf bound_ctrl:1
	s_nop 0
	v_fmac_f32_dpp v44, v46, v148 row_ror:1 row_mask:0xf bank_mask:0xf
	v_fmac_f32_dpp v45, v47, v143 row_ror:1 row_mask:0xf bank_mask:0xf
	s_nop 0
	v_fmac_f32_dpp v44, v46, v147 row_ror:2 row_mask:0xf bank_mask:0xf
	v_fmac_f32_dpp v45, v47, v141 row_ror:2 row_mask:0xf bank_mask:0xf
	v_fma_f32 v46, v116, v28, v100
	v_fma_f32 v47, v117, v29, v101
	v_fmac_f32_dpp v46, v28, v112 row_shr:1 row_mask:0xf bank_mask:0xf bound_ctrl:1
	v_fmac_f32_dpp v47, v29, v113 row_shr:1 row_mask:0xf bank_mask:0xf bound_ctrl:1
	s_nop 0
	v_fmac_f32_dpp v46, v28, v108 row_shr:2 row_mask:0xf bank_mask:0xf bound_ctrl:1
	v_fmac_f32_dpp v47, v29, v109 row_shr:2 row_mask:0xf bank_mask:0xf bound_ctrl:1
	s_nop 0
	v_fmac_f32_dpp v46, v32, v146 row_ror:1 row_mask:0xf bank_mask:0xf
	v_fmac_f32_dpp v47, v33, v142 row_ror:1 row_mask:0xf bank_mask:0xf
	s_nop 0
	v_fmac_f32_dpp v46, v32, v145 row_ror:2 row_mask:0xf bank_mask:0xf
	v_fmac_f32_dpp v47, v33, v140 row_ror:2 row_mask:0xf bank_mask:0xf
	v_fma_f32 v32, v118, v14, v102
	v_fma_f32 v33, v119, v15, v103
	v_fmac_f32_dpp v32, v14, v114 row_shr:1 row_mask:0xf bank_mask:0xf bound_ctrl:1
	v_fmac_f32_dpp v33, v15, v115 row_shr:1 row_mask:0xf bank_mask:0xf bound_ctrl:1
	s_nop 0
	v_fmac_f32_dpp v32, v14, v110 row_shr:2 row_mask:0xf bank_mask:0xf bound_ctrl:1
	v_fmac_f32_dpp v33, v15, v111 row_shr:2 row_mask:0xf bank_mask:0xf bound_ctrl:1
	s_nop 0
	v_fmac_f32_dpp v32, v34, v139 row_ror:1 row_mask:0xf bank_mask:0xf
	v_fmac_f32_dpp v33, v35, v137 row_ror:1 row_mask:0xf bank_mask:0xf
	s_nop 0
	v_fmac_f32_dpp v32, v34, v138 row_ror:2 row_mask:0xf bank_mask:0xf
; __device__ __forceinline__ unsigned cvt_pk_bf16(float lo, float hi) { unsigned r; asm volatile("v_cvt_pk_bf16_f32 %0, %1, %2" : "=v"(r) : "v"(lo), "v"(hi)); return r; }
;     PG8_NOPRE
;     __device__ __forceinline__ void operator()(const f32x4 (&acc_)[2][2][4][2], const Unit& u, int wr, int wc, int fr_, int fq_, int ui) const {
;     ...
;                         for (int k = 0; k < 4; ++k) { const float cur = acc[ai][bj][m][n][k];
;                             float cc = fmaf(Wq[bj][2][k], cur, Wq[bj][3][k]);
;                             PG8_FMAC_DPP(cc, cur, Wq[bj][1][k], "row_shr:1 row_mask:0xf bank_mask:0xf bound_ctrl:1");
;                             PG8_FMAC_DPP(cc, cur, Wq[bj][0][k], "row_shr:2 row_mask:0xf bank_mask:0xf bound_ctrl:1");
;                             if (m == 0) { const float z = fr == 0 ? h2[k] : h1[k]; cc = fmaf(W1m[bj][k], h1[k], cc); cc = fmaf(W0m[bj][k], z, cc); }
;                             else { const float p = acc[ai][bj][m > 0 ? m - 1 : 0][n][k]; PG8_FMAC_DPP(cc, p, W1m[bj][k], "row_ror:1 row_mask:0xf bank_mask:0xf"); PG8_FMAC_DPP(cc, p, W0m[bj][k], "row_ror:2 row_mask:0xf bank_mask:0xf"); }
;                             c[bj][k] = cc; }
;                         __builtin_amdgcn_sched_barrier(0);
;                     }
;                     const int row = u.pm * BM + ai * HALF + wr * 64 + m * 16 + fr;
;                     if (ai == 0 && m == 0 && wr == 0 && fixtile && fr < 2) {
;                         float* fp = FIX + ((size_t)u.pm * 2 + fr) * 11264 + ch0 + n * 4;
;                         *(PG8_G f32x4*)fp = c[0] * 0.6931471805599453f; *(PG8_G f32x4*)(fp + 5632) = c[1] * 1.4426950408889634f;
;                     } else {
;                         f32x4 ex;
; #pragma unroll
;                         for (int k = 0; k < 4; ++k) ex[k] = __builtin_amdgcn_exp2f(-c[0][k]);
;                         const f32x4 den = ex + 1.0f, gv = c[0] * c[1]; f32x4 rc;
; #pragma unroll
;                         for (int k = 0; k < 4; ++k) rc[k] = __builtin_amdgcn_rcpf(den[k]);
;                         const f32x4 a = gv * rc;
;                         u32x2 w; w.x = cvt_pk_bf16(a[0], a[1]); w.y = cvt_pk_bf16(a[2], a[3]);
;                         if (n == 0) wkeep[ai][m] = w;
;                         else { const u32x4 w4 = {wkeep[ai][m].x, wkeep[ai][m].y, w.x, w.y}; *(PG8_G u32x4*)(ACT + (size_t)row * 5632 + ch0) = w4; }
	v_fmac_f32_dpp v33, v35, v136 row_ror:2 row_mask:0xf bank_mask:0xf
	v_exp_f32_e64 v37, -v44
	v_exp_f32_e64 v49, -v45
	v_exp_f32_e64 v34, -v38
	v_exp_f32_e64 v35, -v39
	v_add_f32_e32 v37, 1.0, v37
	v_rcp_f32_e32 v48, v37
	v_add_f32_e32 v37, 1.0, v49
	v_add_f32_e32 v34, 1.0, v34
	v_add_f32_e32 v35, 1.0, v35
	v_rcp_f32_e32 v49, v37
	v_rcp_f32_e32 v34, v34
	v_rcp_f32_e32 v35, v35
	v_pk_mul_f32 v[32:33], v[44:45], v[32:33]
	v_pk_mul_f32 v[38:39], v[38:39], v[46:47]
	v_pk_mul_f32 v[32:33], v[48:49], v[32:33]
	v_pk_mul_f32 v[34:35], v[34:35], v[38:39]
	s_nop 0
	v_cvt_pk_bf16_f32 v88, v34, v35
	v_cvt_pk_bf16_f32 v89, v32, v33
	v_mad_i64_i32 v[32:33], s[8:9], v36, s47, v[24:25]
	v_lshl_add_u64 v[32:33], v[32:33], 0, v[26:27]
	global_store_dwordx4 v[32:33], v[86:89], off
	v_fma_f32 v32, v132, v10, v80
	v_fma_f32 v33, v133, v11, v81
	v_fma_f32 v34, v134, v8, v82
	v_fma_f32 v35, v135, v9, v83
	v_fmac_f32_dpp v32, v10, v128 row_shr:1 row_mask:0xf bank_mask:0xf bound_ctrl:1
	v_fmac_f32_dpp v33, v11, v129 row_shr:1 row_mask:0xf bank_mask:0xf bound_ctrl:1
	v_fmac_f32_dpp v34, v8, v130 row_shr:1 row_mask:0xf bank_mask:0xf bound_ctrl:1
	v_fmac_f32_dpp v35, v9, v131 row_shr:1 row_mask:0xf bank_mask:0xf bound_ctrl:1
	v_fmac_f32_dpp v32, v10, v124 row_shr:2 row_mask:0xf bank_mask:0xf bound_ctrl:1
	v_fmac_f32_dpp v33, v11, v125 row_shr:2 row_mask:0xf bank_mask:0xf bound_ctrl:1
	v_fmac_f32_dpp v34, v8, v126 row_shr:2 row_mask:0xf bank_mask:0xf bound_ctrl:1
	v_fmac_f32_dpp v35, v9, v127 row_shr:2 row_mask:0xf bank_mask:0xf bound_ctrl:1
	v_fmac_f32_dpp v32, v40, v152 row_ror:1 row_mask:0xf bank_mask:0xf
	v_fmac_f32_dpp v33, v41, v150 row_ror:1 row_mask:0xf bank_mask:0xf
	v_fmac_f32_dpp v34, v42, v148 row_ror:1 row_mask:0xf bank_mask:0xf
	v_fmac_f32_dpp v35, v43, v143 row_ror:1 row_mask:0xf bank_mask:0xf
	v_fmac_f32_dpp v32, v40, v151 row_ror:2 row_mask:0xf bank_mask:0xf
	v_fmac_f32_dpp v33, v41, v149 row_ror:2 row_mask:0xf bank_mask:0xf
	v_fmac_f32_dpp v34, v42, v147 row_ror:2 row_mask:0xf bank_mask:0xf
	v_fmac_f32_dpp v35, v43, v141 row_ror:2 row_mask:0xf bank_mask:0xf
	v_fma_f32 v36, v116, v6, v100
	v_fma_f32 v37, v117, v7, v101
	v_fmac_f32_dpp v36, v6, v112 row_shr:1 row_mask:0xf bank_mask:0xf bound_ctrl:1
	v_fmac_f32_dpp v37, v7, v113 row_shr:1 row_mask:0xf bank_mask:0xf bound_ctrl:1
	s_nop 0
	v_fmac_f32_dpp v36, v6, v108 row_shr:2 row_mask:0xf bank_mask:0xf bound_ctrl:1
	v_fmac_f32_dpp v37, v7, v109 row_shr:2 row_mask:0xf bank_mask:0xf bound_ctrl:1
	s_nop 0
	v_fmac_f32_dpp v36, v28, v146 row_ror:1 row_mask:0xf bank_mask:0xf
	v_fmac_f32_dpp v37, v29, v142 row_ror:1 row_mask:0xf bank_mask:0xf
	s_nop 0
	v_fmac_f32_dpp v36, v28, v145 row_ror:2 row_mask:0xf bank_mask:0xf
	v_fmac_f32_dpp v37, v29, v140 row_ror:2 row_mask:0xf bank_mask:0xf
	v_fma_f32 v28, v118, v4, v102
	v_fma_f32 v29, v119, v5, v103
	v_fmac_f32_dpp v28, v4, v114 row_shr:1 row_mask:0xf bank_mask:0xf bound_ctrl:1
	v_fmac_f32_dpp v29, v5, v115 row_shr:1 row_mask:0xf bank_mask:0xf bound_ctrl:1
	s_nop 0
	v_fmac_f32_dpp v28, v4, v110 row_shr:2 row_mask:0xf bank_mask:0xf bound_ctrl:1
	v_fmac_f32_dpp v29, v5, v111 row_shr:2 row_mask:0xf bank_mask:0xf bound_ctrl:1
	s_nop 0
	v_fmac_f32_dpp v28, v14, v139 row_ror:1 row_mask:0xf bank_mask:0xf
	v_fmac_f32_dpp v29, v15, v137 row_ror:1 row_mask:0xf bank_mask:0xf
	s_nop 0
	v_fmac_f32_dpp v28, v14, v138 row_ror:2 row_mask:0xf bank_mask:0xf
	v_fmac_f32_dpp v29, v15, v136 row_ror:2 row_mask:0xf bank_mask:0xf
	v_exp_f32_e64 v14, -v32
	v_exp_f32_e64 v15, -v33
	v_exp_f32_e64 v38, -v34
	v_exp_f32_e64 v39, -v35
	v_add_f32_e32 v14, 1.0, v14
	v_add_f32_e32 v15, 1.0, v15
	v_rcp_f32_e32 v14, v14
	v_rcp_f32_e32 v15, v15
	v_add_f32_e32 v38, 1.0, v38
	v_add_f32_e32 v39, 1.0, v39
	v_rcp_f32_e32 v38, v38
	v_rcp_f32_e32 v39, v39
	v_pk_mul_f32 v[32:33], v[32:33], v[36:37]
;     PG8_NOPRE
;     __device__ __forceinline__ void operator()(const f32x4 (&acc_)[2][2][4][2], const Unit& u, int wr, int wc, int fr_, int fq_, int ui) const {
;     ...
;                         for (int k = 0; k < 4; ++k) { const float cur = acc[ai][bj][m][n][k];
;                             float cc = fmaf(Wq[bj][2][k], cur, Wq[bj][3][k]);
;                             PG8_FMAC_DPP(cc, cur, Wq[bj][1][k], "row_shr:1 row_mask:0xf bank_mask:0xf bound_ctrl:1");
;                             PG8_FMAC_DPP(cc, cur, Wq[bj][0][k], "row_shr:2 row_mask:0xf bank_mask:0xf bound_ctrl:1");
;                             if (m == 0) { const float z = fr == 0 ? h2[k] : h1[k]; cc = fmaf(W1m[bj][k], h1[k], cc); cc = fmaf(W0m[bj][k], z, cc); }
;                             else { const float p = acc[ai][bj][m > 0 ? m - 1 : 0][n][k]; PG8_FMAC_DPP(cc, p, W1m[bj][k], "row_ror:1 row_mask:0xf bank_mask:0xf"); PG8_FMAC_DPP(cc, p, W0m[bj][k], "row_ror:2 row_mask:0xf bank_mask:0xf"); }
;                             c[bj][k] = cc; }
;                         __builtin_amdgcn_sched_barrier(0);
;                     }
;                     const int row = u.pm * BM + ai * HALF + wr * 64 + m * 16 + fr;
;                     if (ai == 0 && m == 0 && wr == 0 && fixtile && fr < 2) {
;                         float* fp = FIX + ((size_t)u.pm * 2 + fr) * 11264 + ch0 + n * 4;
;                         *(PG8_G f32x4*)fp = c[0] * 0.6931471805599453f; *(PG8_G f32x4*)(fp + 5632) = c[1] * 1.4426950408889634f;
;                     } else {
;                         f32x4 ex;
; #pragma unroll
;                         for (int k = 0; k < 4; ++k) ex[k] = __builtin_amdgcn_exp2f(-c[0][k]);
;                         const f32x4 den = ex + 1.0f, gv = c[0] * c[1]; f32x4 rc;
; #pragma unroll
;                         for (int k = 0; k < 4; ++k) rc[k] = __builtin_amdgcn_rcpf(den[k]);
;                         const f32x4 a = gv * rc;
;                         u32x2 w; w.x = cvt_pk_bf16(a[0], a[1]); w.y = cvt_pk_bf16(a[2], a[3]);
;                         if (n == 0) wkeep[ai][m] = w;
;                         else { const u32x4 w4 = {wkeep[ai][m].x, wkeep[ai][m].y, w.x, w.y}; *(PG8_G u32x4*)(ACT + (size_t)row * 5632 + ch0) = w4; }
;     ...
;         if (!has_next) break;
; #pragma unroll
;         for (int a = 0; a < 2; ++a)
; #pragma unroll
;             for (int b = 0; b < 2; ++b)
; #pragma unroll
	v_pk_mul_f32 v[28:29], v[34:35], v[28:29]
	v_pk_mul_f32 v[14:15], v[14:15], v[32:33]
	v_pk_mul_f32 v[28:29], v[38:39], v[28:29]
	v_cvt_pk_bf16_f32 v86, v14, v15
	v_mad_i64_i32 v[14:15], s[8:9], v31, s47, v[24:25]
	v_lshl_add_u64 v[14:15], v[14:15], 0, v[26:27]
	v_cvt_pk_bf16_f32 v87, v28, v29
	global_store_dwordx4 v[14:15], v[84:87], off
	v_fma_f32 v14, v132, v20, v80
	v_fma_f32 v15, v133, v21, v81
	v_fma_f32 v82, v134, v22, v82
	v_fmac_f32_e32 v83, v135, v23
	v_fmac_f32_dpp v14, v20, v128 row_shr:1 row_mask:0xf bank_mask:0xf bound_ctrl:1
	v_fmac_f32_dpp v15, v21, v129 row_shr:1 row_mask:0xf bank_mask:0xf bound_ctrl:1
	v_fmac_f32_dpp v82, v22, v130 row_shr:1 row_mask:0xf bank_mask:0xf bound_ctrl:1
	v_fmac_f32_dpp v83, v23, v131 row_shr:1 row_mask:0xf bank_mask:0xf bound_ctrl:1
	v_fmac_f32_dpp v14, v20, v124 row_shr:2 row_mask:0xf bank_mask:0xf bound_ctrl:1
	v_fmac_f32_dpp v15, v21, v125 row_shr:2 row_mask:0xf bank_mask:0xf bound_ctrl:1
	v_fmac_f32_dpp v82, v22, v126 row_shr:2 row_mask:0xf bank_mask:0xf bound_ctrl:1
	v_fmac_f32_dpp v83, v23, v127 row_shr:2 row_mask:0xf bank_mask:0xf bound_ctrl:1
	v_fmac_f32_dpp v14, v10, v152 row_ror:1 row_mask:0xf bank_mask:0xf
	v_fmac_f32_dpp v15, v11, v150 row_ror:1 row_mask:0xf bank_mask:0xf
	v_fmac_f32_dpp v82, v8, v148 row_ror:1 row_mask:0xf bank_mask:0xf
	v_fmac_f32_dpp v83, v9, v143 row_ror:1 row_mask:0xf bank_mask:0xf
	v_fmac_f32_dpp v14, v10, v151 row_ror:2 row_mask:0xf bank_mask:0xf
	v_fmac_f32_dpp v15, v11, v149 row_ror:2 row_mask:0xf bank_mask:0xf
	v_fmac_f32_dpp v82, v8, v147 row_ror:2 row_mask:0xf bank_mask:0xf
	v_fmac_f32_dpp v83, v9, v141 row_ror:2 row_mask:0xf bank_mask:0xf
	v_fma_f32 v8, v116, v16, v100
	v_fma_f32 v9, v117, v17, v101
	v_fma_f32 v102, v118, v18, v102
	v_fmac_f32_e32 v103, v119, v19
	v_fmac_f32_dpp v8, v16, v112 row_shr:1 row_mask:0xf bank_mask:0xf bound_ctrl:1
	v_fmac_f32_dpp v9, v17, v113 row_shr:1 row_mask:0xf bank_mask:0xf bound_ctrl:1
	v_fmac_f32_dpp v102, v18, v114 row_shr:1 row_mask:0xf bank_mask:0xf bound_ctrl:1
	v_fmac_f32_dpp v103, v19, v115 row_shr:1 row_mask:0xf bank_mask:0xf bound_ctrl:1
	v_fmac_f32_dpp v8, v16, v108 row_shr:2 row_mask:0xf bank_mask:0xf bound_ctrl:1
	v_fmac_f32_dpp v9, v17, v109 row_shr:2 row_mask:0xf bank_mask:0xf bound_ctrl:1
	v_fmac_f32_dpp v102, v18, v110 row_shr:2 row_mask:0xf bank_mask:0xf bound_ctrl:1
	v_fmac_f32_dpp v103, v19, v111 row_shr:2 row_mask:0xf bank_mask:0xf bound_ctrl:1
	v_fmac_f32_dpp v8, v6, v146 row_ror:1 row_mask:0xf bank_mask:0xf
	v_fmac_f32_dpp v9, v7, v142 row_ror:1 row_mask:0xf bank_mask:0xf
	v_fmac_f32_dpp v102, v4, v139 row_ror:1 row_mask:0xf bank_mask:0xf
	v_fmac_f32_dpp v103, v5, v137 row_ror:1 row_mask:0xf bank_mask:0xf
	v_fmac_f32_dpp v8, v6, v145 row_ror:2 row_mask:0xf bank_mask:0xf
	v_fmac_f32_dpp v9, v7, v140 row_ror:2 row_mask:0xf bank_mask:0xf
	v_fmac_f32_dpp v102, v4, v138 row_ror:2 row_mask:0xf bank_mask:0xf
	v_fmac_f32_dpp v103, v5, v136 row_ror:2 row_mask:0xf bank_mask:0xf
	v_exp_f32_e64 v4, -v14
	v_exp_f32_e64 v5, -v15
	v_exp_f32_e64 v6, -v82
	v_exp_f32_e64 v7, -v83
	v_add_f32_e32 v4, 1.0, v4
	v_add_f32_e32 v5, 1.0, v5
	v_rcp_f32_e32 v4, v4
	v_rcp_f32_e32 v5, v5
	v_add_f32_e32 v6, 1.0, v6
	v_add_f32_e32 v7, 1.0, v7
	v_rcp_f32_e32 v6, v6
	v_rcp_f32_e32 v7, v7
	v_pk_mul_f32 v[8:9], v[14:15], v[8:9]
	v_pk_mul_f32 v[10:11], v[82:83], v[102:103]
	v_pk_mul_f32 v[4:5], v[4:5], v[8:9]
	v_pk_mul_f32 v[6:7], v[6:7], v[10:11]
	v_cvt_pk_bf16_f32 v14, v4, v5
	v_mad_i64_i32 v[4:5], s[8:9], v30, s47, v[24:25]
	v_lshl_add_u64 v[4:5], v[4:5], 0, v[26:27]
	v_cvt_pk_bf16_f32 v15, v6, v7
	global_store_dwordx4 v[4:5], v[12:15], off
	s_andn2_b64 vcc, exec, s[6:7]
	s_mov_b64 s[6:7], -1
	s_cbranch_vccnz .LBB0_1082
	s_andn2_b64 vcc, exec, s[60:61]
	s_cbranch_vccnz .LBB0_1081
	s_barrier
	s_branch .LBB0_1081
